# GEMM epilogues: shuffle-xor sum steps via v_permlane16/32_swap instead of ds_bpermute LDS round trips
# baseline (speedup 1.0000x reference)
.LBB0_268:
	s_waitcnt lgkmcnt(0)
	ds_read_b128 v[128:131], v244
	ds_read_b128 v[132:135], v244 offset:1024
	ds_read_b128 v[136:139], v244 offset:2048
	ds_read_b128 v[140:143], v244 offset:3072
	s_add_u32 s38, s36, 0xfff50080
	s_addc_u32 s39, s37, -1
	s_cmp_eq_u32 s67, 40
	s_cselect_b32 s41, s9, s39
	s_cselect_b32 s40, s8, s38
	s_cselect_b32 s39, s11, s66
	s_cselect_b32 s38, s10, s16
	v_lshl_add_u64 v[176:177], s[36:37], 0, v[202:203]
	s_add_i32 m0, s45, 0xc000
	ds_read_b128 v[144:147], v245
	ds_read_b128 v[148:151], v245 offset:1024
	ds_read_b128 v[152:155], v245 offset:2048
	ds_read_b128 v[156:159], v245 offset:3072
	ds_read_b128 v[160:163], v245 offset:4096
	ds_read_b128 v[164:167], v245 offset:5120
	ds_read_b128 v[168:171], v245 offset:6144
	ds_read_b128 v[172:175], v245 offset:7168
	global_load_lds_dwordx4 v[176:177], off
	v_lshl_add_u64 v[176:177], s[36:37], 0, v[204:205]
	s_add_i32 m0, s45, 0xe000
	s_nop 0
	global_load_lds_dwordx4 v[176:177], off
	s_waitcnt lgkmcnt(8)
	s_barrier
	s_waitcnt lgkmcnt(0)
	s_setprio 1
	s_waitcnt lgkmcnt(0)
	v_mfma_f32_16x16x32_bf16 v[124:127], v[128:131], v[144:147], v[124:127]
	v_mfma_f32_16x16x32_bf16 v[120:123], v[136:139], v[144:147], v[120:123]
	v_mfma_f32_16x16x32_bf16 v[108:111], v[128:131], v[152:155], v[108:111]
	v_mfma_f32_16x16x32_bf16 v[104:107], v[136:139], v[152:155], v[104:107]
	v_mfma_f32_16x16x32_bf16 v[92:95], v[128:131], v[160:163], v[92:95]
	v_mfma_f32_16x16x32_bf16 v[88:91], v[136:139], v[160:163], v[88:91]
	v_mfma_f32_16x16x32_bf16 v[76:79], v[128:131], v[168:171], v[76:79]
	v_mfma_f32_16x16x32_bf16 v[72:75], v[136:139], v[168:171], v[72:75]
	v_mfma_f32_16x16x32_bf16 v[124:127], v[132:135], v[148:151], v[124:127]
	v_mfma_f32_16x16x32_bf16 v[120:123], v[140:143], v[148:151], v[120:123]
	v_mfma_f32_16x16x32_bf16 v[108:111], v[132:135], v[156:159], v[108:111]
	v_mfma_f32_16x16x32_bf16 v[104:107], v[140:143], v[156:159], v[104:107]
	v_mfma_f32_16x16x32_bf16 v[92:95], v[132:135], v[164:167], v[92:95]
	v_mfma_f32_16x16x32_bf16 v[88:91], v[140:143], v[164:167], v[88:91]
	v_mfma_f32_16x16x32_bf16 v[76:79], v[132:135], v[172:175], v[76:79]
	v_mfma_f32_16x16x32_bf16 v[72:75], v[140:143], v[172:175], v[72:75]
	s_setprio 0
	s_barrier
	s_add_i32 s68, s55, s44
	v_lshl_add_u64 v[206:207], s[38:39], 0, v[196:197]
	s_mov_b32 m0, s68
	ds_read_b128 v[176:179], v246
	ds_read_b128 v[180:183], v246 offset:1024
	ds_read_b128 v[184:187], v246 offset:2048
	ds_read_b128 v[188:191], v246 offset:3072
	global_load_lds_dwordx4 v[206:207], off
	v_lshl_add_u64 v[208:209], s[38:39], 0, v[200:201]
	s_add_i32 m0, s68, 0x2000
	s_nop 0
	global_load_lds_dwordx4 v[208:209], off
	s_barrier
	s_waitcnt lgkmcnt(0)
	s_setprio 1
	s_waitcnt lgkmcnt(0)
	v_mfma_f32_16x16x32_bf16 v[116:119], v[176:179], v[144:147], v[116:119]
	v_mfma_f32_16x16x32_bf16 v[112:115], v[184:187], v[144:147], v[112:115]
	v_mfma_f32_16x16x32_bf16 v[100:103], v[176:179], v[152:155], v[100:103]
	v_mfma_f32_16x16x32_bf16 v[96:99], v[184:187], v[152:155], v[96:99]
	v_mfma_f32_16x16x32_bf16 v[84:87], v[176:179], v[160:163], v[84:87]
	v_mfma_f32_16x16x32_bf16 v[80:83], v[184:187], v[160:163], v[80:83]
	v_mfma_f32_16x16x32_bf16 v[68:71], v[176:179], v[168:171], v[68:71]
	v_mfma_f32_16x16x32_bf16 v[64:67], v[184:187], v[168:171], v[64:67]
	v_mfma_f32_16x16x32_bf16 v[116:119], v[180:183], v[148:151], v[116:119]
	v_mfma_f32_16x16x32_bf16 v[112:115], v[188:191], v[148:151], v[112:115]
	v_mfma_f32_16x16x32_bf16 v[100:103], v[180:183], v[156:159], v[100:103]
	v_mfma_f32_16x16x32_bf16 v[96:99], v[188:191], v[156:159], v[96:99]
	v_mfma_f32_16x16x32_bf16 v[84:87], v[180:183], v[164:167], v[84:87]
	v_mfma_f32_16x16x32_bf16 v[80:83], v[188:191], v[164:167], v[80:83]
	v_mfma_f32_16x16x32_bf16 v[68:71], v[180:183], v[172:175], v[68:71]
	v_mfma_f32_16x16x32_bf16 v[64:67], v[188:191], v[172:175], v[64:67]
	s_setprio 0
	s_mov_b32 m0, s45
	v_lshl_add_u64 v[210:211], s[40:41], 0, v[194:195]
	s_barrier
	ds_read_b128 v[144:147], v245 offset:16384
	ds_read_b128 v[148:151], v245 offset:17408
	ds_read_b128 v[152:155], v245 offset:18432
	ds_read_b128 v[156:159], v245 offset:19456
	ds_read_b128 v[160:163], v245 offset:20480
	ds_read_b128 v[164:167], v245 offset:21504
	ds_read_b128 v[168:171], v245 offset:22528
	ds_read_b128 v[172:175], v245 offset:23552
	global_load_lds_dwordx4 v[210:211], off
	v_lshl_add_u64 v[212:213], s[40:41], 0, v[198:199]
	s_mov_b32 m0, s46
	s_nop 0
	global_load_lds_dwordx4 v[212:213], off
	s_barrier
	s_waitcnt lgkmcnt(0)
	s_setprio 1
	s_waitcnt lgkmcnt(0)
	v_mfma_f32_16x16x32_bf16 v[60:63], v[128:131], v[144:147], v[60:63]
	v_mfma_f32_16x16x32_bf16 v[56:59], v[136:139], v[144:147], v[56:59]
	v_mfma_f32_16x16x32_bf16 v[44:47], v[128:131], v[152:155], v[44:47]
	v_mfma_f32_16x16x32_bf16 v[40:43], v[136:139], v[152:155], v[40:43]
	v_mfma_f32_16x16x32_bf16 v[28:31], v[128:131], v[160:163], v[28:31]
	v_mfma_f32_16x16x32_bf16 v[24:27], v[136:139], v[160:163], v[24:27]
	v_mfma_f32_16x16x32_bf16 v[12:15], v[128:131], v[168:171], v[12:15]
	v_mfma_f32_16x16x32_bf16 v[8:11], v[136:139], v[168:171], v[8:11]
	v_mfma_f32_16x16x32_bf16 v[60:63], v[132:135], v[148:151], v[60:63]
	v_mfma_f32_16x16x32_bf16 v[56:59], v[140:143], v[148:151], v[56:59]
	v_mfma_f32_16x16x32_bf16 v[44:47], v[132:135], v[156:159], v[44:47]
	v_mfma_f32_16x16x32_bf16 v[40:43], v[140:143], v[156:159], v[40:43]
	v_mfma_f32_16x16x32_bf16 v[28:31], v[132:135], v[164:167], v[28:31]
	v_mfma_f32_16x16x32_bf16 v[24:27], v[140:143], v[164:167], v[24:27]
	v_mfma_f32_16x16x32_bf16 v[12:15], v[132:135], v[172:175], v[12:15]
	v_mfma_f32_16x16x32_bf16 v[8:11], v[140:143], v[172:175], v[8:11]
	s_setprio 0
	s_barrier
	s_add_u32 s68, s38, 0xb0000
	s_addc_u32 s69, s39, 0
	s_add_i32 s70, s56, s44
	v_lshl_add_u64 v[128:129], s[68:69], 0, v[196:197]
	s_mov_b32 m0, s70
	s_nop 0
	global_load_lds_dwordx4 v[128:129], off
	v_lshl_add_u64 v[128:129], s[68:69], 0, v[200:201]
	s_add_i32 m0, s70, 0x2000
	s_nop 0
	global_load_lds_dwordx4 v[128:129], off
	s_waitcnt vmcnt(6)
	s_barrier
	s_setprio 1
	v_mfma_f32_16x16x32_bf16 v[52:55], v[176:179], v[144:147], v[52:55]
	v_mfma_f32_16x16x32_bf16 v[48:51], v[184:187], v[144:147], v[48:51]
	v_mfma_f32_16x16x32_bf16 v[36:39], v[176:179], v[152:155], v[36:39]
	v_mfma_f32_16x16x32_bf16 v[32:35], v[184:187], v[152:155], v[32:35]
	v_mfma_f32_16x16x32_bf16 v[20:23], v[176:179], v[160:163], v[20:23]
	v_mfma_f32_16x16x32_bf16 v[16:19], v[184:187], v[160:163], v[16:19]
	v_mfma_f32_16x16x32_bf16 v[4:7], v[176:179], v[168:171], v[4:7]
	v_mfma_f32_16x16x32_bf16 v[0:3], v[184:187], v[168:171], v[0:3]
	v_mfma_f32_16x16x32_bf16 v[52:55], v[180:183], v[148:151], v[52:55]
	v_mfma_f32_16x16x32_bf16 v[48:51], v[188:191], v[148:151], v[48:51]
	v_mfma_f32_16x16x32_bf16 v[36:39], v[180:183], v[156:159], v[36:39]
	v_mfma_f32_16x16x32_bf16 v[32:35], v[188:191], v[156:159], v[32:35]
	v_mfma_f32_16x16x32_bf16 v[20:23], v[180:183], v[164:167], v[20:23]
	v_mfma_f32_16x16x32_bf16 v[16:19], v[188:191], v[164:167], v[16:19]
	v_mfma_f32_16x16x32_bf16 v[4:7], v[180:183], v[172:175], v[4:7]
	v_mfma_f32_16x16x32_bf16 v[0:3], v[188:191], v[172:175], v[0:3]
	s_setprio 0
	s_add_i32 s68, 0, 0x18000
	v_add_u32_e32 v140, s68, v242
	s_barrier
	ds_read_b128 v[128:131], v140
	ds_read_b128 v[132:135], v140 offset:1024
	ds_read_b128 v[136:139], v140 offset:2048
	ds_read_b128 v[140:143], v140 offset:3072
	s_add_u32 s40, s40, 0xb0000
	s_addc_u32 s41, s41, 0
	s_mov_b32 m0, s47
	v_lshl_add_u64 v[176:177], s[40:41], 0, v[194:195]
	ds_read_b128 v[144:147], v245 offset:32768
	ds_read_b128 v[148:151], v245 offset:33792
	ds_read_b128 v[152:155], v245 offset:34816
	ds_read_b128 v[156:159], v245 offset:35840
	ds_read_b128 v[160:163], v245 offset:36864
	ds_read_b128 v[164:167], v245 offset:37888
	ds_read_b128 v[168:171], v245 offset:38912
	ds_read_b128 v[172:175], v245 offset:39936
	global_load_lds_dwordx4 v[176:177], off
	v_lshl_add_u64 v[176:177], s[40:41], 0, v[198:199]
	s_mov_b32 m0, s48
	s_nop 0
	global_load_lds_dwordx4 v[176:177], off
	s_waitcnt lgkmcnt(8)
	s_barrier
	s_waitcnt lgkmcnt(0)
	s_setprio 1
	s_waitcnt lgkmcnt(0)
	v_mfma_f32_16x16x32_bf16 v[124:127], v[128:131], v[144:147], v[124:127]
	v_mfma_f32_16x16x32_bf16 v[120:123], v[136:139], v[144:147], v[120:123]
	v_mfma_f32_16x16x32_bf16 v[108:111], v[128:131], v[152:155], v[108:111]
	v_mfma_f32_16x16x32_bf16 v[104:107], v[136:139], v[152:155], v[104:107]
	v_mfma_f32_16x16x32_bf16 v[92:95], v[128:131], v[160:163], v[92:95]
	v_mfma_f32_16x16x32_bf16 v[88:91], v[136:139], v[160:163], v[88:91]
	v_mfma_f32_16x16x32_bf16 v[76:79], v[128:131], v[168:171], v[76:79]
	v_mfma_f32_16x16x32_bf16 v[72:75], v[136:139], v[168:171], v[72:75]
	v_mfma_f32_16x16x32_bf16 v[124:127], v[132:135], v[148:151], v[124:127]
	v_mfma_f32_16x16x32_bf16 v[120:123], v[140:143], v[148:151], v[120:123]
	v_mfma_f32_16x16x32_bf16 v[108:111], v[132:135], v[156:159], v[108:111]
	v_mfma_f32_16x16x32_bf16 v[104:107], v[140:143], v[156:159], v[104:107]
	v_mfma_f32_16x16x32_bf16 v[92:95], v[132:135], v[164:167], v[92:95]
	v_mfma_f32_16x16x32_bf16 v[88:91], v[140:143], v[164:167], v[88:91]
	v_mfma_f32_16x16x32_bf16 v[76:79], v[132:135], v[172:175], v[76:79]
	v_mfma_f32_16x16x32_bf16 v[72:75], v[140:143], v[172:175], v[72:75]
	s_setprio 0
	s_barrier
	s_add_i32 s40, 0, 0x1c000
	s_add_i32 s41, s68, s44
	v_add_u32_e32 v188, s40, v242
	v_lshl_add_u64 v[206:207], v[206:207], 0, s[28:29]
	s_mov_b32 m0, s41
	ds_read_b128 v[176:179], v188
	ds_read_b128 v[180:183], v188 offset:1024
	ds_read_b128 v[184:187], v188 offset:2048
	ds_read_b128 v[188:191], v188 offset:3072
	global_load_lds_dwordx4 v[206:207], off
	v_lshl_add_u64 v[206:207], v[208:209], 0, s[28:29]
	s_add_i32 m0, s41, 0x2000
	s_nop 0
	global_load_lds_dwordx4 v[206:207], off
	s_barrier
	s_waitcnt lgkmcnt(0)
	s_setprio 1
	s_waitcnt lgkmcnt(0)
	v_mfma_f32_16x16x32_bf16 v[116:119], v[176:179], v[144:147], v[116:119]
	v_mfma_f32_16x16x32_bf16 v[112:115], v[184:187], v[144:147], v[112:115]
	v_mfma_f32_16x16x32_bf16 v[100:103], v[176:179], v[152:155], v[100:103]
	v_mfma_f32_16x16x32_bf16 v[96:99], v[184:187], v[152:155], v[96:99]
	v_mfma_f32_16x16x32_bf16 v[84:87], v[176:179], v[160:163], v[84:87]
	v_mfma_f32_16x16x32_bf16 v[80:83], v[184:187], v[160:163], v[80:83]
	v_mfma_f32_16x16x32_bf16 v[68:71], v[176:179], v[168:171], v[68:71]
	v_mfma_f32_16x16x32_bf16 v[64:67], v[184:187], v[168:171], v[64:67]
	v_mfma_f32_16x16x32_bf16 v[116:119], v[180:183], v[148:151], v[116:119]
	v_mfma_f32_16x16x32_bf16 v[112:115], v[188:191], v[148:151], v[112:115]
	v_mfma_f32_16x16x32_bf16 v[100:103], v[180:183], v[156:159], v[100:103]
	v_mfma_f32_16x16x32_bf16 v[96:99], v[188:191], v[156:159], v[96:99]
	v_mfma_f32_16x16x32_bf16 v[84:87], v[180:183], v[164:167], v[84:87]
	v_mfma_f32_16x16x32_bf16 v[80:83], v[188:191], v[164:167], v[80:83]
	v_mfma_f32_16x16x32_bf16 v[68:71], v[180:183], v[172:175], v[68:71]
	v_mfma_f32_16x16x32_bf16 v[64:67], v[188:191], v[172:175], v[64:67]
	s_setprio 0
	s_mov_b32 m0, s50
	v_lshl_add_u64 v[206:207], v[210:211], 0, s[28:29]
	s_barrier
	ds_read_b128 v[144:147], v245 offset:49152
	ds_read_b128 v[148:151], v245 offset:50176
	ds_read_b128 v[152:155], v245 offset:51200
	ds_read_b128 v[156:159], v245 offset:52224
	ds_read_b128 v[160:163], v245 offset:53248
	ds_read_b128 v[164:167], v245 offset:54272
	ds_read_b128 v[168:171], v245 offset:55296
	ds_read_b128 v[172:175], v245 offset:56320
	global_load_lds_dwordx4 v[206:207], off
	v_lshl_add_u64 v[206:207], v[212:213], 0, s[28:29]
	s_mov_b32 m0, s51
	s_nop 0
	global_load_lds_dwordx4 v[206:207], off
	s_barrier
	s_waitcnt lgkmcnt(0)
	s_setprio 1
	s_waitcnt lgkmcnt(0)
	v_mfma_f32_16x16x32_bf16 v[60:63], v[128:131], v[144:147], v[60:63]
	v_mfma_f32_16x16x32_bf16 v[56:59], v[136:139], v[144:147], v[56:59]
	v_mfma_f32_16x16x32_bf16 v[44:47], v[128:131], v[152:155], v[44:47]
	v_mfma_f32_16x16x32_bf16 v[40:43], v[136:139], v[152:155], v[40:43]
	v_mfma_f32_16x16x32_bf16 v[28:31], v[128:131], v[160:163], v[28:31]
	v_mfma_f32_16x16x32_bf16 v[24:27], v[136:139], v[160:163], v[24:27]
	v_mfma_f32_16x16x32_bf16 v[12:15], v[128:131], v[168:171], v[12:15]
	v_mfma_f32_16x16x32_bf16 v[8:11], v[136:139], v[168:171], v[8:11]
	v_mfma_f32_16x16x32_bf16 v[60:63], v[132:135], v[148:151], v[60:63]
	v_mfma_f32_16x16x32_bf16 v[56:59], v[140:143], v[148:151], v[56:59]
	v_mfma_f32_16x16x32_bf16 v[44:47], v[132:135], v[156:159], v[44:47]
	v_mfma_f32_16x16x32_bf16 v[40:43], v[140:143], v[156:159], v[40:43]
	v_mfma_f32_16x16x32_bf16 v[28:31], v[132:135], v[164:167], v[28:31]
	v_mfma_f32_16x16x32_bf16 v[24:27], v[140:143], v[164:167], v[24:27]
	v_mfma_f32_16x16x32_bf16 v[12:15], v[132:135], v[172:175], v[12:15]
	v_mfma_f32_16x16x32_bf16 v[8:11], v[140:143], v[172:175], v[8:11]
	s_setprio 0
	s_barrier
	s_add_u32 s38, s38, 0xb0080
	s_addc_u32 s39, s39, 0
	s_add_i32 s40, s40, s44
	v_lshl_add_u64 v[128:129], s[38:39], 0, v[196:197]
	s_mov_b32 m0, s40
	s_nop 0
	global_load_lds_dwordx4 v[128:129], off
	v_lshl_add_u64 v[128:129], s[38:39], 0, v[200:201]
	s_add_i32 m0, s40, 0x2000
	s_nop 0
	global_load_lds_dwordx4 v[128:129], off
	s_waitcnt vmcnt(6)
	s_barrier
	s_setprio 1
	v_mfma_f32_16x16x32_bf16 v[52:55], v[176:179], v[144:147], v[52:55]
	v_mfma_f32_16x16x32_bf16 v[48:51], v[184:187], v[144:147], v[48:51]
	v_mfma_f32_16x16x32_bf16 v[36:39], v[176:179], v[152:155], v[36:39]
	v_mfma_f32_16x16x32_bf16 v[32:35], v[184:187], v[152:155], v[32:35]
	v_mfma_f32_16x16x32_bf16 v[20:23], v[176:179], v[160:163], v[20:23]
	v_mfma_f32_16x16x32_bf16 v[16:19], v[184:187], v[160:163], v[16:19]
	v_mfma_f32_16x16x32_bf16 v[4:7], v[176:179], v[168:171], v[4:7]
	v_mfma_f32_16x16x32_bf16 v[0:3], v[184:187], v[168:171], v[0:3]
	v_mfma_f32_16x16x32_bf16 v[52:55], v[180:183], v[148:151], v[52:55]
	v_mfma_f32_16x16x32_bf16 v[48:51], v[188:191], v[148:151], v[48:51]
	v_mfma_f32_16x16x32_bf16 v[36:39], v[180:183], v[156:159], v[36:39]
	v_mfma_f32_16x16x32_bf16 v[32:35], v[188:191], v[156:159], v[32:35]
	v_mfma_f32_16x16x32_bf16 v[20:23], v[180:183], v[164:167], v[20:23]
	v_mfma_f32_16x16x32_bf16 v[16:19], v[188:191], v[164:167], v[16:19]
	v_mfma_f32_16x16x32_bf16 v[4:7], v[180:183], v[172:175], v[4:7]
	v_mfma_f32_16x16x32_bf16 v[0:3], v[188:191], v[172:175], v[0:3]
	s_setprio 0
	s_add_i32 s67, s67, 2
	s_add_u32 s36, s36, 0x100
	s_addc_u32 s37, s37, 0
	s_add_u32 s16, s16, 0x100
	s_addc_u32 s66, s66, 0
	s_cmp_gt_u32 s67, 41
	s_barrier
	s_cbranch_scc0 .LBB0_268
	v_lshl_add_u32 v216, s65, 8, v193
	v_lshl_or_b32 v206, s64, 8, v243
	v_or_b32_e32 v214, 16, v216
	v_or_b32_e32 v210, 32, v216
	v_or_b32_e32 v208, 48, v216
	v_ashrrev_i32_e32 v207, 31, v206
	s_andn2_b64 vcc, exec, s[34:35]
	v_ashrrev_i32_e32 v217, 31, v216
	v_ashrrev_i32_e32 v215, 31, v214
	v_ashrrev_i32_e32 v211, 31, v210
	v_ashrrev_i32_e32 v209, 31, v208
	s_cbranch_vccnz .LBB0_300
	v_lshl_add_u64 v[176:177], v[206:207], 2, s[12:13]
	v_lshlrev_b64 v[128:129], 12, v[216:217]
	v_lshl_add_u64 v[128:129], v[176:177], 0, v[128:129]
	global_load_dwordx4 v[178:181], v[128:129], off
	global_load_dwordx4 v[186:189], v[128:129], off offset:16
	global_load_dwordx4 v[218:221], v[128:129], off offset:512
	global_load_dwordx4 v[222:225], v[128:129], off offset:528
	v_lshlrev_b64 v[128:129], 12, v[214:215]
	v_lshlrev_b64 v[130:131], 12, v[210:211]
	v_lshlrev_b64 v[132:133], 12, v[208:209]
	v_lshl_add_u64 v[128:129], v[176:177], 0, v[128:129]
	v_lshl_add_u64 v[130:131], v[176:177], 0, v[130:131]
	v_lshl_add_u64 v[132:133], v[176:177], 0, v[132:133]
	global_load_dwordx4 v[168:171], v[128:129], off offset:16
	global_load_dwordx4 v[172:175], v[128:129], off
	global_load_dwordx4 v[160:163], v[128:129], off offset:528
	global_load_dwordx4 v[164:167], v[128:129], off offset:512
	global_load_dwordx4 v[152:155], v[130:131], off offset:16
	global_load_dwordx4 v[156:159], v[130:131], off
	global_load_dwordx4 v[144:147], v[130:131], off offset:528
	global_load_dwordx4 v[148:151], v[130:131], off offset:512
	global_load_dwordx4 v[136:139], v[132:133], off offset:16
	global_load_dwordx4 v[140:143], v[132:133], off
	s_nop 0
	global_load_dwordx4 v[128:131], v[132:133], off offset:528
	s_nop 0
	global_load_dwordx4 v[132:135], v[132:133], off offset:512
	v_and_b32_e32 v185, 64, v247
	v_xor_b32_e32 v184, 16, v247
	v_add_u32_e32 v185, 64, v185
	v_xor_b32_e32 v190, 32, v247
	v_cmp_lt_i32_e32 vcc, v184, v185
	v_lshlrev_b64 v[182:183], 11, v[216:217]
	v_lshl_add_u64 v[182:183], s[24:25], 0, v[182:183]
	v_cndmask_b32_e32 v184, v247, v184, vcc
	v_cmp_lt_i32_e32 vcc, v190, v185
	v_lshlrev_b32_e32 v185, 2, v184
	s_lshl_b32 s36, s64, 2
	v_cndmask_b32_e32 v190, v247, v190, vcc
	v_lshlrev_b32_e32 v184, 2, v190
	s_ashr_i32 s37, s36, 31
	s_waitcnt vmcnt(0)
	v_pk_add_f32 v[190:191], v[126:127], v[180:181]
	v_pk_add_f32 v[212:213], v[124:125], v[178:179]
	v_pk_add_f32 v[188:189], v[122:123], v[188:189]
	v_pk_add_f32 v[186:187], v[120:121], v[186:187]
	v_pk_add_f32 v[220:221], v[118:119], v[220:221]
	v_pk_add_f32 v[218:219], v[116:117], v[218:219]
	v_pk_add_f32 v[224:225], v[114:115], v[224:225]
	v_pk_add_f32 v[222:223], v[112:113], v[222:223]
	v_mul_f32_e32 v226, v213, v213
	v_mul_f32_e32 v227, v191, v191
	v_mul_f32_e32 v228, v187, v187
	v_mul_f32_e32 v229, v189, v189
	v_cvt_pk_bf16_f32 v178, v212, v213
	v_cvt_pk_bf16_f32 v179, v190, v191
	v_cvt_pk_bf16_f32 v180, v186, v187
	v_cvt_pk_bf16_f32 v181, v188, v189
	v_mul_f32_e32 v187, v219, v219
	v_mul_f32_e32 v189, v221, v221
	v_mul_f32_e32 v191, v223, v223
	v_mul_f32_e32 v213, v225, v225
	v_fmac_f32_e32 v226, v212, v212
	v_fmac_f32_e32 v227, v190, v190
	v_fmac_f32_e32 v228, v186, v186
	v_fmac_f32_e32 v229, v188, v188
	v_fmac_f32_e32 v187, v218, v218
	v_fmac_f32_e32 v189, v220, v220
	v_fmac_f32_e32 v191, v222, v222
	v_fmac_f32_e32 v213, v224, v224
	v_add_f32_e32 v186, v226, v227
	v_add_f32_e32 v188, v228, v229
	v_add_f32_e32 v187, v187, v189
	v_add_f32_e32 v189, v191, v213
	v_add_f32_e32 v186, v186, v188
	v_add_f32_e32 v187, v187, v189
	v_add_f32_e32 v188, v186, v187
	v_mov_b32_e32 v189, v188
	s_nop 1
	v_permlane16_swap_b32_e32 v188, v189
	v_lshl_add_u64 v[186:187], v[206:207], 1, v[182:183]
	global_store_dwordx4 v[186:187], v[178:181], off sc1
	v_cvt_pk_bf16_f32 v182, v222, v223
	v_cvt_pk_bf16_f32 v183, v224, v225
	s_waitcnt lgkmcnt(0)
	v_add_f32_e32 v178, v188, v189
	v_mov_b32_e32 v179, v178
	s_nop 1
	v_permlane32_swap_b32_e32 v178, v179
	v_cvt_pk_bf16_f32 v180, v218, v219
	v_cvt_pk_bf16_f32 v181, v220, v221
	global_store_dwordx4 v[186:187], v[180:183], off offset:256 sc1
	s_and_saveexec_b64 s[38:39], s[30:31]
	s_cbranch_execz .LBB0_272
	v_lshlrev_b64 v[180:181], 6, v[216:217]
	v_lshl_add_u64 v[180:181], s[26:27], 0, v[180:181]
	v_lshl_add_u64 v[180:181], s[36:37], 2, v[180:181]
	s_lshl_b32 s16, s49, 2
	v_lshl_add_u64 v[180:181], v[180:181], 0, s[16:17]
	s_waitcnt lgkmcnt(0)
	v_add_f32_e32 v178, v178, v179
	global_store_dword v[180:181], v178, off
.LBB0_272:
	s_or_b64 exec, exec, s[38:39]
	v_pk_add_f32 v[174:175], v[110:111], v[174:175]
	v_pk_add_f32 v[172:173], v[108:109], v[172:173]
	v_pk_add_f32 v[180:181], v[106:107], v[170:171]
	v_pk_add_f32 v[170:171], v[104:105], v[168:169]
	v_mul_f32_e32 v168, v173, v173
	v_mul_f32_e32 v169, v175, v175
	v_fmac_f32_e32 v168, v172, v172
	v_fmac_f32_e32 v169, v174, v174
	v_add_f32_e32 v168, v168, v169
	v_mul_f32_e32 v169, v171, v171
	v_mul_f32_e32 v182, v181, v181
	v_fmac_f32_e32 v169, v170, v170
	v_fmac_f32_e32 v182, v180, v180
	v_add_f32_e32 v169, v169, v182
	v_pk_add_f32 v[166:167], v[102:103], v[166:167]
	v_pk_add_f32 v[164:165], v[100:101], v[164:165]
	v_add_f32_e32 v182, v168, v169
	v_cvt_pk_bf16_f32 v169, v174, v175
	v_pk_add_f32 v[174:175], v[96:97], v[160:161]
	v_mul_f32_e32 v160, v165, v165
	v_mul_f32_e32 v161, v167, v167
	v_cvt_pk_bf16_f32 v168, v172, v173
	v_pk_add_f32 v[172:173], v[98:99], v[162:163]
	v_fmac_f32_e32 v160, v164, v164
	v_fmac_f32_e32 v161, v166, v166
	v_add_f32_e32 v160, v160, v161
	v_mul_f32_e32 v161, v175, v175
	v_mul_f32_e32 v162, v173, v173
	v_fmac_f32_e32 v161, v174, v174
	v_fmac_f32_e32 v162, v172, v172
	v_add_f32_e32 v161, v161, v162
	v_add_f32_e32 v160, v160, v161
	v_add_f32_e32 v163, v182, v160
	v_cvt_pk_bf16_f32 v170, v170, v171
	v_cvt_pk_bf16_f32 v171, v180, v181
	v_mov_b32_e32 v180, v163
	s_nop 1
	v_permlane16_swap_b32_e32 v163, v180
	s_waitcnt lgkmcnt(1)
	v_lshlrev_b64 v[178:179], 11, v[214:215]
	v_lshl_add_u64 v[160:161], s[24:25], 0, v[178:179]
	v_lshl_add_u64 v[178:179], v[206:207], 1, v[160:161]
	v_cvt_pk_bf16_f32 v162, v164, v165
	s_waitcnt lgkmcnt(0)
	v_add_f32_e32 v160, v163, v180
	v_mov_b32_e32 v161, v160
	s_nop 1
	v_permlane32_swap_b32_e32 v160, v161
	v_cvt_pk_bf16_f32 v163, v166, v167
	v_cvt_pk_bf16_f32 v164, v174, v175
	v_cvt_pk_bf16_f32 v165, v172, v173
	global_store_dwordx4 v[178:179], v[168:171], off sc1
	global_store_dwordx4 v[178:179], v[162:165], off offset:256 sc1
	s_and_saveexec_b64 s[38:39], s[30:31]
	s_cbranch_execz .LBB0_274
	v_lshlrev_b64 v[162:163], 6, v[214:215]
	v_lshl_add_u64 v[162:163], s[26:27], 0, v[162:163]
	v_lshl_add_u64 v[162:163], s[36:37], 2, v[162:163]
	s_lshl_b32 s16, s49, 2
	v_lshl_add_u64 v[162:163], v[162:163], 0, s[16:17]
	s_waitcnt lgkmcnt(0)
	v_add_f32_e32 v160, v160, v161
	global_store_dword v[162:163], v160, off
.LBB0_274:
	s_or_b64 exec, exec, s[38:39]
	v_pk_add_f32 v[158:159], v[94:95], v[158:159]
	v_pk_add_f32 v[156:157], v[92:93], v[156:157]
	v_pk_add_f32 v[162:163], v[90:91], v[154:155]
	v_pk_add_f32 v[154:155], v[88:89], v[152:153]
	v_mul_f32_e32 v152, v157, v157
	v_mul_f32_e32 v153, v159, v159
	v_fmac_f32_e32 v152, v156, v156
	v_fmac_f32_e32 v153, v158, v158
	v_add_f32_e32 v152, v152, v153
	v_mul_f32_e32 v153, v155, v155
	v_mul_f32_e32 v164, v163, v163
	v_fmac_f32_e32 v153, v154, v154
	v_fmac_f32_e32 v164, v162, v162
	v_add_f32_e32 v153, v153, v164
	v_pk_add_f32 v[150:151], v[86:87], v[150:151]
	v_pk_add_f32 v[148:149], v[84:85], v[148:149]
	v_add_f32_e32 v164, v152, v153
	v_cvt_pk_bf16_f32 v153, v158, v159
	v_pk_add_f32 v[158:159], v[80:81], v[144:145]
	v_mul_f32_e32 v144, v149, v149
	v_mul_f32_e32 v145, v151, v151
	v_cvt_pk_bf16_f32 v152, v156, v157
	v_pk_add_f32 v[156:157], v[82:83], v[146:147]
	v_fmac_f32_e32 v144, v148, v148
	v_fmac_f32_e32 v145, v150, v150
	v_add_f32_e32 v144, v144, v145
	v_mul_f32_e32 v145, v159, v159
	v_mul_f32_e32 v146, v157, v157
	v_fmac_f32_e32 v145, v158, v158
	v_fmac_f32_e32 v146, v156, v156
	v_add_f32_e32 v145, v145, v146
	v_add_f32_e32 v144, v144, v145
	v_add_f32_e32 v147, v164, v144
	v_cvt_pk_bf16_f32 v154, v154, v155
	v_cvt_pk_bf16_f32 v155, v162, v163
	v_mov_b32_e32 v162, v147
	s_nop 1
	v_permlane16_swap_b32_e32 v147, v162
	s_waitcnt lgkmcnt(1)
	v_lshlrev_b64 v[160:161], 11, v[210:211]
	v_lshl_add_u64 v[144:145], s[24:25], 0, v[160:161]
	v_lshl_add_u64 v[160:161], v[206:207], 1, v[144:145]
	v_cvt_pk_bf16_f32 v146, v148, v149
	s_waitcnt lgkmcnt(0)
	v_add_f32_e32 v144, v147, v162
	v_mov_b32_e32 v145, v144
	s_nop 1
	v_permlane32_swap_b32_e32 v144, v145
	v_cvt_pk_bf16_f32 v147, v150, v151
	v_cvt_pk_bf16_f32 v148, v158, v159
	v_cvt_pk_bf16_f32 v149, v156, v157
	global_store_dwordx4 v[160:161], v[152:155], off sc1
	global_store_dwordx4 v[160:161], v[146:149], off offset:256 sc1
	s_and_saveexec_b64 s[38:39], s[30:31]
	s_cbranch_execz .LBB0_276
	v_lshlrev_b64 v[146:147], 6, v[210:211]
	v_lshl_add_u64 v[146:147], s[26:27], 0, v[146:147]
	v_lshl_add_u64 v[146:147], s[36:37], 2, v[146:147]
	s_lshl_b32 s16, s49, 2
	v_lshl_add_u64 v[146:147], v[146:147], 0, s[16:17]
	s_waitcnt lgkmcnt(0)
	v_add_f32_e32 v144, v144, v145
	global_store_dword v[146:147], v144, off
.LBB0_276:
	s_or_b64 exec, exec, s[38:39]
	v_pk_add_f32 v[142:143], v[78:79], v[142:143]
	v_pk_add_f32 v[140:141], v[76:77], v[140:141]
	v_pk_add_f32 v[146:147], v[74:75], v[138:139]
	v_pk_add_f32 v[138:139], v[72:73], v[136:137]
	v_mul_f32_e32 v136, v141, v141
	v_mul_f32_e32 v137, v143, v143
	v_fmac_f32_e32 v136, v140, v140
	v_fmac_f32_e32 v137, v142, v142
	v_add_f32_e32 v136, v136, v137
	v_mul_f32_e32 v137, v139, v139
	v_mul_f32_e32 v148, v147, v147
	v_fmac_f32_e32 v137, v138, v138
	v_fmac_f32_e32 v148, v146, v146
	v_add_f32_e32 v137, v137, v148
	v_pk_add_f32 v[134:135], v[70:71], v[134:135]
	v_pk_add_f32 v[132:133], v[68:69], v[132:133]
	v_add_f32_e32 v148, v136, v137
	v_cvt_pk_bf16_f32 v137, v142, v143
	v_pk_add_f32 v[142:143], v[64:65], v[128:129]
	v_mul_f32_e32 v128, v133, v133
	v_mul_f32_e32 v129, v135, v135
	v_cvt_pk_bf16_f32 v136, v140, v141
	v_pk_add_f32 v[140:141], v[66:67], v[130:131]
	v_fmac_f32_e32 v128, v132, v132
	v_fmac_f32_e32 v129, v134, v134
	v_add_f32_e32 v128, v128, v129
	v_mul_f32_e32 v129, v143, v143
	v_mul_f32_e32 v130, v141, v141
	v_fmac_f32_e32 v129, v142, v142
	v_fmac_f32_e32 v130, v140, v140
	v_add_f32_e32 v129, v129, v130
	v_add_f32_e32 v128, v128, v129
	v_add_f32_e32 v131, v148, v128
	v_cvt_pk_bf16_f32 v138, v138, v139
	v_cvt_pk_bf16_f32 v139, v146, v147
	v_mov_b32_e32 v146, v131
	s_nop 1
	v_permlane16_swap_b32_e32 v131, v146
	s_waitcnt lgkmcnt(1)
	v_lshlrev_b64 v[144:145], 11, v[208:209]
	v_lshl_add_u64 v[128:129], s[24:25], 0, v[144:145]
	v_lshl_add_u64 v[144:145], v[206:207], 1, v[128:129]
	v_cvt_pk_bf16_f32 v130, v132, v133
	s_waitcnt lgkmcnt(0)
	v_add_f32_e32 v128, v131, v146
	v_mov_b32_e32 v129, v128
	s_nop 1
	v_permlane32_swap_b32_e32 v128, v129
	v_cvt_pk_bf16_f32 v131, v134, v135
	v_cvt_pk_bf16_f32 v132, v142, v143
	v_cvt_pk_bf16_f32 v133, v140, v141
	global_store_dwordx4 v[144:145], v[136:139], off sc1
	global_store_dwordx4 v[144:145], v[130:133], off offset:256 sc1
	s_and_saveexec_b64 s[38:39], s[30:31]
	s_cbranch_execz .LBB0_278
	v_lshlrev_b64 v[130:131], 6, v[208:209]
	v_lshl_add_u64 v[130:131], s[26:27], 0, v[130:131]
	v_lshl_add_u64 v[130:131], s[36:37], 2, v[130:131]
	s_lshl_b32 s16, s49, 2
	v_lshl_add_u64 v[130:131], v[130:131], 0, s[16:17]
	s_waitcnt lgkmcnt(0)
	v_add_f32_e32 v128, v128, v129
	global_store_dword v[130:131], v128, off
.LBB0_278:
	s_or_b64 exec, exec, s[38:39]
	v_add_u32_e32 v182, 0x80, v216
	v_ashrrev_i32_e32 v183, 31, v182
	s_waitcnt lgkmcnt(0)
	v_lshlrev_b64 v[128:129], 12, v[182:183]
	v_lshl_add_u64 v[128:129], v[176:177], 0, v[128:129]
	global_load_dwordx4 v[186:189], v[128:129], off
	global_load_dwordx4 v[218:221], v[128:129], off offset:16
	global_load_dwordx4 v[222:225], v[128:129], off offset:512
	global_load_dwordx4 v[226:229], v[128:129], off offset:528
	v_add_u32_e32 v180, 0x90, v216
	v_add_u32_e32 v178, 0xa0, v216
	v_add_u32_e32 v212, 0xb0, v216
	v_ashrrev_i32_e32 v181, 31, v180
	v_ashrrev_i32_e32 v179, 31, v178
	v_ashrrev_i32_e32 v213, 31, v212
	v_lshlrev_b64 v[128:129], 12, v[180:181]
	v_lshlrev_b64 v[130:131], 12, v[178:179]
	v_lshlrev_b64 v[132:133], 12, v[212:213]
	v_lshl_add_u64 v[128:129], v[176:177], 0, v[128:129]
	v_lshl_add_u64 v[130:131], v[176:177], 0, v[130:131]
	v_lshl_add_u64 v[132:133], v[176:177], 0, v[132:133]
	global_load_dwordx4 v[168:171], v[128:129], off offset:16
	global_load_dwordx4 v[172:175], v[128:129], off
	global_load_dwordx4 v[160:163], v[128:129], off offset:528
	global_load_dwordx4 v[164:167], v[128:129], off offset:512
	global_load_dwordx4 v[152:155], v[130:131], off offset:16
	global_load_dwordx4 v[156:159], v[130:131], off
	global_load_dwordx4 v[144:147], v[130:131], off offset:528
	global_load_dwordx4 v[148:151], v[130:131], off offset:512
	global_load_dwordx4 v[136:139], v[132:133], off offset:16
	global_load_dwordx4 v[140:143], v[132:133], off
	s_nop 0
	global_load_dwordx4 v[128:131], v[132:133], off offset:528
	s_nop 0
	global_load_dwordx4 v[132:135], v[132:133], off offset:512
	v_lshlrev_b64 v[176:177], 11, v[182:183]
	v_lshl_add_u64 v[176:177], s[24:25], 0, v[176:177]
	s_waitcnt vmcnt(15)
	v_pk_add_f32 v[190:191], v[62:63], v[188:189]
	v_pk_add_f32 v[230:231], v[60:61], v[186:187]
	s_waitcnt vmcnt(14)
	v_pk_add_f32 v[220:221], v[58:59], v[220:221]
	v_pk_add_f32 v[218:219], v[56:57], v[218:219]
	s_waitcnt vmcnt(13)
	v_pk_add_f32 v[224:225], v[54:55], v[224:225]
	v_pk_add_f32 v[222:223], v[52:53], v[222:223]
	s_waitcnt vmcnt(12)
	v_pk_add_f32 v[228:229], v[50:51], v[228:229]
	v_pk_add_f32 v[226:227], v[48:49], v[226:227]
	v_mul_f32_e32 v232, v231, v231
	v_mul_f32_e32 v233, v191, v191
	v_mul_f32_e32 v234, v219, v219
	v_mul_f32_e32 v235, v221, v221
	v_cvt_pk_bf16_f32 v186, v230, v231
	v_cvt_pk_bf16_f32 v187, v190, v191
	v_cvt_pk_bf16_f32 v188, v218, v219
	v_cvt_pk_bf16_f32 v189, v220, v221
	v_mul_f32_e32 v191, v223, v223
	v_mul_f32_e32 v219, v225, v225
	v_mul_f32_e32 v221, v227, v227
	v_mul_f32_e32 v231, v229, v229
	v_fmac_f32_e32 v232, v230, v230
	v_fmac_f32_e32 v233, v190, v190
	v_fmac_f32_e32 v234, v218, v218
	v_fmac_f32_e32 v235, v220, v220
	v_fmac_f32_e32 v191, v222, v222
	v_fmac_f32_e32 v219, v224, v224
	v_fmac_f32_e32 v221, v226, v226
	v_fmac_f32_e32 v231, v228, v228
	v_add_f32_e32 v190, v232, v233
	v_add_f32_e32 v218, v234, v235
	v_add_f32_e32 v191, v191, v219
	v_add_f32_e32 v219, v221, v231
	v_add_f32_e32 v190, v190, v218
	v_add_f32_e32 v191, v191, v219
	v_add_f32_e32 v218, v190, v191
	v_mov_b32_e32 v219, v218
	s_nop 1
	v_permlane16_swap_b32_e32 v218, v219
	v_lshl_add_u64 v[190:191], v[206:207], 1, v[176:177]
	global_store_dwordx4 v[190:191], v[186:189], off sc1
	s_waitcnt lgkmcnt(0)
	v_add_f32_e32 v176, v218, v219
	s_nop 1
	v_mov_b32_e32 v177, v176
	s_nop 1
	v_permlane32_swap_b32_e32 v176, v177
	v_cvt_pk_bf16_f32 v186, v222, v223
	v_cvt_pk_bf16_f32 v187, v224, v225
	v_cvt_pk_bf16_f32 v188, v226, v227
	v_cvt_pk_bf16_f32 v189, v228, v229
	global_store_dwordx4 v[190:191], v[186:189], off offset:256 sc1
	s_and_saveexec_b64 s[38:39], s[30:31]
	s_cbranch_execz .LBB0_280
	v_lshlrev_b64 v[182:183], 6, v[182:183]
	v_lshl_add_u64 v[182:183], s[26:27], 0, v[182:183]
	v_lshl_add_u64 v[182:183], s[36:37], 2, v[182:183]
	s_lshl_b32 s16, s49, 2
	v_lshl_add_u64 v[182:183], v[182:183], 0, s[16:17]
	s_waitcnt lgkmcnt(0)
	v_add_f32_e32 v176, v176, v177
	global_store_dword v[182:183], v176, off
.LBB0_280:
	s_or_b64 exec, exec, s[38:39]
	s_waitcnt vmcnt(12)
	v_pk_add_f32 v[174:175], v[46:47], v[174:175]
	v_pk_add_f32 v[172:173], v[44:45], v[172:173]
	v_pk_add_f32 v[182:183], v[42:43], v[170:171]
	v_pk_add_f32 v[170:171], v[40:41], v[168:169]
	v_mul_f32_e32 v168, v173, v173
	v_mul_f32_e32 v169, v175, v175
	v_fmac_f32_e32 v168, v172, v172
	v_fmac_f32_e32 v169, v174, v174
	v_add_f32_e32 v168, v168, v169
	v_mul_f32_e32 v169, v171, v171
	v_mul_f32_e32 v186, v183, v183
	v_fmac_f32_e32 v169, v170, v170
	v_fmac_f32_e32 v186, v182, v182
	v_add_f32_e32 v169, v169, v186
	s_waitcnt vmcnt(10)
	v_pk_add_f32 v[166:167], v[38:39], v[166:167]
	v_pk_add_f32 v[164:165], v[36:37], v[164:165]
	v_add_f32_e32 v186, v168, v169
	v_cvt_pk_bf16_f32 v169, v174, v175
	v_pk_add_f32 v[174:175], v[32:33], v[160:161]
	v_mul_f32_e32 v160, v165, v165
	v_mul_f32_e32 v161, v167, v167
	v_cvt_pk_bf16_f32 v168, v172, v173
	v_pk_add_f32 v[172:173], v[34:35], v[162:163]
	v_fmac_f32_e32 v160, v164, v164
	v_fmac_f32_e32 v161, v166, v166
	v_add_f32_e32 v160, v160, v161
	v_mul_f32_e32 v161, v175, v175
	v_mul_f32_e32 v162, v173, v173
	v_fmac_f32_e32 v161, v174, v174
	v_fmac_f32_e32 v162, v172, v172
	v_add_f32_e32 v161, v161, v162
	v_add_f32_e32 v160, v160, v161
	v_add_f32_e32 v163, v186, v160
	v_cvt_pk_bf16_f32 v170, v170, v171
	v_cvt_pk_bf16_f32 v171, v182, v183
	v_mov_b32_e32 v182, v163
	s_nop 1
	v_permlane16_swap_b32_e32 v163, v182
	s_waitcnt lgkmcnt(1)
	v_lshlrev_b64 v[176:177], 11, v[180:181]
	v_lshl_add_u64 v[160:161], s[24:25], 0, v[176:177]
	v_lshl_add_u64 v[176:177], v[206:207], 1, v[160:161]
	v_cvt_pk_bf16_f32 v162, v164, v165
	s_waitcnt lgkmcnt(0)
	v_add_f32_e32 v160, v163, v182
	v_mov_b32_e32 v161, v160
	s_nop 1
	v_permlane32_swap_b32_e32 v160, v161
	v_cvt_pk_bf16_f32 v163, v166, v167
	v_cvt_pk_bf16_f32 v164, v174, v175
	v_cvt_pk_bf16_f32 v165, v172, v173
	global_store_dwordx4 v[176:177], v[168:171], off sc1
	global_store_dwordx4 v[176:177], v[162:165], off offset:256 sc1
	s_and_saveexec_b64 s[38:39], s[30:31]
	s_cbranch_execz .LBB0_282
	v_lshlrev_b64 v[162:163], 6, v[180:181]
	v_lshl_add_u64 v[162:163], s[26:27], 0, v[162:163]
	v_lshl_add_u64 v[162:163], s[36:37], 2, v[162:163]
	s_lshl_b32 s16, s49, 2
	v_lshl_add_u64 v[162:163], v[162:163], 0, s[16:17]
	s_waitcnt lgkmcnt(0)
	v_add_f32_e32 v160, v160, v161
	global_store_dword v[162:163], v160, off
.LBB0_282:
	s_or_b64 exec, exec, s[38:39]
	s_waitcnt vmcnt(10)
	v_pk_add_f32 v[158:159], v[30:31], v[158:159]
	v_pk_add_f32 v[156:157], v[28:29], v[156:157]
	v_pk_add_f32 v[162:163], v[26:27], v[154:155]
	v_pk_add_f32 v[154:155], v[24:25], v[152:153]
	v_mul_f32_e32 v152, v157, v157
	v_mul_f32_e32 v153, v159, v159
	v_fmac_f32_e32 v152, v156, v156
	v_fmac_f32_e32 v153, v158, v158
	v_add_f32_e32 v152, v152, v153
	v_mul_f32_e32 v153, v155, v155
	v_mul_f32_e32 v164, v163, v163
	v_fmac_f32_e32 v153, v154, v154
	v_fmac_f32_e32 v164, v162, v162
	v_add_f32_e32 v153, v153, v164
	s_waitcnt vmcnt(8)
	v_pk_add_f32 v[150:151], v[22:23], v[150:151]
	v_pk_add_f32 v[148:149], v[20:21], v[148:149]
	v_add_f32_e32 v164, v152, v153
	v_cvt_pk_bf16_f32 v153, v158, v159
	v_pk_add_f32 v[158:159], v[16:17], v[144:145]
	v_mul_f32_e32 v144, v149, v149
	v_mul_f32_e32 v145, v151, v151
	v_cvt_pk_bf16_f32 v152, v156, v157
	v_pk_add_f32 v[156:157], v[18:19], v[146:147]
	v_fmac_f32_e32 v144, v148, v148
	v_fmac_f32_e32 v145, v150, v150
	v_add_f32_e32 v144, v144, v145
	v_mul_f32_e32 v145, v159, v159
	v_mul_f32_e32 v146, v157, v157
	v_fmac_f32_e32 v145, v158, v158
	v_fmac_f32_e32 v146, v156, v156
	v_add_f32_e32 v145, v145, v146
	v_add_f32_e32 v144, v144, v145
	v_add_f32_e32 v147, v164, v144
	v_cvt_pk_bf16_f32 v154, v154, v155
	v_cvt_pk_bf16_f32 v155, v162, v163
	v_mov_b32_e32 v162, v147
	s_nop 1
	v_permlane16_swap_b32_e32 v147, v162
	s_waitcnt lgkmcnt(1)
	v_lshlrev_b64 v[160:161], 11, v[178:179]
	v_lshl_add_u64 v[144:145], s[24:25], 0, v[160:161]
	v_lshl_add_u64 v[160:161], v[206:207], 1, v[144:145]
	v_cvt_pk_bf16_f32 v146, v148, v149
	s_waitcnt lgkmcnt(0)
	v_add_f32_e32 v144, v147, v162
	v_mov_b32_e32 v145, v144
	s_nop 1
	v_permlane32_swap_b32_e32 v144, v145
	v_cvt_pk_bf16_f32 v147, v150, v151
	v_cvt_pk_bf16_f32 v148, v158, v159
	v_cvt_pk_bf16_f32 v149, v156, v157
	global_store_dwordx4 v[160:161], v[152:155], off sc1
	global_store_dwordx4 v[160:161], v[146:149], off offset:256 sc1
	s_and_saveexec_b64 s[38:39], s[30:31]
	s_cbranch_execz .LBB0_284
	v_lshlrev_b64 v[146:147], 6, v[178:179]
	v_lshl_add_u64 v[146:147], s[26:27], 0, v[146:147]
	v_lshl_add_u64 v[146:147], s[36:37], 2, v[146:147]
	s_lshl_b32 s16, s49, 2
	v_lshl_add_u64 v[146:147], v[146:147], 0, s[16:17]
	s_waitcnt lgkmcnt(0)
	v_add_f32_e32 v144, v144, v145
	global_store_dword v[146:147], v144, off
.LBB0_284:
	s_or_b64 exec, exec, s[38:39]
	s_waitcnt vmcnt(8)
	v_pk_add_f32 v[140:141], v[12:13], v[140:141]
	s_waitcnt vmcnt(6)
	v_pk_add_f32 v[132:133], v[4:5], v[132:133]
	v_pk_add_f32 v[148:149], v[8:9], v[136:137]
	v_cvt_pk_bf16_f32 v136, v140, v141
	v_pk_add_f32 v[150:151], v[2:3], v[130:131]
	v_mov_b32_e32 v130, v140
	v_mov_b32_e32 v140, v141
	v_mov_b32_e32 v141, v133
	v_pk_add_f32 v[142:143], v[14:15], v[142:143]
	v_pk_add_f32 v[134:135], v[6:7], v[134:135]
	v_mov_b32_e32 v131, v132
	v_pk_mul_f32 v[140:141], v[140:141], v[140:141]
	v_cvt_pk_bf16_f32 v137, v142, v143
	v_pk_fma_f32 v[130:131], v[130:131], v[130:131], v[140:141]
	v_mov_b32_e32 v140, v142
	v_mov_b32_e32 v142, v143
	v_mov_b32_e32 v143, v135
	v_pk_add_f32 v[128:129], v[0:1], v[128:129]
	v_mov_b32_e32 v141, v134
	v_pk_mul_f32 v[142:143], v[142:143], v[142:143]
	v_pk_add_f32 v[146:147], v[10:11], v[138:139]
	v_pk_fma_f32 v[140:141], v[140:141], v[140:141], v[142:143]
	v_mov_b32_e32 v142, v149
	v_mov_b32_e32 v143, v129
	v_pk_add_f32 v[130:131], v[130:131], v[140:141]
	v_mov_b32_e32 v140, v148
	v_mov_b32_e32 v141, v128
	v_pk_mul_f32 v[142:143], v[142:143], v[142:143]
	v_cvt_pk_bf16_f32 v139, v146, v147
	v_pk_fma_f32 v[140:141], v[140:141], v[140:141], v[142:143]
	v_mov_b32_e32 v142, v146
	v_mov_b32_e32 v146, v147
	v_mov_b32_e32 v147, v151
	v_mov_b32_e32 v143, v150
	v_pk_mul_f32 v[146:147], v[146:147], v[146:147]
	s_waitcnt lgkmcnt(0)
	v_lshlrev_b64 v[144:145], 11, v[212:213]
	v_pk_fma_f32 v[142:143], v[142:143], v[142:143], v[146:147]
	v_lshl_add_u64 v[144:145], s[24:25], 0, v[144:145]
	v_pk_add_f32 v[140:141], v[140:141], v[142:143]
	v_cvt_pk_bf16_f32 v138, v148, v149
	v_pk_add_f32 v[130:131], v[130:131], v[140:141]
	v_lshl_add_u64 v[144:145], v[206:207], 1, v[144:145]
	v_add_f32_e32 v140, v130, v131
	v_mov_b32_e32 v141, v140
	s_nop 1
	v_permlane16_swap_b32_e32 v140, v141
	v_cvt_pk_bf16_f32 v130, v132, v133
	v_cvt_pk_bf16_f32 v132, v128, v129
	v_cvt_pk_bf16_f32 v131, v134, v135
	v_cvt_pk_bf16_f32 v133, v150, v151
	s_waitcnt lgkmcnt(0)
	v_add_f32_e32 v128, v140, v141
	ds_bpermute_b32 v129, v184, v128
	s_mov_b64 s[38:39], s[30:31]
	global_store_dwordx4 v[144:145], v[136:139], off sc1
	global_store_dwordx4 v[144:145], v[130:133], off offset:256 sc1
	s_branch .LBB0_301
.LBB0_285:
	v_lshlrev_b64 v[238:239], 1, v[206:207]
	v_lshl_add_u64 v[132:133], s[24:25], 0, v[238:239]
	v_lshlrev_b64 v[240:241], 11, v[216:217]
	s_waitcnt lgkmcnt(0)
	v_lshl_add_u64 v[128:129], v[132:133], 0, v[240:241]
	global_load_dwordx4 v[188:191], v[128:129], off
	global_load_dwordx4 v[184:187], v[128:129], off offset:256
	v_lshlrev_b64 v[236:237], 11, v[214:215]
	v_lshl_add_u64 v[128:129], v[132:133], 0, v[236:237]
	v_lshlrev_b64 v[234:235], 11, v[210:211]
	v_add_u32_e32 v228, 0x80, v216
	global_load_dwordx4 v[180:183], v[128:129], off
	global_load_dwordx4 v[176:179], v[128:129], off offset:256
	v_lshl_add_u64 v[128:129], v[132:133], 0, v[234:235]
	v_lshlrev_b64 v[232:233], 11, v[208:209]
	v_ashrrev_i32_e32 v229, 31, v228
	v_add_u32_e32 v224, 0x90, v216
	global_load_dwordx4 v[172:175], v[128:129], off
	global_load_dwordx4 v[168:171], v[128:129], off offset:256
	v_lshl_add_u64 v[128:129], v[132:133], 0, v[232:233]
	v_lshlrev_b64 v[230:231], 11, v[228:229]
	v_ashrrev_i32_e32 v225, 31, v224
	v_add_u32_e32 v218, 0xa0, v216
	v_add_u32_e32 v212, 0xb0, v216
	global_load_dwordx4 v[164:167], v[128:129], off
	global_load_dwordx4 v[160:163], v[128:129], off offset:256
	v_lshl_add_u64 v[128:129], v[132:133], 0, v[230:231]
	v_lshlrev_b64 v[226:227], 11, v[224:225]
	v_ashrrev_i32_e32 v219, 31, v218
	v_ashrrev_i32_e32 v213, 31, v212
	global_load_dwordx4 v[156:159], v[128:129], off
	global_load_dwordx4 v[152:155], v[128:129], off offset:256
	v_lshl_add_u64 v[128:129], v[132:133], 0, v[226:227]
	v_lshlrev_b64 v[220:221], 11, v[218:219]
	v_lshlrev_b64 v[222:223], 11, v[212:213]
	global_load_dwordx4 v[148:151], v[128:129], off
	global_load_dwordx4 v[144:147], v[128:129], off offset:256
	v_lshl_add_u64 v[128:129], v[132:133], 0, v[220:221]
	v_lshl_add_u64 v[132:133], v[132:133], 0, v[222:223]
	global_load_dwordx4 v[140:143], v[128:129], off
	s_nop 0
	global_load_dwordx4 v[128:131], v[128:129], off offset:256
	s_nop 0
	global_load_dwordx4 v[136:139], v[132:133], off
	s_nop 0
	global_load_dwordx4 v[132:135], v[132:133], off offset:256
	v_and_b32_e32 v249, 64, v247
	v_xor_b32_e32 v248, 16, v247
	v_add_u32_e32 v249, 64, v249
	v_cmp_lt_i32_e32 vcc, v248, v249
	v_xor_b32_e32 v250, 32, v247
	s_lshl_b32 s36, s64, 2
	v_cndmask_b32_e32 v248, v247, v248, vcc
	v_cmp_lt_i32_e32 vcc, v250, v249
	v_lshlrev_b32_e32 v248, 2, v248
	s_ashr_i32 s37, s36, 31
	v_cndmask_b32_e32 v249, v247, v250, vcc
	v_lshlrev_b32_e32 v249, 2, v249
	s_waitcnt vmcnt(0)
	v_lshlrev_b32_e32 v250, 16, v188
	v_and_b32_e32 v251, 0xffff0000, v188
	v_lshlrev_b32_e32 v188, 16, v189
	v_and_b32_e32 v189, 0xffff0000, v189
	v_lshlrev_b32_e32 v252, 16, v190
	v_and_b32_e32 v253, 0xffff0000, v190
	v_lshlrev_b32_e32 v190, 16, v191
	v_and_b32_e32 v191, 0xffff0000, v191
	v_pk_add_f32 v[126:127], v[126:127], v[188:189]
	v_pk_add_f32 v[124:125], v[124:125], v[250:251]
	v_pk_add_f32 v[188:189], v[122:123], v[190:191]
	v_pk_add_f32 v[122:123], v[120:121], v[252:253]
	v_mul_f32_e32 v120, v125, v125
	v_mul_f32_e32 v121, v127, v127
	v_fmac_f32_e32 v120, v124, v124
	v_fmac_f32_e32 v121, v126, v126
	v_add_f32_e32 v120, v120, v121
	v_mul_f32_e32 v121, v123, v123
	v_mul_f32_e32 v190, v189, v189
	v_fmac_f32_e32 v121, v122, v122
	v_fmac_f32_e32 v190, v188, v188
	v_add_f32_e32 v121, v121, v190
	v_add_f32_e32 v190, v120, v121
	v_cvt_pk_bf16_f32 v120, v124, v125
	v_lshl_add_u64 v[124:125], s[24:25], 0, v[240:241]
	v_cvt_pk_bf16_f32 v121, v126, v127
	v_cvt_pk_bf16_f32 v122, v122, v123
	v_cvt_pk_bf16_f32 v123, v188, v189
	v_lshl_add_u64 v[124:125], v[124:125], 0, v[238:239]
	global_store_dwordx4 v[124:125], v[120:123], off sc1
	v_lshlrev_b32_e32 v126, 16, v186
	v_and_b32_e32 v127, 0xffff0000, v186
	v_lshlrev_b32_e32 v120, 16, v184
	v_and_b32_e32 v121, 0xffff0000, v184
	v_lshlrev_b32_e32 v122, 16, v185
	v_and_b32_e32 v123, 0xffff0000, v185
	v_lshlrev_b32_e32 v184, 16, v187
	v_and_b32_e32 v185, 0xffff0000, v187
	v_pk_add_f32 v[118:119], v[118:119], v[122:123]
	v_pk_add_f32 v[116:117], v[116:117], v[120:121]
	v_pk_add_f32 v[120:121], v[114:115], v[184:185]
	v_pk_add_f32 v[114:115], v[112:113], v[126:127]
	v_mul_f32_e32 v112, v117, v117
	v_mul_f32_e32 v113, v119, v119
	v_fmac_f32_e32 v112, v116, v116
	v_fmac_f32_e32 v113, v118, v118
	v_add_f32_e32 v112, v112, v113
	v_mul_f32_e32 v113, v115, v115
	v_mul_f32_e32 v122, v121, v121
	v_fmac_f32_e32 v113, v114, v114
	v_fmac_f32_e32 v122, v120, v120
	v_add_f32_e32 v113, v113, v122
	v_add_f32_e32 v112, v112, v113
	v_add_f32_e32 v122, v190, v112
	v_cvt_pk_bf16_f32 v112, v116, v117
	v_cvt_pk_bf16_f32 v113, v118, v119
	v_cvt_pk_bf16_f32 v114, v114, v115
	v_cvt_pk_bf16_f32 v115, v120, v121
	global_store_dwordx4 v[124:125], v[112:115], off offset:256 sc1
	s_nop 1
	v_mov_b32_e32 v112, v122
	s_nop 1
	v_permlane16_swap_b32_e32 v122, v112
	s_waitcnt lgkmcnt(0)
	v_add_f32_e32 v112, v122, v112
	v_mov_b32_e32 v113, v112
	s_nop 1
	v_permlane32_swap_b32_e32 v112, v113
	s_and_saveexec_b64 s[38:39], s[30:31]
	s_cbranch_execz .LBB0_287
	v_lshlrev_b64 v[114:115], 6, v[216:217]
	v_lshl_add_u64 v[114:115], s[26:27], 0, v[114:115]
	v_lshl_add_u64 v[114:115], s[36:37], 2, v[114:115]
	s_lshl_b32 s16, s49, 2
	v_lshl_add_u64 v[114:115], v[114:115], 0, s[16:17]
	s_waitcnt lgkmcnt(0)
	v_add_f32_e32 v112, v112, v113
	global_store_dword v[114:115], v112, off
.LBB0_287:
	s_or_b64 exec, exec, s[38:39]
	v_lshlrev_b32_e32 v112, 16, v180
	s_waitcnt lgkmcnt(0)
	v_and_b32_e32 v113, 0xffff0000, v180
	v_lshlrev_b32_e32 v114, 16, v181
	v_and_b32_e32 v115, 0xffff0000, v181
	v_lshlrev_b32_e32 v116, 16, v182
	v_and_b32_e32 v117, 0xffff0000, v182
	v_lshlrev_b32_e32 v118, 16, v183
	v_and_b32_e32 v119, 0xffff0000, v183
	v_pk_add_f32 v[110:111], v[110:111], v[114:115]
	v_pk_add_f32 v[108:109], v[108:109], v[112:113]
	v_pk_add_f32 v[112:113], v[106:107], v[118:119]
	v_pk_add_f32 v[106:107], v[104:105], v[116:117]
	v_mul_f32_e32 v104, v109, v109
	v_mul_f32_e32 v105, v111, v111
	v_fmac_f32_e32 v104, v108, v108
	v_fmac_f32_e32 v105, v110, v110
	v_add_f32_e32 v104, v104, v105
	v_mul_f32_e32 v105, v107, v107
	v_mul_f32_e32 v114, v113, v113
	v_fmac_f32_e32 v105, v106, v106
	v_fmac_f32_e32 v114, v112, v112
	v_add_f32_e32 v105, v105, v114
	v_add_f32_e32 v116, v104, v105
	v_cvt_pk_bf16_f32 v104, v108, v109
	v_cvt_pk_bf16_f32 v105, v110, v111
	v_lshlrev_b32_e32 v108, 16, v176
	v_and_b32_e32 v109, 0xffff0000, v176
	v_lshlrev_b32_e32 v110, 16, v177
	v_and_b32_e32 v111, 0xffff0000, v177
	v_cvt_pk_bf16_f32 v106, v106, v107
	v_cvt_pk_bf16_f32 v107, v112, v113
	v_lshlrev_b32_e32 v112, 16, v178
	v_and_b32_e32 v113, 0xffff0000, v178
	v_pk_add_f32 v[102:103], v[102:103], v[110:111]
	v_pk_add_f32 v[100:101], v[100:101], v[108:109]
	v_lshlrev_b32_e32 v114, 16, v179
	v_and_b32_e32 v115, 0xffff0000, v179
	v_pk_add_f32 v[110:111], v[96:97], v[112:113]
	v_mul_f32_e32 v96, v101, v101
	v_mul_f32_e32 v97, v103, v103
	v_pk_add_f32 v[108:109], v[98:99], v[114:115]
	v_fmac_f32_e32 v96, v100, v100
	v_fmac_f32_e32 v97, v102, v102
	v_add_f32_e32 v96, v96, v97
	v_mul_f32_e32 v97, v111, v111
	v_mul_f32_e32 v98, v109, v109
	v_fmac_f32_e32 v97, v110, v110
	v_fmac_f32_e32 v98, v108, v108
	v_add_f32_e32 v97, v97, v98
	v_add_f32_e32 v96, v96, v97
	v_add_f32_e32 v99, v116, v96
	v_mov_b32_e32 v114, v99
	s_nop 1
	v_permlane16_swap_b32_e32 v99, v114
	v_lshl_add_u64 v[96:97], s[24:25], 0, v[236:237]
	v_lshl_add_u64 v[112:113], v[206:207], 1, v[96:97]
	v_cvt_pk_bf16_f32 v98, v100, v101
	v_cvt_pk_bf16_f32 v100, v110, v111
	s_waitcnt lgkmcnt(0)
	v_add_f32_e32 v96, v99, v114
	v_mov_b32_e32 v97, v96
	s_nop 1
	v_permlane32_swap_b32_e32 v96, v97
	v_cvt_pk_bf16_f32 v99, v102, v103
	v_cvt_pk_bf16_f32 v101, v108, v109
	global_store_dwordx4 v[112:113], v[104:107], off sc1
	global_store_dwordx4 v[112:113], v[98:101], off offset:256 sc1
	s_and_saveexec_b64 s[38:39], s[30:31]
	s_cbranch_execz .LBB0_289
	v_lshlrev_b64 v[98:99], 6, v[214:215]
	v_lshl_add_u64 v[98:99], s[26:27], 0, v[98:99]
	v_lshl_add_u64 v[98:99], s[36:37], 2, v[98:99]
	s_lshl_b32 s16, s49, 2
	v_lshl_add_u64 v[98:99], v[98:99], 0, s[16:17]
	s_waitcnt lgkmcnt(0)
	v_add_f32_e32 v96, v96, v97
	global_store_dword v[98:99], v96, off
.LBB0_289:
	s_or_b64 exec, exec, s[38:39]
	v_lshlrev_b32_e32 v96, 16, v172
	s_waitcnt lgkmcnt(0)
	v_and_b32_e32 v97, 0xffff0000, v172
	v_lshlrev_b32_e32 v98, 16, v173
	v_and_b32_e32 v99, 0xffff0000, v173
	v_lshlrev_b32_e32 v100, 16, v174
	v_and_b32_e32 v101, 0xffff0000, v174
	v_lshlrev_b32_e32 v102, 16, v175
	v_and_b32_e32 v103, 0xffff0000, v175
	v_pk_add_f32 v[94:95], v[94:95], v[98:99]
	v_pk_add_f32 v[92:93], v[92:93], v[96:97]
	v_pk_add_f32 v[96:97], v[90:91], v[102:103]
	v_pk_add_f32 v[90:91], v[88:89], v[100:101]
	v_mul_f32_e32 v88, v93, v93
	v_mul_f32_e32 v89, v95, v95
	v_fmac_f32_e32 v88, v92, v92
	v_fmac_f32_e32 v89, v94, v94
	v_add_f32_e32 v88, v88, v89
	v_mul_f32_e32 v89, v91, v91
	v_mul_f32_e32 v98, v97, v97
	v_fmac_f32_e32 v89, v90, v90
	v_fmac_f32_e32 v98, v96, v96
	v_add_f32_e32 v89, v89, v98
	v_add_f32_e32 v100, v88, v89
	v_cvt_pk_bf16_f32 v88, v92, v93
	v_cvt_pk_bf16_f32 v89, v94, v95
	v_lshlrev_b32_e32 v92, 16, v168
	v_and_b32_e32 v93, 0xffff0000, v168
	v_lshlrev_b32_e32 v94, 16, v169
	v_and_b32_e32 v95, 0xffff0000, v169
	v_cvt_pk_bf16_f32 v90, v90, v91
	v_cvt_pk_bf16_f32 v91, v96, v97
	v_lshlrev_b32_e32 v96, 16, v170
	v_and_b32_e32 v97, 0xffff0000, v170
	v_pk_add_f32 v[86:87], v[86:87], v[94:95]
	v_pk_add_f32 v[84:85], v[84:85], v[92:93]
	v_lshlrev_b32_e32 v98, 16, v171
	v_and_b32_e32 v99, 0xffff0000, v171
	v_pk_add_f32 v[94:95], v[80:81], v[96:97]
	v_mul_f32_e32 v80, v85, v85
	v_mul_f32_e32 v81, v87, v87
	v_pk_add_f32 v[92:93], v[82:83], v[98:99]
	v_fmac_f32_e32 v80, v84, v84
	v_fmac_f32_e32 v81, v86, v86
	v_add_f32_e32 v80, v80, v81
	v_mul_f32_e32 v81, v95, v95
	v_mul_f32_e32 v82, v93, v93
	v_fmac_f32_e32 v81, v94, v94
	v_fmac_f32_e32 v82, v92, v92
	v_add_f32_e32 v81, v81, v82
	v_add_f32_e32 v80, v80, v81
	v_add_f32_e32 v83, v100, v80
	v_mov_b32_e32 v98, v83
	s_nop 1
	v_permlane16_swap_b32_e32 v83, v98
	v_lshl_add_u64 v[80:81], s[24:25], 0, v[234:235]
	v_lshl_add_u64 v[96:97], v[206:207], 1, v[80:81]
	v_cvt_pk_bf16_f32 v82, v84, v85
	v_cvt_pk_bf16_f32 v84, v94, v95
	s_waitcnt lgkmcnt(0)
	v_add_f32_e32 v80, v83, v98
	v_mov_b32_e32 v81, v80
	s_nop 1
	v_permlane32_swap_b32_e32 v80, v81
	v_cvt_pk_bf16_f32 v83, v86, v87
	v_cvt_pk_bf16_f32 v85, v92, v93
	global_store_dwordx4 v[96:97], v[88:91], off sc1
	global_store_dwordx4 v[96:97], v[82:85], off offset:256 sc1
	s_and_saveexec_b64 s[38:39], s[30:31]
	s_cbranch_execz .LBB0_291
	v_lshlrev_b64 v[82:83], 6, v[210:211]
	v_lshl_add_u64 v[82:83], s[26:27], 0, v[82:83]
	v_lshl_add_u64 v[82:83], s[36:37], 2, v[82:83]
	s_lshl_b32 s16, s49, 2
	v_lshl_add_u64 v[82:83], v[82:83], 0, s[16:17]
	s_waitcnt lgkmcnt(0)
	v_add_f32_e32 v80, v80, v81
	global_store_dword v[82:83], v80, off
.LBB0_291:
	s_or_b64 exec, exec, s[38:39]
	v_lshlrev_b32_e32 v80, 16, v164
	s_waitcnt lgkmcnt(0)
	v_and_b32_e32 v81, 0xffff0000, v164
	v_lshlrev_b32_e32 v82, 16, v165
	v_and_b32_e32 v83, 0xffff0000, v165
	v_lshlrev_b32_e32 v84, 16, v166
	v_and_b32_e32 v85, 0xffff0000, v166
	v_lshlrev_b32_e32 v86, 16, v167
	v_and_b32_e32 v87, 0xffff0000, v167
	v_pk_add_f32 v[78:79], v[78:79], v[82:83]
	v_pk_add_f32 v[76:77], v[76:77], v[80:81]
	v_pk_add_f32 v[80:81], v[74:75], v[86:87]
	v_pk_add_f32 v[74:75], v[72:73], v[84:85]
	v_mul_f32_e32 v72, v77, v77
	v_mul_f32_e32 v73, v79, v79
	v_fmac_f32_e32 v72, v76, v76
	v_fmac_f32_e32 v73, v78, v78
	v_add_f32_e32 v72, v72, v73
	v_mul_f32_e32 v73, v75, v75
	v_mul_f32_e32 v82, v81, v81
	v_fmac_f32_e32 v73, v74, v74
	v_fmac_f32_e32 v82, v80, v80
	v_add_f32_e32 v73, v73, v82
	v_add_f32_e32 v84, v72, v73
	v_cvt_pk_bf16_f32 v72, v76, v77
	v_cvt_pk_bf16_f32 v73, v78, v79
	v_lshlrev_b32_e32 v76, 16, v160
	v_and_b32_e32 v77, 0xffff0000, v160
	v_lshlrev_b32_e32 v78, 16, v161
	v_and_b32_e32 v79, 0xffff0000, v161
	v_cvt_pk_bf16_f32 v74, v74, v75
	v_cvt_pk_bf16_f32 v75, v80, v81
	v_lshlrev_b32_e32 v80, 16, v162
	v_and_b32_e32 v81, 0xffff0000, v162
	v_pk_add_f32 v[70:71], v[70:71], v[78:79]
	v_pk_add_f32 v[68:69], v[68:69], v[76:77]
	v_lshlrev_b32_e32 v82, 16, v163
	v_and_b32_e32 v83, 0xffff0000, v163
	v_pk_add_f32 v[78:79], v[64:65], v[80:81]
	v_mul_f32_e32 v64, v69, v69
	v_mul_f32_e32 v65, v71, v71
	v_pk_add_f32 v[76:77], v[66:67], v[82:83]
	v_fmac_f32_e32 v64, v68, v68
	v_fmac_f32_e32 v65, v70, v70
	v_add_f32_e32 v64, v64, v65
	v_mul_f32_e32 v65, v79, v79
	v_mul_f32_e32 v66, v77, v77
	v_fmac_f32_e32 v65, v78, v78
	v_fmac_f32_e32 v66, v76, v76
	v_add_f32_e32 v65, v65, v66
	v_add_f32_e32 v64, v64, v65
	v_add_f32_e32 v67, v84, v64
	v_mov_b32_e32 v82, v67
	s_nop 1
	v_permlane16_swap_b32_e32 v67, v82
	v_lshl_add_u64 v[64:65], s[24:25], 0, v[232:233]
	v_lshl_add_u64 v[80:81], v[206:207], 1, v[64:65]
	v_cvt_pk_bf16_f32 v66, v68, v69
	v_cvt_pk_bf16_f32 v68, v78, v79
	s_waitcnt lgkmcnt(0)
	v_add_f32_e32 v64, v67, v82
	v_mov_b32_e32 v65, v64
	s_nop 1
	v_permlane32_swap_b32_e32 v64, v65
	v_cvt_pk_bf16_f32 v67, v70, v71
	v_cvt_pk_bf16_f32 v69, v76, v77
	global_store_dwordx4 v[80:81], v[72:75], off sc1
	global_store_dwordx4 v[80:81], v[66:69], off offset:256 sc1
	s_and_saveexec_b64 s[38:39], s[30:31]
	s_cbranch_execz .LBB0_293
	v_lshlrev_b64 v[66:67], 6, v[208:209]
	v_lshl_add_u64 v[66:67], s[26:27], 0, v[66:67]
	v_lshl_add_u64 v[66:67], s[36:37], 2, v[66:67]
	s_lshl_b32 s16, s49, 2
	v_lshl_add_u64 v[66:67], v[66:67], 0, s[16:17]
	s_waitcnt lgkmcnt(0)
	v_add_f32_e32 v64, v64, v65
	global_store_dword v[66:67], v64, off
.LBB0_293:
	s_or_b64 exec, exec, s[38:39]
	v_lshlrev_b32_e32 v64, 16, v156
	s_waitcnt lgkmcnt(0)
	v_and_b32_e32 v65, 0xffff0000, v156
	v_lshlrev_b32_e32 v66, 16, v157
	v_and_b32_e32 v67, 0xffff0000, v157
	v_lshlrev_b32_e32 v68, 16, v158
	v_and_b32_e32 v69, 0xffff0000, v158
	v_lshlrev_b32_e32 v70, 16, v159
	v_and_b32_e32 v71, 0xffff0000, v159
	v_pk_add_f32 v[62:63], v[62:63], v[66:67]
	v_pk_add_f32 v[60:61], v[60:61], v[64:65]
	v_pk_add_f32 v[64:65], v[58:59], v[70:71]
	v_pk_add_f32 v[58:59], v[56:57], v[68:69]
	v_mul_f32_e32 v56, v61, v61
	v_mul_f32_e32 v57, v63, v63
	v_fmac_f32_e32 v56, v60, v60
	v_fmac_f32_e32 v57, v62, v62
	v_add_f32_e32 v56, v56, v57
	v_mul_f32_e32 v57, v59, v59
	v_mul_f32_e32 v66, v65, v65
	v_fmac_f32_e32 v57, v58, v58
	v_fmac_f32_e32 v66, v64, v64
	v_add_f32_e32 v57, v57, v66
	v_add_f32_e32 v68, v56, v57
	v_cvt_pk_bf16_f32 v56, v60, v61
	v_cvt_pk_bf16_f32 v57, v62, v63
	v_lshlrev_b32_e32 v60, 16, v152
	v_and_b32_e32 v61, 0xffff0000, v152
	v_lshlrev_b32_e32 v62, 16, v153
	v_and_b32_e32 v63, 0xffff0000, v153
	v_cvt_pk_bf16_f32 v58, v58, v59
	v_cvt_pk_bf16_f32 v59, v64, v65
	v_lshlrev_b32_e32 v64, 16, v154
	v_and_b32_e32 v65, 0xffff0000, v154
	v_pk_add_f32 v[54:55], v[54:55], v[62:63]
	v_pk_add_f32 v[52:53], v[52:53], v[60:61]
	v_lshlrev_b32_e32 v66, 16, v155
	v_and_b32_e32 v67, 0xffff0000, v155
	v_pk_add_f32 v[62:63], v[48:49], v[64:65]
	v_mul_f32_e32 v48, v53, v53
	v_mul_f32_e32 v49, v55, v55
	v_pk_add_f32 v[60:61], v[50:51], v[66:67]
	v_fmac_f32_e32 v48, v52, v52
	v_fmac_f32_e32 v49, v54, v54
	v_add_f32_e32 v48, v48, v49
	v_mul_f32_e32 v49, v63, v63
	v_mul_f32_e32 v50, v61, v61
	v_fmac_f32_e32 v49, v62, v62
	v_fmac_f32_e32 v50, v60, v60
	v_add_f32_e32 v49, v49, v50
	v_add_f32_e32 v48, v48, v49
	v_add_f32_e32 v51, v68, v48
	v_mov_b32_e32 v66, v51
	s_nop 1
	v_permlane16_swap_b32_e32 v51, v66
	v_lshl_add_u64 v[48:49], s[24:25], 0, v[230:231]
	v_lshl_add_u64 v[64:65], v[206:207], 1, v[48:49]
	v_cvt_pk_bf16_f32 v50, v52, v53
	v_cvt_pk_bf16_f32 v52, v62, v63
	s_waitcnt lgkmcnt(0)
	v_add_f32_e32 v48, v51, v66
	v_mov_b32_e32 v49, v48
	s_nop 1
	v_permlane32_swap_b32_e32 v48, v49
	v_cvt_pk_bf16_f32 v51, v54, v55
	v_cvt_pk_bf16_f32 v53, v60, v61
	global_store_dwordx4 v[64:65], v[56:59], off sc1
	global_store_dwordx4 v[64:65], v[50:53], off offset:256 sc1
	s_and_saveexec_b64 s[38:39], s[30:31]
	s_cbranch_execz .LBB0_295
	v_lshlrev_b64 v[50:51], 6, v[228:229]
	v_lshl_add_u64 v[50:51], s[26:27], 0, v[50:51]
	v_lshl_add_u64 v[50:51], s[36:37], 2, v[50:51]
	s_lshl_b32 s16, s49, 2
	v_lshl_add_u64 v[50:51], v[50:51], 0, s[16:17]
	s_waitcnt lgkmcnt(0)
	v_add_f32_e32 v48, v48, v49
	global_store_dword v[50:51], v48, off
.LBB0_295:
	s_or_b64 exec, exec, s[38:39]
	v_lshlrev_b32_e32 v48, 16, v148
	s_waitcnt lgkmcnt(0)
	v_and_b32_e32 v49, 0xffff0000, v148
	v_lshlrev_b32_e32 v50, 16, v149
	v_and_b32_e32 v51, 0xffff0000, v149
	v_lshlrev_b32_e32 v52, 16, v150
	v_and_b32_e32 v53, 0xffff0000, v150
	v_lshlrev_b32_e32 v54, 16, v151
	v_and_b32_e32 v55, 0xffff0000, v151
	v_pk_add_f32 v[46:47], v[46:47], v[50:51]
	v_pk_add_f32 v[44:45], v[44:45], v[48:49]
	v_pk_add_f32 v[48:49], v[42:43], v[54:55]
	v_pk_add_f32 v[42:43], v[40:41], v[52:53]
	v_mul_f32_e32 v40, v45, v45
	v_mul_f32_e32 v41, v47, v47
	v_fmac_f32_e32 v40, v44, v44
	v_fmac_f32_e32 v41, v46, v46
	v_add_f32_e32 v40, v40, v41
	v_mul_f32_e32 v41, v43, v43
	v_mul_f32_e32 v50, v49, v49
	v_fmac_f32_e32 v41, v42, v42
	v_fmac_f32_e32 v50, v48, v48
	v_add_f32_e32 v41, v41, v50
	v_add_f32_e32 v52, v40, v41
	v_cvt_pk_bf16_f32 v40, v44, v45
	v_cvt_pk_bf16_f32 v41, v46, v47
	v_lshlrev_b32_e32 v44, 16, v144
	v_and_b32_e32 v45, 0xffff0000, v144
	v_lshlrev_b32_e32 v46, 16, v145
	v_and_b32_e32 v47, 0xffff0000, v145
	v_cvt_pk_bf16_f32 v42, v42, v43
	v_cvt_pk_bf16_f32 v43, v48, v49
	v_lshlrev_b32_e32 v48, 16, v146
	v_and_b32_e32 v49, 0xffff0000, v146
	v_pk_add_f32 v[38:39], v[38:39], v[46:47]
	v_pk_add_f32 v[36:37], v[36:37], v[44:45]
	v_lshlrev_b32_e32 v50, 16, v147
	v_and_b32_e32 v51, 0xffff0000, v147
	v_pk_add_f32 v[46:47], v[32:33], v[48:49]
	v_mul_f32_e32 v32, v37, v37
	v_mul_f32_e32 v33, v39, v39
	v_pk_add_f32 v[44:45], v[34:35], v[50:51]
	v_fmac_f32_e32 v32, v36, v36
	v_fmac_f32_e32 v33, v38, v38
	v_add_f32_e32 v32, v32, v33
	v_mul_f32_e32 v33, v47, v47
	v_mul_f32_e32 v34, v45, v45
	v_fmac_f32_e32 v33, v46, v46
	v_fmac_f32_e32 v34, v44, v44
	v_add_f32_e32 v33, v33, v34
	v_add_f32_e32 v32, v32, v33
	v_add_f32_e32 v35, v52, v32
	v_mov_b32_e32 v50, v35
	s_nop 1
	v_permlane16_swap_b32_e32 v35, v50
	v_lshl_add_u64 v[32:33], s[24:25], 0, v[226:227]
	v_lshl_add_u64 v[48:49], v[206:207], 1, v[32:33]
	v_cvt_pk_bf16_f32 v34, v36, v37
	v_cvt_pk_bf16_f32 v36, v46, v47
	s_waitcnt lgkmcnt(0)
	v_add_f32_e32 v32, v35, v50
	v_mov_b32_e32 v33, v32
	s_nop 1
	v_permlane32_swap_b32_e32 v32, v33
	v_cvt_pk_bf16_f32 v35, v38, v39
	v_cvt_pk_bf16_f32 v37, v44, v45
	global_store_dwordx4 v[48:49], v[40:43], off sc1
	global_store_dwordx4 v[48:49], v[34:37], off offset:256 sc1
	s_and_saveexec_b64 s[38:39], s[30:31]
	s_cbranch_execz .LBB0_297
	v_lshlrev_b64 v[34:35], 6, v[224:225]
	v_lshl_add_u64 v[34:35], s[26:27], 0, v[34:35]
	v_lshl_add_u64 v[34:35], s[36:37], 2, v[34:35]
	s_lshl_b32 s16, s49, 2
	v_lshl_add_u64 v[34:35], v[34:35], 0, s[16:17]
	s_waitcnt lgkmcnt(0)
	v_add_f32_e32 v32, v32, v33
	global_store_dword v[34:35], v32, off
.LBB0_297:
	s_or_b64 exec, exec, s[38:39]
	v_lshlrev_b32_e32 v32, 16, v140
	s_waitcnt lgkmcnt(0)
	v_and_b32_e32 v33, 0xffff0000, v140
	v_lshlrev_b32_e32 v34, 16, v141
	v_and_b32_e32 v35, 0xffff0000, v141
	v_lshlrev_b32_e32 v36, 16, v142
	v_and_b32_e32 v37, 0xffff0000, v142
	v_lshlrev_b32_e32 v38, 16, v143
	v_and_b32_e32 v39, 0xffff0000, v143
	v_pk_add_f32 v[30:31], v[30:31], v[34:35]
	v_pk_add_f32 v[28:29], v[28:29], v[32:33]
	v_pk_add_f32 v[32:33], v[26:27], v[38:39]
	v_pk_add_f32 v[26:27], v[24:25], v[36:37]
	v_mul_f32_e32 v24, v29, v29
	v_mul_f32_e32 v25, v31, v31
	v_fmac_f32_e32 v24, v28, v28
	v_fmac_f32_e32 v25, v30, v30
	v_add_f32_e32 v24, v24, v25
	v_mul_f32_e32 v25, v27, v27
	v_mul_f32_e32 v34, v33, v33
	v_fmac_f32_e32 v25, v26, v26
	v_fmac_f32_e32 v34, v32, v32
	v_add_f32_e32 v25, v25, v34
	v_add_f32_e32 v36, v24, v25
	v_cvt_pk_bf16_f32 v24, v28, v29
	v_cvt_pk_bf16_f32 v25, v30, v31
	v_lshlrev_b32_e32 v28, 16, v128
	v_and_b32_e32 v29, 0xffff0000, v128
	v_lshlrev_b32_e32 v30, 16, v129
	v_and_b32_e32 v31, 0xffff0000, v129
	v_cvt_pk_bf16_f32 v26, v26, v27
	v_cvt_pk_bf16_f32 v27, v32, v33
	v_lshlrev_b32_e32 v32, 16, v130
	v_and_b32_e32 v33, 0xffff0000, v130
	v_pk_add_f32 v[22:23], v[22:23], v[30:31]
	v_pk_add_f32 v[20:21], v[20:21], v[28:29]
	v_lshlrev_b32_e32 v34, 16, v131
	v_and_b32_e32 v35, 0xffff0000, v131
	v_pk_add_f32 v[30:31], v[16:17], v[32:33]
	v_mul_f32_e32 v16, v21, v21
	v_mul_f32_e32 v17, v23, v23
	v_pk_add_f32 v[28:29], v[18:19], v[34:35]
	v_fmac_f32_e32 v16, v20, v20
	v_fmac_f32_e32 v17, v22, v22
	v_add_f32_e32 v16, v16, v17
	v_mul_f32_e32 v17, v31, v31
	v_mul_f32_e32 v18, v29, v29
	v_fmac_f32_e32 v17, v30, v30
	v_fmac_f32_e32 v18, v28, v28
	v_add_f32_e32 v17, v17, v18
	v_add_f32_e32 v16, v16, v17
	v_add_f32_e32 v19, v36, v16
	v_mov_b32_e32 v34, v19
	s_nop 1
	v_permlane16_swap_b32_e32 v19, v34
	v_lshl_add_u64 v[16:17], s[24:25], 0, v[220:221]
	v_lshl_add_u64 v[32:33], v[206:207], 1, v[16:17]
	v_cvt_pk_bf16_f32 v18, v20, v21
	v_cvt_pk_bf16_f32 v20, v30, v31
	s_waitcnt lgkmcnt(0)
	v_add_f32_e32 v16, v19, v34
	v_mov_b32_e32 v17, v16
	s_nop 1
	v_permlane32_swap_b32_e32 v16, v17
	v_cvt_pk_bf16_f32 v19, v22, v23
	v_cvt_pk_bf16_f32 v21, v28, v29
	global_store_dwordx4 v[32:33], v[24:27], off sc1
	global_store_dwordx4 v[32:33], v[18:21], off offset:256 sc1
	s_and_saveexec_b64 s[38:39], s[30:31]
	s_cbranch_execz .LBB0_299
	v_lshlrev_b64 v[18:19], 6, v[218:219]
	v_lshl_add_u64 v[18:19], s[26:27], 0, v[18:19]
	v_lshl_add_u64 v[18:19], s[36:37], 2, v[18:19]
	s_lshl_b32 s16, s49, 2
	v_lshl_add_u64 v[18:19], v[18:19], 0, s[16:17]
	s_waitcnt lgkmcnt(0)
	v_add_f32_e32 v16, v16, v17
	global_store_dword v[18:19], v16, off
.LBB0_299:
	s_or_b64 exec, exec, s[38:39]
	v_lshlrev_b32_e32 v16, 16, v136
	s_waitcnt lgkmcnt(0)
	v_and_b32_e32 v17, 0xffff0000, v136
	v_lshlrev_b32_e32 v22, 16, v139
	v_and_b32_e32 v23, 0xffff0000, v139
	v_pk_add_f32 v[12:13], v[12:13], v[16:17]
	v_pk_add_f32 v[16:17], v[10:11], v[22:23]
	v_lshlrev_b32_e32 v22, 16, v132
	v_and_b32_e32 v23, 0xffff0000, v132
	v_lshlrev_b32_e32 v18, 16, v137
	v_and_b32_e32 v19, 0xffff0000, v137
	v_lshlrev_b32_e32 v20, 16, v138
	v_and_b32_e32 v21, 0xffff0000, v138
	v_lshlrev_b32_e32 v26, 16, v134
	v_and_b32_e32 v27, 0xffff0000, v134
	v_lshlrev_b32_e32 v28, 16, v135
	v_and_b32_e32 v29, 0xffff0000, v135
	v_pk_add_f32 v[4:5], v[4:5], v[22:23]
	v_pk_add_f32 v[14:15], v[14:15], v[18:19]
	v_pk_add_f32 v[18:19], v[8:9], v[20:21]
	v_cvt_pk_bf16_f32 v8, v12, v13
	v_lshlrev_b32_e32 v24, 16, v133
	v_and_b32_e32 v25, 0xffff0000, v133
	v_pk_add_f32 v[22:23], v[2:3], v[28:29]
	v_pk_add_f32 v[2:3], v[0:1], v[26:27]
	v_mov_b32_e32 v0, v12
	v_mov_b32_e32 v12, v13
	v_mov_b32_e32 v13, v5
	v_pk_add_f32 v[6:7], v[6:7], v[24:25]
	v_mov_b32_e32 v1, v4
	v_pk_mul_f32 v[12:13], v[12:13], v[12:13]
	v_cvt_pk_bf16_f32 v9, v14, v15
	v_pk_fma_f32 v[0:1], v[0:1], v[0:1], v[12:13]
	v_mov_b32_e32 v12, v14
	v_mov_b32_e32 v14, v15
	v_mov_b32_e32 v15, v7
	v_mov_b32_e32 v13, v6
	v_pk_mul_f32 v[14:15], v[14:15], v[14:15]
	v_cvt_pk_bf16_f32 v11, v16, v17
	v_pk_fma_f32 v[12:13], v[12:13], v[12:13], v[14:15]
	v_mov_b32_e32 v14, v19
	v_mov_b32_e32 v15, v3
	v_pk_add_f32 v[0:1], v[0:1], v[12:13]
	v_mov_b32_e32 v12, v18
	v_mov_b32_e32 v13, v2
	v_pk_mul_f32 v[14:15], v[14:15], v[14:15]
	v_lshl_add_u64 v[20:21], s[24:25], 0, v[222:223]
	v_pk_fma_f32 v[12:13], v[12:13], v[12:13], v[14:15]
	v_mov_b32_e32 v14, v16
	v_mov_b32_e32 v16, v17
	v_mov_b32_e32 v17, v23
	v_mov_b32_e32 v15, v22
	v_pk_mul_f32 v[16:17], v[16:17], v[16:17]
	v_cvt_pk_bf16_f32 v10, v18, v19
	v_pk_fma_f32 v[14:15], v[14:15], v[14:15], v[16:17]
	v_cvt_pk_bf16_f32 v2, v2, v3
	v_pk_add_f32 v[12:13], v[12:13], v[14:15]
	v_cvt_pk_bf16_f32 v3, v22, v23
	v_pk_add_f32 v[0:1], v[0:1], v[12:13]
	v_lshl_add_u64 v[12:13], v[206:207], 1, v[20:21]
	v_add_f32_e32 v14, v0, v1
	v_mov_b32_e32 v15, v14
	s_nop 1
	v_permlane16_swap_b32_e32 v14, v15
	v_cvt_pk_bf16_f32 v0, v4, v5
	v_cvt_pk_bf16_f32 v1, v6, v7
	s_mov_b64 s[38:39], s[30:31]
	global_store_dwordx4 v[12:13], v[8:11], off sc1
	s_waitcnt lgkmcnt(0)
	v_add_f32_e32 v128, v14, v15
	s_nop 1
	v_mov_b32_e32 v129, v128
	s_nop 1
	v_permlane32_swap_b32_e32 v128, v129
	global_store_dwordx4 v[12:13], v[0:3], off offset:256 sc1
	s_and_saveexec_b64 s[40:41], s[38:39]
	s_cbranch_execz .LBB0_256
	s_branch .LBB0_302

.LBB0_818:
	ds_read_b128 v[120:123], v244
	ds_read_b128 v[124:127], v244 offset:1024
	ds_read_b128 v[132:135], v244 offset:2048
	ds_read_b128 v[140:143], v244 offset:3072
	s_add_u32 s34, s10, 0xffea0080
	s_addc_u32 s35, s11, -1
	s_cmp_eq_u32 s65, 28
	s_cselect_b32 s37, s29, s35
	s_cselect_b32 s36, s28, s34
	s_cselect_b32 s35, s27, s64
	s_cselect_b32 s34, s58, s59
	v_lshl_add_u64 v[176:177], s[10:11], 0, v[202:203]
	s_add_i32 m0, s43, 0xc000
	ds_read_b128 v[144:147], v245
	ds_read_b128 v[148:151], v245 offset:1024
	ds_read_b128 v[152:155], v245 offset:2048
	ds_read_b128 v[156:159], v245 offset:3072
	ds_read_b128 v[160:163], v245 offset:4096
	ds_read_b128 v[164:167], v245 offset:5120
	ds_read_b128 v[168:171], v245 offset:6144
	ds_read_b128 v[172:175], v245 offset:7168
	global_load_lds_dwordx4 v[176:177], off
	v_lshl_add_u64 v[176:177], s[10:11], 0, v[204:205]
	s_add_i32 m0, s43, 0xe000
	s_nop 0
	global_load_lds_dwordx4 v[176:177], off
	s_waitcnt lgkmcnt(8)
	s_barrier
	s_waitcnt lgkmcnt(0)
	s_setprio 1
	s_waitcnt lgkmcnt(0)
	v_mfma_f32_16x16x32_bf16 v[136:139], v[120:123], v[144:147], v[136:139]
	v_mfma_f32_16x16x32_bf16 v[128:131], v[132:135], v[144:147], v[128:131]
	v_mfma_f32_16x16x32_bf16 v[108:111], v[120:123], v[152:155], v[108:111]
	v_mfma_f32_16x16x32_bf16 v[104:107], v[132:135], v[152:155], v[104:107]
	v_mfma_f32_16x16x32_bf16 v[92:95], v[120:123], v[160:163], v[92:95]
	v_mfma_f32_16x16x32_bf16 v[88:91], v[132:135], v[160:163], v[88:91]
	v_mfma_f32_16x16x32_bf16 v[76:79], v[120:123], v[168:171], v[76:79]
	v_mfma_f32_16x16x32_bf16 v[72:75], v[132:135], v[168:171], v[72:75]
	v_mfma_f32_16x16x32_bf16 v[136:139], v[124:127], v[148:151], v[136:139]
	v_mfma_f32_16x16x32_bf16 v[128:131], v[140:143], v[148:151], v[128:131]
	v_mfma_f32_16x16x32_bf16 v[108:111], v[124:127], v[156:159], v[108:111]
	v_mfma_f32_16x16x32_bf16 v[104:107], v[140:143], v[156:159], v[104:107]
	v_mfma_f32_16x16x32_bf16 v[92:95], v[124:127], v[164:167], v[92:95]
	v_mfma_f32_16x16x32_bf16 v[88:91], v[140:143], v[164:167], v[88:91]
	v_mfma_f32_16x16x32_bf16 v[76:79], v[124:127], v[172:175], v[76:79]
	v_mfma_f32_16x16x32_bf16 v[72:75], v[140:143], v[172:175], v[72:75]
	s_setprio 0
	s_barrier
	s_add_i32 s66, s53, s42
	v_lshl_add_u64 v[206:207], s[34:35], 0, v[196:197]
	s_mov_b32 m0, s66
	ds_read_b128 v[176:179], v246
	ds_read_b128 v[180:183], v246 offset:1024
	ds_read_b128 v[184:187], v246 offset:2048
	ds_read_b128 v[188:191], v246 offset:3072
	global_load_lds_dwordx4 v[206:207], off
	v_lshl_add_u64 v[208:209], s[34:35], 0, v[200:201]
	s_add_i32 m0, s66, 0x2000
	s_nop 0
	global_load_lds_dwordx4 v[208:209], off
	s_barrier
	s_waitcnt lgkmcnt(0)
	s_setprio 1
	s_waitcnt lgkmcnt(0)
	v_mfma_f32_16x16x32_bf16 v[116:119], v[176:179], v[144:147], v[116:119]
	v_mfma_f32_16x16x32_bf16 v[112:115], v[184:187], v[144:147], v[112:115]
	v_mfma_f32_16x16x32_bf16 v[100:103], v[176:179], v[152:155], v[100:103]
	v_mfma_f32_16x16x32_bf16 v[96:99], v[184:187], v[152:155], v[96:99]
	v_mfma_f32_16x16x32_bf16 v[84:87], v[176:179], v[160:163], v[84:87]
	v_mfma_f32_16x16x32_bf16 v[80:83], v[184:187], v[160:163], v[80:83]
	v_mfma_f32_16x16x32_bf16 v[68:71], v[176:179], v[168:171], v[68:71]
	v_mfma_f32_16x16x32_bf16 v[64:67], v[184:187], v[168:171], v[64:67]
	v_mfma_f32_16x16x32_bf16 v[116:119], v[180:183], v[148:151], v[116:119]
	v_mfma_f32_16x16x32_bf16 v[112:115], v[188:191], v[148:151], v[112:115]
	v_mfma_f32_16x16x32_bf16 v[100:103], v[180:183], v[156:159], v[100:103]
	v_mfma_f32_16x16x32_bf16 v[96:99], v[188:191], v[156:159], v[96:99]
	v_mfma_f32_16x16x32_bf16 v[84:87], v[180:183], v[164:167], v[84:87]
	v_mfma_f32_16x16x32_bf16 v[80:83], v[188:191], v[164:167], v[80:83]
	v_mfma_f32_16x16x32_bf16 v[68:71], v[180:183], v[172:175], v[68:71]
	v_mfma_f32_16x16x32_bf16 v[64:67], v[188:191], v[172:175], v[64:67]
	s_setprio 0
	s_mov_b32 m0, s43
	v_lshl_add_u64 v[210:211], s[36:37], 0, v[194:195]
	s_barrier
	ds_read_b128 v[144:147], v245 offset:16384
	ds_read_b128 v[148:151], v245 offset:17408
	ds_read_b128 v[152:155], v245 offset:18432
	ds_read_b128 v[156:159], v245 offset:19456
	ds_read_b128 v[160:163], v245 offset:20480
	ds_read_b128 v[164:167], v245 offset:21504
	ds_read_b128 v[168:171], v245 offset:22528
	ds_read_b128 v[172:175], v245 offset:23552
	global_load_lds_dwordx4 v[210:211], off
	v_lshl_add_u64 v[212:213], s[36:37], 0, v[198:199]
	s_mov_b32 m0, s44
	s_nop 0
	global_load_lds_dwordx4 v[212:213], off
	s_barrier
	s_waitcnt lgkmcnt(0)
	s_setprio 1
	s_waitcnt lgkmcnt(0)
	v_mfma_f32_16x16x32_bf16 v[60:63], v[120:123], v[144:147], v[60:63]
	v_mfma_f32_16x16x32_bf16 v[56:59], v[132:135], v[144:147], v[56:59]
	v_mfma_f32_16x16x32_bf16 v[44:47], v[120:123], v[152:155], v[44:47]
	v_mfma_f32_16x16x32_bf16 v[40:43], v[132:135], v[152:155], v[40:43]
	v_mfma_f32_16x16x32_bf16 v[28:31], v[120:123], v[160:163], v[28:31]
	v_mfma_f32_16x16x32_bf16 v[24:27], v[132:135], v[160:163], v[24:27]
	v_mfma_f32_16x16x32_bf16 v[12:15], v[120:123], v[168:171], v[12:15]
	v_mfma_f32_16x16x32_bf16 v[8:11], v[132:135], v[168:171], v[8:11]
	v_mfma_f32_16x16x32_bf16 v[60:63], v[124:127], v[148:151], v[60:63]
	v_mfma_f32_16x16x32_bf16 v[56:59], v[140:143], v[148:151], v[56:59]
	v_mfma_f32_16x16x32_bf16 v[44:47], v[124:127], v[156:159], v[44:47]
	v_mfma_f32_16x16x32_bf16 v[40:43], v[140:143], v[156:159], v[40:43]
	v_mfma_f32_16x16x32_bf16 v[28:31], v[124:127], v[164:167], v[28:31]
	v_mfma_f32_16x16x32_bf16 v[24:27], v[140:143], v[164:167], v[24:27]
	v_mfma_f32_16x16x32_bf16 v[12:15], v[124:127], v[172:175], v[12:15]
	v_mfma_f32_16x16x32_bf16 v[8:11], v[140:143], v[172:175], v[8:11]
	s_setprio 0
	s_barrier
	s_add_u32 s66, s34, 0x80000
	s_addc_u32 s67, s35, 0
	s_add_i32 s68, s54, s42
	v_lshl_add_u64 v[120:121], s[66:67], 0, v[196:197]
	s_mov_b32 m0, s68
	s_nop 0
	global_load_lds_dwordx4 v[120:121], off
	v_lshl_add_u64 v[120:121], s[66:67], 0, v[200:201]
	s_add_i32 m0, s68, 0x2000
	s_nop 0
	global_load_lds_dwordx4 v[120:121], off
	s_waitcnt vmcnt(6)
	s_barrier
	s_setprio 1
	v_mfma_f32_16x16x32_bf16 v[52:55], v[176:179], v[144:147], v[52:55]
	v_mfma_f32_16x16x32_bf16 v[48:51], v[184:187], v[144:147], v[48:51]
	v_mfma_f32_16x16x32_bf16 v[36:39], v[176:179], v[152:155], v[36:39]
	v_mfma_f32_16x16x32_bf16 v[32:35], v[184:187], v[152:155], v[32:35]
	v_mfma_f32_16x16x32_bf16 v[20:23], v[176:179], v[160:163], v[20:23]
	v_mfma_f32_16x16x32_bf16 v[16:19], v[184:187], v[160:163], v[16:19]
	v_mfma_f32_16x16x32_bf16 v[4:7], v[176:179], v[168:171], v[4:7]
	v_mfma_f32_16x16x32_bf16 v[0:3], v[184:187], v[168:171], v[0:3]
	v_mfma_f32_16x16x32_bf16 v[52:55], v[180:183], v[148:151], v[52:55]
	v_mfma_f32_16x16x32_bf16 v[48:51], v[188:191], v[148:151], v[48:51]
	v_mfma_f32_16x16x32_bf16 v[36:39], v[180:183], v[156:159], v[36:39]
	v_mfma_f32_16x16x32_bf16 v[32:35], v[188:191], v[156:159], v[32:35]
	v_mfma_f32_16x16x32_bf16 v[20:23], v[180:183], v[164:167], v[20:23]
	v_mfma_f32_16x16x32_bf16 v[16:19], v[188:191], v[164:167], v[16:19]
	v_mfma_f32_16x16x32_bf16 v[4:7], v[180:183], v[172:175], v[4:7]
	v_mfma_f32_16x16x32_bf16 v[0:3], v[188:191], v[172:175], v[0:3]
	s_setprio 0
	s_add_i32 s66, 0, 0x18000
	v_add_u32_e32 v140, s66, v242
	s_barrier
	ds_read_b128 v[120:123], v140
	ds_read_b128 v[124:127], v140 offset:1024
	ds_read_b128 v[132:135], v140 offset:2048
	ds_read_b128 v[140:143], v140 offset:3072
	s_add_u32 s36, s36, 0x160000
	s_addc_u32 s37, s37, 0
	s_mov_b32 m0, s45
	v_lshl_add_u64 v[176:177], s[36:37], 0, v[194:195]
	ds_read_b128 v[144:147], v245 offset:32768
	ds_read_b128 v[148:151], v245 offset:33792
	ds_read_b128 v[152:155], v245 offset:34816
	ds_read_b128 v[156:159], v245 offset:35840
	ds_read_b128 v[160:163], v245 offset:36864
	ds_read_b128 v[164:167], v245 offset:37888
	ds_read_b128 v[168:171], v245 offset:38912
	ds_read_b128 v[172:175], v245 offset:39936
	global_load_lds_dwordx4 v[176:177], off
	v_lshl_add_u64 v[176:177], s[36:37], 0, v[198:199]
	s_mov_b32 m0, s46
	s_nop 0
	global_load_lds_dwordx4 v[176:177], off
	s_waitcnt lgkmcnt(8)
	s_barrier
	s_waitcnt lgkmcnt(0)
	s_setprio 1
	s_waitcnt lgkmcnt(0)
	v_mfma_f32_16x16x32_bf16 v[136:139], v[120:123], v[144:147], v[136:139]
	v_mfma_f32_16x16x32_bf16 v[128:131], v[132:135], v[144:147], v[128:131]
	v_mfma_f32_16x16x32_bf16 v[108:111], v[120:123], v[152:155], v[108:111]
	v_mfma_f32_16x16x32_bf16 v[104:107], v[132:135], v[152:155], v[104:107]
	v_mfma_f32_16x16x32_bf16 v[92:95], v[120:123], v[160:163], v[92:95]
	v_mfma_f32_16x16x32_bf16 v[88:91], v[132:135], v[160:163], v[88:91]
	v_mfma_f32_16x16x32_bf16 v[76:79], v[120:123], v[168:171], v[76:79]
	v_mfma_f32_16x16x32_bf16 v[72:75], v[132:135], v[168:171], v[72:75]
	v_mfma_f32_16x16x32_bf16 v[136:139], v[124:127], v[148:151], v[136:139]
	v_mfma_f32_16x16x32_bf16 v[128:131], v[140:143], v[148:151], v[128:131]
	v_mfma_f32_16x16x32_bf16 v[108:111], v[124:127], v[156:159], v[108:111]
	v_mfma_f32_16x16x32_bf16 v[104:107], v[140:143], v[156:159], v[104:107]
	v_mfma_f32_16x16x32_bf16 v[92:95], v[124:127], v[164:167], v[92:95]
	v_mfma_f32_16x16x32_bf16 v[88:91], v[140:143], v[164:167], v[88:91]
	v_mfma_f32_16x16x32_bf16 v[76:79], v[124:127], v[172:175], v[76:79]
	v_mfma_f32_16x16x32_bf16 v[72:75], v[140:143], v[172:175], v[72:75]
	s_setprio 0
	s_barrier
	s_add_i32 s36, 0, 0x1c000
	s_add_i32 s37, s66, s42
	v_add_u32_e32 v188, s36, v242
	v_lshl_add_u64 v[206:207], v[206:207], 0, s[24:25]
	s_mov_b32 m0, s37
	ds_read_b128 v[176:179], v188
	ds_read_b128 v[180:183], v188 offset:1024
	ds_read_b128 v[184:187], v188 offset:2048
	ds_read_b128 v[188:191], v188 offset:3072
	global_load_lds_dwordx4 v[206:207], off
	v_lshl_add_u64 v[206:207], v[208:209], 0, s[24:25]
	s_add_i32 m0, s37, 0x2000
	s_nop 0
	global_load_lds_dwordx4 v[206:207], off
	s_barrier
	s_waitcnt lgkmcnt(0)
	s_setprio 1
	s_waitcnt lgkmcnt(0)
	v_mfma_f32_16x16x32_bf16 v[116:119], v[176:179], v[144:147], v[116:119]
	v_mfma_f32_16x16x32_bf16 v[112:115], v[184:187], v[144:147], v[112:115]
	v_mfma_f32_16x16x32_bf16 v[100:103], v[176:179], v[152:155], v[100:103]
	v_mfma_f32_16x16x32_bf16 v[96:99], v[184:187], v[152:155], v[96:99]
	v_mfma_f32_16x16x32_bf16 v[84:87], v[176:179], v[160:163], v[84:87]
	v_mfma_f32_16x16x32_bf16 v[80:83], v[184:187], v[160:163], v[80:83]
	v_mfma_f32_16x16x32_bf16 v[68:71], v[176:179], v[168:171], v[68:71]
	v_mfma_f32_16x16x32_bf16 v[64:67], v[184:187], v[168:171], v[64:67]
	v_mfma_f32_16x16x32_bf16 v[116:119], v[180:183], v[148:151], v[116:119]
	v_mfma_f32_16x16x32_bf16 v[112:115], v[188:191], v[148:151], v[112:115]
	v_mfma_f32_16x16x32_bf16 v[100:103], v[180:183], v[156:159], v[100:103]
	v_mfma_f32_16x16x32_bf16 v[96:99], v[188:191], v[156:159], v[96:99]
	v_mfma_f32_16x16x32_bf16 v[84:87], v[180:183], v[164:167], v[84:87]
	v_mfma_f32_16x16x32_bf16 v[80:83], v[188:191], v[164:167], v[80:83]
	v_mfma_f32_16x16x32_bf16 v[68:71], v[180:183], v[172:175], v[68:71]
	v_mfma_f32_16x16x32_bf16 v[64:67], v[188:191], v[172:175], v[64:67]
	s_setprio 0
	s_mov_b32 m0, s48
	v_lshl_add_u64 v[206:207], v[210:211], 0, s[24:25]
	s_barrier
	ds_read_b128 v[144:147], v245 offset:49152
	ds_read_b128 v[148:151], v245 offset:50176
	ds_read_b128 v[152:155], v245 offset:51200
	ds_read_b128 v[156:159], v245 offset:52224
	ds_read_b128 v[160:163], v245 offset:53248
	ds_read_b128 v[164:167], v245 offset:54272
	ds_read_b128 v[168:171], v245 offset:55296
	ds_read_b128 v[172:175], v245 offset:56320
	global_load_lds_dwordx4 v[206:207], off
	v_lshl_add_u64 v[206:207], v[212:213], 0, s[24:25]
	s_mov_b32 m0, s49
	s_nop 0
	global_load_lds_dwordx4 v[206:207], off
	s_barrier
	s_waitcnt lgkmcnt(0)
	s_setprio 1
	s_waitcnt lgkmcnt(0)
	v_mfma_f32_16x16x32_bf16 v[60:63], v[120:123], v[144:147], v[60:63]
	v_mfma_f32_16x16x32_bf16 v[56:59], v[132:135], v[144:147], v[56:59]
	v_mfma_f32_16x16x32_bf16 v[44:47], v[120:123], v[152:155], v[44:47]
	v_mfma_f32_16x16x32_bf16 v[40:43], v[132:135], v[152:155], v[40:43]
	v_mfma_f32_16x16x32_bf16 v[28:31], v[120:123], v[160:163], v[28:31]
	v_mfma_f32_16x16x32_bf16 v[24:27], v[132:135], v[160:163], v[24:27]
	v_mfma_f32_16x16x32_bf16 v[12:15], v[120:123], v[168:171], v[12:15]
	v_mfma_f32_16x16x32_bf16 v[8:11], v[132:135], v[168:171], v[8:11]
	v_mfma_f32_16x16x32_bf16 v[60:63], v[124:127], v[148:151], v[60:63]
	v_mfma_f32_16x16x32_bf16 v[56:59], v[140:143], v[148:151], v[56:59]
	v_mfma_f32_16x16x32_bf16 v[44:47], v[124:127], v[156:159], v[44:47]
	v_mfma_f32_16x16x32_bf16 v[40:43], v[140:143], v[156:159], v[40:43]
	v_mfma_f32_16x16x32_bf16 v[28:31], v[124:127], v[164:167], v[28:31]
	v_mfma_f32_16x16x32_bf16 v[24:27], v[140:143], v[164:167], v[24:27]
	v_mfma_f32_16x16x32_bf16 v[12:15], v[124:127], v[172:175], v[12:15]
	v_mfma_f32_16x16x32_bf16 v[8:11], v[140:143], v[172:175], v[8:11]
	s_setprio 0
	s_barrier
	s_add_u32 s34, s34, 0x80080
	s_addc_u32 s35, s35, 0
	s_add_i32 s36, s36, s42
	v_lshl_add_u64 v[120:121], s[34:35], 0, v[196:197]
	s_mov_b32 m0, s36
	s_nop 0
	global_load_lds_dwordx4 v[120:121], off
	v_lshl_add_u64 v[120:121], s[34:35], 0, v[200:201]
	s_add_i32 m0, s36, 0x2000
	s_nop 0
	global_load_lds_dwordx4 v[120:121], off
	s_waitcnt vmcnt(6)
	s_barrier
	s_setprio 1
	v_mfma_f32_16x16x32_bf16 v[52:55], v[176:179], v[144:147], v[52:55]
	v_mfma_f32_16x16x32_bf16 v[48:51], v[184:187], v[144:147], v[48:51]
	v_mfma_f32_16x16x32_bf16 v[36:39], v[176:179], v[152:155], v[36:39]
	v_mfma_f32_16x16x32_bf16 v[32:35], v[184:187], v[152:155], v[32:35]
	v_mfma_f32_16x16x32_bf16 v[20:23], v[176:179], v[160:163], v[20:23]
	v_mfma_f32_16x16x32_bf16 v[16:19], v[184:187], v[160:163], v[16:19]
	v_mfma_f32_16x16x32_bf16 v[4:7], v[176:179], v[168:171], v[4:7]
	v_mfma_f32_16x16x32_bf16 v[0:3], v[184:187], v[168:171], v[0:3]
	v_mfma_f32_16x16x32_bf16 v[52:55], v[180:183], v[148:151], v[52:55]
	v_mfma_f32_16x16x32_bf16 v[48:51], v[188:191], v[148:151], v[48:51]
	v_mfma_f32_16x16x32_bf16 v[36:39], v[180:183], v[156:159], v[36:39]
	v_mfma_f32_16x16x32_bf16 v[32:35], v[188:191], v[156:159], v[32:35]
	v_mfma_f32_16x16x32_bf16 v[20:23], v[180:183], v[164:167], v[20:23]
	v_mfma_f32_16x16x32_bf16 v[16:19], v[188:191], v[164:167], v[16:19]
	v_mfma_f32_16x16x32_bf16 v[4:7], v[180:183], v[172:175], v[4:7]
	v_mfma_f32_16x16x32_bf16 v[0:3], v[188:191], v[172:175], v[0:3]
	s_setprio 0
	s_add_i32 s65, s65, 2
	s_add_u32 s10, s10, 0x100
	s_addc_u32 s11, s11, 0
	s_add_u32 s59, s59, 0x100
	s_addc_u32 s64, s64, 0
	s_cmp_gt_u32 s65, 29
	s_barrier
	s_cbranch_scc0 .LBB0_818
	v_lshl_or_b32 v206, s12, 8, v243
	v_lshl_add_u32 v236, s57, 8, v193
	v_ashrrev_i32_e32 v207, 31, v206
	v_lshlrev_b64 v[238:239], 1, v[206:207]
	v_ashrrev_i32_e32 v237, 31, v236
	v_lshl_add_u64 v[124:125], s[14:15], 0, v[238:239]
	v_lshlrev_b64 v[240:241], 11, v[236:237]
	v_lshl_add_u64 v[120:121], v[124:125], 0, v[240:241]
	global_load_dwordx4 v[188:191], v[120:121], off
	global_load_dwordx4 v[184:187], v[120:121], off offset:256
	v_or_b32_e32 v232, 16, v236
	v_ashrrev_i32_e32 v233, 31, v232
	v_or_b32_e32 v228, 32, v236
	v_lshlrev_b64 v[234:235], 11, v[232:233]
	v_ashrrev_i32_e32 v229, 31, v228
	v_or_b32_e32 v224, 48, v236
	v_lshl_add_u64 v[120:121], v[124:125], 0, v[234:235]
	v_lshlrev_b64 v[230:231], 11, v[228:229]
	v_ashrrev_i32_e32 v225, 31, v224
	v_add_u32_e32 v220, 0x80, v236
	global_load_dwordx4 v[180:183], v[120:121], off
	global_load_dwordx4 v[176:179], v[120:121], off offset:256
	v_lshl_add_u64 v[120:121], v[124:125], 0, v[230:231]
	v_lshlrev_b64 v[226:227], 11, v[224:225]
	v_ashrrev_i32_e32 v221, 31, v220
	v_add_u32_e32 v216, 0x90, v236
	global_load_dwordx4 v[172:175], v[120:121], off
	global_load_dwordx4 v[168:171], v[120:121], off offset:256
	v_lshl_add_u64 v[120:121], v[124:125], 0, v[226:227]
	v_lshlrev_b64 v[222:223], 11, v[220:221]
	v_ashrrev_i32_e32 v217, 31, v216
	v_add_u32_e32 v212, 0xa0, v236
	v_add_u32_e32 v208, 0xb0, v236
	global_load_dwordx4 v[164:167], v[120:121], off
	global_load_dwordx4 v[160:163], v[120:121], off offset:256
	v_lshl_add_u64 v[120:121], v[124:125], 0, v[222:223]
	v_lshlrev_b64 v[218:219], 11, v[216:217]
	v_ashrrev_i32_e32 v213, 31, v212
	v_ashrrev_i32_e32 v209, 31, v208
	global_load_dwordx4 v[156:159], v[120:121], off
	global_load_dwordx4 v[152:155], v[120:121], off offset:256
	v_lshl_add_u64 v[120:121], v[124:125], 0, v[218:219]
	v_lshlrev_b64 v[214:215], 11, v[212:213]
	v_lshlrev_b64 v[210:211], 11, v[208:209]
	global_load_dwordx4 v[148:151], v[120:121], off
	global_load_dwordx4 v[144:147], v[120:121], off offset:256
	v_lshl_add_u64 v[120:121], v[124:125], 0, v[214:215]
	v_lshl_add_u64 v[124:125], v[124:125], 0, v[210:211]
	global_load_dwordx4 v[132:135], v[120:121], off
	s_nop 0
	global_load_dwordx4 v[120:123], v[120:121], off offset:256
	s_nop 0
	global_load_dwordx4 v[140:143], v[124:125], off
	s_nop 0
	global_load_dwordx4 v[124:127], v[124:125], off offset:256
	v_and_b32_e32 v249, 64, v247
	v_xor_b32_e32 v248, 16, v247
	v_add_u32_e32 v249, 64, v249
	v_cmp_lt_i32_e32 vcc, v248, v249
	v_xor_b32_e32 v250, 32, v247
	s_lshl_b32 s10, s12, 2
	v_cndmask_b32_e32 v248, v247, v248, vcc
	v_cmp_lt_i32_e32 vcc, v250, v249
	v_lshlrev_b32_e32 v248, 2, v248
	s_ashr_i32 s11, s10, 31
	v_cndmask_b32_e32 v249, v247, v250, vcc
	v_lshlrev_b32_e32 v249, 2, v249
	s_waitcnt vmcnt(0)
	v_lshlrev_b32_e32 v250, 16, v188
	v_and_b32_e32 v251, 0xffff0000, v188
	v_lshlrev_b32_e32 v188, 16, v189
	v_and_b32_e32 v189, 0xffff0000, v189
	v_lshlrev_b32_e32 v252, 16, v190
	v_and_b32_e32 v253, 0xffff0000, v190
	v_lshlrev_b32_e32 v190, 16, v191
	v_and_b32_e32 v191, 0xffff0000, v191
	v_pk_add_f32 v[138:139], v[138:139], v[188:189]
	v_pk_add_f32 v[136:137], v[136:137], v[250:251]
	v_pk_add_f32 v[188:189], v[130:131], v[190:191]
	v_pk_add_f32 v[130:131], v[128:129], v[252:253]
	v_mul_f32_e32 v128, v137, v137
	v_mul_f32_e32 v129, v139, v139
	v_fmac_f32_e32 v128, v136, v136
	v_fmac_f32_e32 v129, v138, v138
	v_add_f32_e32 v128, v128, v129
	v_mul_f32_e32 v129, v131, v131
	v_mul_f32_e32 v190, v189, v189
	v_fmac_f32_e32 v129, v130, v130
	v_fmac_f32_e32 v190, v188, v188
	v_add_f32_e32 v129, v129, v190
	v_add_f32_e32 v190, v128, v129
	v_cvt_pk_bf16_f32 v128, v136, v137
	v_lshl_add_u64 v[136:137], s[14:15], 0, v[240:241]
	v_cvt_pk_bf16_f32 v129, v138, v139
	v_cvt_pk_bf16_f32 v130, v130, v131
	v_cvt_pk_bf16_f32 v131, v188, v189
	v_lshl_add_u64 v[136:137], v[136:137], 0, v[238:239]
	global_store_dwordx4 v[136:137], v[128:131], off sc1
	v_lshlrev_b32_e32 v138, 16, v186
	v_and_b32_e32 v139, 0xffff0000, v186
	v_lshlrev_b32_e32 v128, 16, v184
	v_and_b32_e32 v129, 0xffff0000, v184
	v_lshlrev_b32_e32 v130, 16, v185
	v_and_b32_e32 v131, 0xffff0000, v185
	v_lshlrev_b32_e32 v184, 16, v187
	v_and_b32_e32 v185, 0xffff0000, v187
	v_pk_add_f32 v[118:119], v[118:119], v[130:131]
	v_pk_add_f32 v[116:117], v[116:117], v[128:129]
	v_pk_add_f32 v[128:129], v[114:115], v[184:185]
	v_pk_add_f32 v[114:115], v[112:113], v[138:139]
	v_mul_f32_e32 v112, v117, v117
	v_mul_f32_e32 v113, v119, v119
	v_fmac_f32_e32 v112, v116, v116
	v_fmac_f32_e32 v113, v118, v118
	v_add_f32_e32 v112, v112, v113
	v_mul_f32_e32 v113, v115, v115
	v_mul_f32_e32 v130, v129, v129
	v_fmac_f32_e32 v113, v114, v114
	v_fmac_f32_e32 v130, v128, v128
	v_add_f32_e32 v113, v113, v130
	v_add_f32_e32 v112, v112, v113
	v_add_f32_e32 v130, v190, v112
	v_cvt_pk_bf16_f32 v112, v116, v117
	v_cvt_pk_bf16_f32 v113, v118, v119
	v_cvt_pk_bf16_f32 v114, v114, v115
	v_cvt_pk_bf16_f32 v115, v128, v129
	global_store_dwordx4 v[136:137], v[112:115], off offset:256 sc1
	s_nop 1
	v_mov_b32_e32 v112, v130
	s_nop 1
	v_permlane16_swap_b32_e32 v130, v112
	s_waitcnt lgkmcnt(0)
	v_add_f32_e32 v112, v130, v112
	v_mov_b32_e32 v113, v112
	s_nop 1
	v_permlane32_swap_b32_e32 v112, v113
	s_and_saveexec_b64 s[34:35], s[6:7]
	s_cbranch_execz .LBB0_821
	v_lshlrev_b64 v[114:115], 6, v[236:237]
	v_lshl_add_u64 v[114:115], s[16:17], 0, v[114:115]
	v_lshl_add_u64 v[114:115], s[10:11], 2, v[114:115]
	s_lshl_b32 s12, s47, 2
	v_lshl_add_u64 v[114:115], v[114:115], 0, s[12:13]
	s_waitcnt lgkmcnt(0)
	v_add_f32_e32 v112, v112, v113
	global_store_dword v[114:115], v112, off
.LBB0_821:
	s_or_b64 exec, exec, s[34:35]
	v_lshlrev_b32_e32 v112, 16, v180
	s_waitcnt lgkmcnt(0)
	v_and_b32_e32 v113, 0xffff0000, v180
	v_lshlrev_b32_e32 v114, 16, v181
	v_and_b32_e32 v115, 0xffff0000, v181
	v_lshlrev_b32_e32 v116, 16, v182
	v_and_b32_e32 v117, 0xffff0000, v182
	v_lshlrev_b32_e32 v118, 16, v183
	v_and_b32_e32 v119, 0xffff0000, v183
	v_pk_add_f32 v[110:111], v[110:111], v[114:115]
	v_pk_add_f32 v[108:109], v[108:109], v[112:113]
	v_pk_add_f32 v[112:113], v[106:107], v[118:119]
	v_pk_add_f32 v[106:107], v[104:105], v[116:117]
	v_mul_f32_e32 v104, v109, v109
	v_mul_f32_e32 v105, v111, v111
	v_fmac_f32_e32 v104, v108, v108
	v_fmac_f32_e32 v105, v110, v110
	v_add_f32_e32 v104, v104, v105
	v_mul_f32_e32 v105, v107, v107
	v_mul_f32_e32 v114, v113, v113
	v_fmac_f32_e32 v105, v106, v106
	v_fmac_f32_e32 v114, v112, v112
	v_add_f32_e32 v105, v105, v114
	v_add_f32_e32 v116, v104, v105
	v_cvt_pk_bf16_f32 v104, v108, v109
	v_cvt_pk_bf16_f32 v105, v110, v111
	v_lshlrev_b32_e32 v108, 16, v176
	v_and_b32_e32 v109, 0xffff0000, v176
	v_lshlrev_b32_e32 v110, 16, v177
	v_and_b32_e32 v111, 0xffff0000, v177
	v_cvt_pk_bf16_f32 v106, v106, v107
	v_cvt_pk_bf16_f32 v107, v112, v113
	v_lshlrev_b32_e32 v112, 16, v178
	v_and_b32_e32 v113, 0xffff0000, v178
	v_pk_add_f32 v[102:103], v[102:103], v[110:111]
	v_pk_add_f32 v[100:101], v[100:101], v[108:109]
	v_lshlrev_b32_e32 v114, 16, v179
	v_and_b32_e32 v115, 0xffff0000, v179
	v_pk_add_f32 v[110:111], v[96:97], v[112:113]
	v_mul_f32_e32 v96, v101, v101
	v_mul_f32_e32 v97, v103, v103
	v_pk_add_f32 v[108:109], v[98:99], v[114:115]
	v_fmac_f32_e32 v96, v100, v100
	v_fmac_f32_e32 v97, v102, v102
	v_add_f32_e32 v96, v96, v97
	v_mul_f32_e32 v97, v111, v111
	v_mul_f32_e32 v98, v109, v109
	v_fmac_f32_e32 v97, v110, v110
	v_fmac_f32_e32 v98, v108, v108
	v_add_f32_e32 v97, v97, v98
	v_add_f32_e32 v96, v96, v97
	v_add_f32_e32 v99, v116, v96
	v_mov_b32_e32 v114, v99
	s_nop 1
	v_permlane16_swap_b32_e32 v99, v114
	v_lshl_add_u64 v[96:97], s[14:15], 0, v[234:235]
	v_lshl_add_u64 v[112:113], v[206:207], 1, v[96:97]
	v_cvt_pk_bf16_f32 v98, v100, v101
	v_cvt_pk_bf16_f32 v100, v110, v111
	s_waitcnt lgkmcnt(0)
	v_add_f32_e32 v96, v99, v114
	v_mov_b32_e32 v97, v96
	s_nop 1
	v_permlane32_swap_b32_e32 v96, v97
	v_cvt_pk_bf16_f32 v99, v102, v103
	v_cvt_pk_bf16_f32 v101, v108, v109
	global_store_dwordx4 v[112:113], v[104:107], off sc1
	global_store_dwordx4 v[112:113], v[98:101], off offset:256 sc1
	s_and_saveexec_b64 s[34:35], s[6:7]
	s_cbranch_execz .LBB0_823
	v_lshlrev_b64 v[98:99], 6, v[232:233]
	v_lshl_add_u64 v[98:99], s[16:17], 0, v[98:99]
	v_lshl_add_u64 v[98:99], s[10:11], 2, v[98:99]
	s_lshl_b32 s12, s47, 2
	v_lshl_add_u64 v[98:99], v[98:99], 0, s[12:13]
	s_waitcnt lgkmcnt(0)
	v_add_f32_e32 v96, v96, v97
	global_store_dword v[98:99], v96, off
.LBB0_823:
	s_or_b64 exec, exec, s[34:35]
	v_lshlrev_b32_e32 v96, 16, v172
	s_waitcnt lgkmcnt(0)
	v_and_b32_e32 v97, 0xffff0000, v172
	v_lshlrev_b32_e32 v98, 16, v173
	v_and_b32_e32 v99, 0xffff0000, v173
	v_lshlrev_b32_e32 v100, 16, v174
	v_and_b32_e32 v101, 0xffff0000, v174
	v_lshlrev_b32_e32 v102, 16, v175
	v_and_b32_e32 v103, 0xffff0000, v175
	v_pk_add_f32 v[94:95], v[94:95], v[98:99]
	v_pk_add_f32 v[92:93], v[92:93], v[96:97]
	v_pk_add_f32 v[96:97], v[90:91], v[102:103]
	v_pk_add_f32 v[90:91], v[88:89], v[100:101]
	v_mul_f32_e32 v88, v93, v93
	v_mul_f32_e32 v89, v95, v95
	v_fmac_f32_e32 v88, v92, v92
	v_fmac_f32_e32 v89, v94, v94
	v_add_f32_e32 v88, v88, v89
	v_mul_f32_e32 v89, v91, v91
	v_mul_f32_e32 v98, v97, v97
	v_fmac_f32_e32 v89, v90, v90
	v_fmac_f32_e32 v98, v96, v96
	v_add_f32_e32 v89, v89, v98
	v_add_f32_e32 v100, v88, v89
	v_cvt_pk_bf16_f32 v88, v92, v93
	v_cvt_pk_bf16_f32 v89, v94, v95
	v_lshlrev_b32_e32 v92, 16, v168
	v_and_b32_e32 v93, 0xffff0000, v168
	v_lshlrev_b32_e32 v94, 16, v169
	v_and_b32_e32 v95, 0xffff0000, v169
	v_cvt_pk_bf16_f32 v90, v90, v91
	v_cvt_pk_bf16_f32 v91, v96, v97
	v_lshlrev_b32_e32 v96, 16, v170
	v_and_b32_e32 v97, 0xffff0000, v170
	v_pk_add_f32 v[86:87], v[86:87], v[94:95]
	v_pk_add_f32 v[84:85], v[84:85], v[92:93]
	v_lshlrev_b32_e32 v98, 16, v171
	v_and_b32_e32 v99, 0xffff0000, v171
	v_pk_add_f32 v[94:95], v[80:81], v[96:97]
	v_mul_f32_e32 v80, v85, v85
	v_mul_f32_e32 v81, v87, v87
	v_pk_add_f32 v[92:93], v[82:83], v[98:99]
	v_fmac_f32_e32 v80, v84, v84
	v_fmac_f32_e32 v81, v86, v86
	v_add_f32_e32 v80, v80, v81
	v_mul_f32_e32 v81, v95, v95
	v_mul_f32_e32 v82, v93, v93
	v_fmac_f32_e32 v81, v94, v94
	v_fmac_f32_e32 v82, v92, v92
	v_add_f32_e32 v81, v81, v82
	v_add_f32_e32 v80, v80, v81
	v_add_f32_e32 v83, v100, v80
	v_mov_b32_e32 v98, v83
	s_nop 1
	v_permlane16_swap_b32_e32 v83, v98
	v_lshl_add_u64 v[80:81], s[14:15], 0, v[230:231]
	v_lshl_add_u64 v[96:97], v[206:207], 1, v[80:81]
	v_cvt_pk_bf16_f32 v82, v84, v85
	v_cvt_pk_bf16_f32 v84, v94, v95
	s_waitcnt lgkmcnt(0)
	v_add_f32_e32 v80, v83, v98
	v_mov_b32_e32 v81, v80
	s_nop 1
	v_permlane32_swap_b32_e32 v80, v81
	v_cvt_pk_bf16_f32 v83, v86, v87
	v_cvt_pk_bf16_f32 v85, v92, v93
	global_store_dwordx4 v[96:97], v[88:91], off sc1
	global_store_dwordx4 v[96:97], v[82:85], off offset:256 sc1
	s_and_saveexec_b64 s[34:35], s[6:7]
	s_cbranch_execz .LBB0_825
	v_lshlrev_b64 v[82:83], 6, v[228:229]
	v_lshl_add_u64 v[82:83], s[16:17], 0, v[82:83]
	v_lshl_add_u64 v[82:83], s[10:11], 2, v[82:83]
	s_lshl_b32 s12, s47, 2
	v_lshl_add_u64 v[82:83], v[82:83], 0, s[12:13]
	s_waitcnt lgkmcnt(0)
	v_add_f32_e32 v80, v80, v81
	global_store_dword v[82:83], v80, off
.LBB0_825:
	s_or_b64 exec, exec, s[34:35]
	v_lshlrev_b32_e32 v80, 16, v164
	s_waitcnt lgkmcnt(0)
	v_and_b32_e32 v81, 0xffff0000, v164
	v_lshlrev_b32_e32 v82, 16, v165
	v_and_b32_e32 v83, 0xffff0000, v165
	v_lshlrev_b32_e32 v84, 16, v166
	v_and_b32_e32 v85, 0xffff0000, v166
	v_lshlrev_b32_e32 v86, 16, v167
	v_and_b32_e32 v87, 0xffff0000, v167
	v_pk_add_f32 v[78:79], v[78:79], v[82:83]
	v_pk_add_f32 v[76:77], v[76:77], v[80:81]
	v_pk_add_f32 v[80:81], v[74:75], v[86:87]
	v_pk_add_f32 v[74:75], v[72:73], v[84:85]
	v_mul_f32_e32 v72, v77, v77
	v_mul_f32_e32 v73, v79, v79
	v_fmac_f32_e32 v72, v76, v76
	v_fmac_f32_e32 v73, v78, v78
	v_add_f32_e32 v72, v72, v73
	v_mul_f32_e32 v73, v75, v75
	v_mul_f32_e32 v82, v81, v81
	v_fmac_f32_e32 v73, v74, v74
	v_fmac_f32_e32 v82, v80, v80
	v_add_f32_e32 v73, v73, v82
	v_add_f32_e32 v84, v72, v73
	v_cvt_pk_bf16_f32 v72, v76, v77
	v_cvt_pk_bf16_f32 v73, v78, v79
	v_lshlrev_b32_e32 v76, 16, v160
	v_and_b32_e32 v77, 0xffff0000, v160
	v_lshlrev_b32_e32 v78, 16, v161
	v_and_b32_e32 v79, 0xffff0000, v161
	v_cvt_pk_bf16_f32 v74, v74, v75
	v_cvt_pk_bf16_f32 v75, v80, v81
	v_lshlrev_b32_e32 v80, 16, v162
	v_and_b32_e32 v81, 0xffff0000, v162
	v_pk_add_f32 v[70:71], v[70:71], v[78:79]
	v_pk_add_f32 v[68:69], v[68:69], v[76:77]
	v_lshlrev_b32_e32 v82, 16, v163
	v_and_b32_e32 v83, 0xffff0000, v163
	v_pk_add_f32 v[78:79], v[64:65], v[80:81]
	v_mul_f32_e32 v64, v69, v69
	v_mul_f32_e32 v65, v71, v71
	v_pk_add_f32 v[76:77], v[66:67], v[82:83]
	v_fmac_f32_e32 v64, v68, v68
	v_fmac_f32_e32 v65, v70, v70
	v_add_f32_e32 v64, v64, v65
	v_mul_f32_e32 v65, v79, v79
	v_mul_f32_e32 v66, v77, v77
	v_fmac_f32_e32 v65, v78, v78
	v_fmac_f32_e32 v66, v76, v76
	v_add_f32_e32 v65, v65, v66
	v_add_f32_e32 v64, v64, v65
	v_add_f32_e32 v67, v84, v64
	v_mov_b32_e32 v82, v67
	s_nop 1
	v_permlane16_swap_b32_e32 v67, v82
	v_lshl_add_u64 v[64:65], s[14:15], 0, v[226:227]
	v_lshl_add_u64 v[80:81], v[206:207], 1, v[64:65]
	v_cvt_pk_bf16_f32 v66, v68, v69
	v_cvt_pk_bf16_f32 v68, v78, v79
	s_waitcnt lgkmcnt(0)
	v_add_f32_e32 v64, v67, v82
	v_mov_b32_e32 v65, v64
	s_nop 1
	v_permlane32_swap_b32_e32 v64, v65
	v_cvt_pk_bf16_f32 v67, v70, v71
	v_cvt_pk_bf16_f32 v69, v76, v77
	global_store_dwordx4 v[80:81], v[72:75], off sc1
	global_store_dwordx4 v[80:81], v[66:69], off offset:256 sc1
	s_and_saveexec_b64 s[34:35], s[6:7]
	s_cbranch_execz .LBB0_827
	v_lshlrev_b64 v[66:67], 6, v[224:225]
	v_lshl_add_u64 v[66:67], s[16:17], 0, v[66:67]
	v_lshl_add_u64 v[66:67], s[10:11], 2, v[66:67]
	s_lshl_b32 s12, s47, 2
	v_lshl_add_u64 v[66:67], v[66:67], 0, s[12:13]
	s_waitcnt lgkmcnt(0)
	v_add_f32_e32 v64, v64, v65
	global_store_dword v[66:67], v64, off
.LBB0_827:
	s_or_b64 exec, exec, s[34:35]
	v_lshlrev_b32_e32 v64, 16, v156
	s_waitcnt lgkmcnt(0)
	v_and_b32_e32 v65, 0xffff0000, v156
	v_lshlrev_b32_e32 v66, 16, v157
	v_and_b32_e32 v67, 0xffff0000, v157
	v_lshlrev_b32_e32 v68, 16, v158
	v_and_b32_e32 v69, 0xffff0000, v158
	v_lshlrev_b32_e32 v70, 16, v159
	v_and_b32_e32 v71, 0xffff0000, v159
	v_pk_add_f32 v[62:63], v[62:63], v[66:67]
	v_pk_add_f32 v[60:61], v[60:61], v[64:65]
	v_pk_add_f32 v[64:65], v[58:59], v[70:71]
	v_pk_add_f32 v[58:59], v[56:57], v[68:69]
	v_mul_f32_e32 v56, v61, v61
	v_mul_f32_e32 v57, v63, v63
	v_fmac_f32_e32 v56, v60, v60
	v_fmac_f32_e32 v57, v62, v62
	v_add_f32_e32 v56, v56, v57
	v_mul_f32_e32 v57, v59, v59
	v_mul_f32_e32 v66, v65, v65
	v_fmac_f32_e32 v57, v58, v58
	v_fmac_f32_e32 v66, v64, v64
	v_add_f32_e32 v57, v57, v66
	v_add_f32_e32 v68, v56, v57
	v_cvt_pk_bf16_f32 v56, v60, v61
	v_cvt_pk_bf16_f32 v57, v62, v63
	v_lshlrev_b32_e32 v60, 16, v152
	v_and_b32_e32 v61, 0xffff0000, v152
	v_lshlrev_b32_e32 v62, 16, v153
	v_and_b32_e32 v63, 0xffff0000, v153
	v_cvt_pk_bf16_f32 v58, v58, v59
	v_cvt_pk_bf16_f32 v59, v64, v65
	v_lshlrev_b32_e32 v64, 16, v154
	v_and_b32_e32 v65, 0xffff0000, v154
	v_pk_add_f32 v[54:55], v[54:55], v[62:63]
	v_pk_add_f32 v[52:53], v[52:53], v[60:61]
	v_lshlrev_b32_e32 v66, 16, v155
	v_and_b32_e32 v67, 0xffff0000, v155
	v_pk_add_f32 v[62:63], v[48:49], v[64:65]
	v_mul_f32_e32 v48, v53, v53
	v_mul_f32_e32 v49, v55, v55
	v_pk_add_f32 v[60:61], v[50:51], v[66:67]
	v_fmac_f32_e32 v48, v52, v52
	v_fmac_f32_e32 v49, v54, v54
	v_add_f32_e32 v48, v48, v49
	v_mul_f32_e32 v49, v63, v63
	v_mul_f32_e32 v50, v61, v61
	v_fmac_f32_e32 v49, v62, v62
	v_fmac_f32_e32 v50, v60, v60
	v_add_f32_e32 v49, v49, v50
	v_add_f32_e32 v48, v48, v49
	v_add_f32_e32 v51, v68, v48
	v_mov_b32_e32 v66, v51
	s_nop 1
	v_permlane16_swap_b32_e32 v51, v66
	v_lshl_add_u64 v[48:49], s[14:15], 0, v[222:223]
	v_lshl_add_u64 v[64:65], v[206:207], 1, v[48:49]
	v_cvt_pk_bf16_f32 v50, v52, v53
	v_cvt_pk_bf16_f32 v52, v62, v63
	s_waitcnt lgkmcnt(0)
	v_add_f32_e32 v48, v51, v66
	v_mov_b32_e32 v49, v48
	s_nop 1
	v_permlane32_swap_b32_e32 v48, v49
	v_cvt_pk_bf16_f32 v51, v54, v55
	v_cvt_pk_bf16_f32 v53, v60, v61
	global_store_dwordx4 v[64:65], v[56:59], off sc1
	global_store_dwordx4 v[64:65], v[50:53], off offset:256 sc1
	s_and_saveexec_b64 s[34:35], s[6:7]
	s_cbranch_execz .LBB0_829
	v_lshlrev_b64 v[50:51], 6, v[220:221]
	v_lshl_add_u64 v[50:51], s[16:17], 0, v[50:51]
	v_lshl_add_u64 v[50:51], s[10:11], 2, v[50:51]
	s_lshl_b32 s12, s47, 2
	v_lshl_add_u64 v[50:51], v[50:51], 0, s[12:13]
	s_waitcnt lgkmcnt(0)
	v_add_f32_e32 v48, v48, v49
	global_store_dword v[50:51], v48, off
.LBB0_829:
	s_or_b64 exec, exec, s[34:35]
	v_lshlrev_b32_e32 v48, 16, v148
	s_waitcnt lgkmcnt(0)
	v_and_b32_e32 v49, 0xffff0000, v148
	v_lshlrev_b32_e32 v50, 16, v149
	v_and_b32_e32 v51, 0xffff0000, v149
	v_lshlrev_b32_e32 v52, 16, v150
	v_and_b32_e32 v53, 0xffff0000, v150
	v_lshlrev_b32_e32 v54, 16, v151
	v_and_b32_e32 v55, 0xffff0000, v151
	v_pk_add_f32 v[46:47], v[46:47], v[50:51]
	v_pk_add_f32 v[44:45], v[44:45], v[48:49]
	v_pk_add_f32 v[48:49], v[42:43], v[54:55]
	v_pk_add_f32 v[42:43], v[40:41], v[52:53]
	v_mul_f32_e32 v40, v45, v45
	v_mul_f32_e32 v41, v47, v47
	v_fmac_f32_e32 v40, v44, v44
	v_fmac_f32_e32 v41, v46, v46
	v_add_f32_e32 v40, v40, v41
	v_mul_f32_e32 v41, v43, v43
	v_mul_f32_e32 v50, v49, v49
	v_fmac_f32_e32 v41, v42, v42
	v_fmac_f32_e32 v50, v48, v48
	v_add_f32_e32 v41, v41, v50
	v_add_f32_e32 v52, v40, v41
	v_cvt_pk_bf16_f32 v40, v44, v45
	v_cvt_pk_bf16_f32 v41, v46, v47
	v_lshlrev_b32_e32 v44, 16, v144
	v_and_b32_e32 v45, 0xffff0000, v144
	v_lshlrev_b32_e32 v46, 16, v145
	v_and_b32_e32 v47, 0xffff0000, v145
	v_cvt_pk_bf16_f32 v42, v42, v43
	v_cvt_pk_bf16_f32 v43, v48, v49
	v_lshlrev_b32_e32 v48, 16, v146
	v_and_b32_e32 v49, 0xffff0000, v146
	v_pk_add_f32 v[38:39], v[38:39], v[46:47]
	v_pk_add_f32 v[36:37], v[36:37], v[44:45]
	v_lshlrev_b32_e32 v50, 16, v147
	v_and_b32_e32 v51, 0xffff0000, v147
	v_pk_add_f32 v[46:47], v[32:33], v[48:49]
	v_mul_f32_e32 v32, v37, v37
	v_mul_f32_e32 v33, v39, v39
	v_pk_add_f32 v[44:45], v[34:35], v[50:51]
	v_fmac_f32_e32 v32, v36, v36
	v_fmac_f32_e32 v33, v38, v38
	v_add_f32_e32 v32, v32, v33
	v_mul_f32_e32 v33, v47, v47
	v_mul_f32_e32 v34, v45, v45
	v_fmac_f32_e32 v33, v46, v46
	v_fmac_f32_e32 v34, v44, v44
	v_add_f32_e32 v33, v33, v34
	v_add_f32_e32 v32, v32, v33
	v_add_f32_e32 v35, v52, v32
	v_mov_b32_e32 v50, v35
	s_nop 1
	v_permlane16_swap_b32_e32 v35, v50
	v_lshl_add_u64 v[32:33], s[14:15], 0, v[218:219]
	v_lshl_add_u64 v[48:49], v[206:207], 1, v[32:33]
	v_cvt_pk_bf16_f32 v34, v36, v37
	v_cvt_pk_bf16_f32 v36, v46, v47
	s_waitcnt lgkmcnt(0)
	v_add_f32_e32 v32, v35, v50
	v_mov_b32_e32 v33, v32
	s_nop 1
	v_permlane32_swap_b32_e32 v32, v33
	v_cvt_pk_bf16_f32 v35, v38, v39
	v_cvt_pk_bf16_f32 v37, v44, v45
	global_store_dwordx4 v[48:49], v[40:43], off sc1
	global_store_dwordx4 v[48:49], v[34:37], off offset:256 sc1
	s_and_saveexec_b64 s[34:35], s[6:7]
	s_cbranch_execz .LBB0_831
	v_lshlrev_b64 v[34:35], 6, v[216:217]
	v_lshl_add_u64 v[34:35], s[16:17], 0, v[34:35]
	v_lshl_add_u64 v[34:35], s[10:11], 2, v[34:35]
	s_lshl_b32 s12, s47, 2
	v_lshl_add_u64 v[34:35], v[34:35], 0, s[12:13]
	s_waitcnt lgkmcnt(0)
	v_add_f32_e32 v32, v32, v33
	global_store_dword v[34:35], v32, off
.LBB0_831:
	s_or_b64 exec, exec, s[34:35]
	v_lshlrev_b32_e32 v32, 16, v132
	s_waitcnt lgkmcnt(0)
	v_and_b32_e32 v33, 0xffff0000, v132
	v_lshlrev_b32_e32 v34, 16, v133
	v_and_b32_e32 v35, 0xffff0000, v133
	v_lshlrev_b32_e32 v36, 16, v134
	v_and_b32_e32 v37, 0xffff0000, v134
	v_lshlrev_b32_e32 v38, 16, v135
	v_and_b32_e32 v39, 0xffff0000, v135
	v_pk_add_f32 v[30:31], v[30:31], v[34:35]
	v_pk_add_f32 v[28:29], v[28:29], v[32:33]
	v_pk_add_f32 v[32:33], v[26:27], v[38:39]
	v_pk_add_f32 v[26:27], v[24:25], v[36:37]
	v_mul_f32_e32 v24, v29, v29
	v_mul_f32_e32 v25, v31, v31
	v_fmac_f32_e32 v24, v28, v28
	v_fmac_f32_e32 v25, v30, v30
	v_add_f32_e32 v24, v24, v25
	v_mul_f32_e32 v25, v27, v27
	v_mul_f32_e32 v34, v33, v33
	v_fmac_f32_e32 v25, v26, v26
	v_fmac_f32_e32 v34, v32, v32
	v_add_f32_e32 v25, v25, v34
	v_add_f32_e32 v36, v24, v25
	v_cvt_pk_bf16_f32 v24, v28, v29
	v_cvt_pk_bf16_f32 v25, v30, v31
	v_lshlrev_b32_e32 v28, 16, v120
	v_and_b32_e32 v29, 0xffff0000, v120
	v_lshlrev_b32_e32 v30, 16, v121
	v_and_b32_e32 v31, 0xffff0000, v121
	v_cvt_pk_bf16_f32 v26, v26, v27
	v_cvt_pk_bf16_f32 v27, v32, v33
	v_lshlrev_b32_e32 v32, 16, v122
	v_and_b32_e32 v33, 0xffff0000, v122
	v_pk_add_f32 v[22:23], v[22:23], v[30:31]
	v_pk_add_f32 v[20:21], v[20:21], v[28:29]
	v_lshlrev_b32_e32 v34, 16, v123
	v_and_b32_e32 v35, 0xffff0000, v123
	v_pk_add_f32 v[30:31], v[16:17], v[32:33]
	v_mul_f32_e32 v16, v21, v21
	v_mul_f32_e32 v17, v23, v23
	v_pk_add_f32 v[28:29], v[18:19], v[34:35]
	v_fmac_f32_e32 v16, v20, v20
	v_fmac_f32_e32 v17, v22, v22
	v_add_f32_e32 v16, v16, v17
	v_mul_f32_e32 v17, v31, v31
	v_mul_f32_e32 v18, v29, v29
	v_fmac_f32_e32 v17, v30, v30
	v_fmac_f32_e32 v18, v28, v28
	v_add_f32_e32 v17, v17, v18
	v_add_f32_e32 v16, v16, v17
	v_add_f32_e32 v19, v36, v16
	v_mov_b32_e32 v34, v19
	s_nop 1
	v_permlane16_swap_b32_e32 v19, v34
	v_lshl_add_u64 v[16:17], s[14:15], 0, v[214:215]
	v_lshl_add_u64 v[32:33], v[206:207], 1, v[16:17]
	v_cvt_pk_bf16_f32 v18, v20, v21
	v_cvt_pk_bf16_f32 v20, v30, v31
	s_waitcnt lgkmcnt(0)
	v_add_f32_e32 v16, v19, v34
	v_mov_b32_e32 v17, v16
	s_nop 1
	v_permlane32_swap_b32_e32 v16, v17
	v_cvt_pk_bf16_f32 v19, v22, v23
	v_cvt_pk_bf16_f32 v21, v28, v29
	global_store_dwordx4 v[32:33], v[24:27], off sc1
	global_store_dwordx4 v[32:33], v[18:21], off offset:256 sc1
	s_and_saveexec_b64 s[34:35], s[6:7]
	s_cbranch_execz .LBB0_833
	v_lshlrev_b64 v[18:19], 6, v[212:213]
	v_lshl_add_u64 v[18:19], s[16:17], 0, v[18:19]
	v_lshl_add_u64 v[18:19], s[10:11], 2, v[18:19]
	s_lshl_b32 s12, s47, 2
	v_lshl_add_u64 v[18:19], v[18:19], 0, s[12:13]
	s_waitcnt lgkmcnt(0)
	v_add_f32_e32 v16, v16, v17
	global_store_dword v[18:19], v16, off
.LBB0_833:
	s_or_b64 exec, exec, s[34:35]
	v_lshlrev_b32_e32 v16, 16, v140
	s_waitcnt lgkmcnt(0)
	v_and_b32_e32 v17, 0xffff0000, v140
	v_lshlrev_b32_e32 v18, 16, v141
	v_and_b32_e32 v19, 0xffff0000, v141
	v_lshlrev_b32_e32 v20, 16, v142
	v_and_b32_e32 v21, 0xffff0000, v142
	v_lshlrev_b32_e32 v22, 16, v143
	v_and_b32_e32 v23, 0xffff0000, v143
	v_pk_add_f32 v[14:15], v[14:15], v[18:19]
	v_pk_add_f32 v[12:13], v[12:13], v[16:17]
	v_pk_add_f32 v[16:17], v[10:11], v[22:23]
	v_pk_add_f32 v[10:11], v[8:9], v[20:21]
	v_mul_f32_e32 v8, v13, v13
	v_mul_f32_e32 v9, v15, v15
	v_fmac_f32_e32 v8, v12, v12
	v_fmac_f32_e32 v9, v14, v14
	v_add_f32_e32 v8, v8, v9
	v_mul_f32_e32 v9, v11, v11
	v_mul_f32_e32 v18, v17, v17
	v_fmac_f32_e32 v9, v10, v10
	v_fmac_f32_e32 v18, v16, v16
	v_add_f32_e32 v9, v9, v18
	v_add_f32_e32 v20, v8, v9
	v_cvt_pk_bf16_f32 v8, v12, v13
	v_cvt_pk_bf16_f32 v9, v14, v15
	v_lshlrev_b32_e32 v12, 16, v124
	v_and_b32_e32 v13, 0xffff0000, v124
	v_lshlrev_b32_e32 v14, 16, v125
	v_and_b32_e32 v15, 0xffff0000, v125
	v_cvt_pk_bf16_f32 v10, v10, v11
	v_cvt_pk_bf16_f32 v11, v16, v17
	v_lshlrev_b32_e32 v16, 16, v126
	v_and_b32_e32 v17, 0xffff0000, v126
	v_pk_add_f32 v[6:7], v[6:7], v[14:15]
	v_pk_add_f32 v[4:5], v[4:5], v[12:13]
	v_lshlrev_b32_e32 v18, 16, v127
	v_and_b32_e32 v19, 0xffff0000, v127
	v_pk_add_f32 v[14:15], v[0:1], v[16:17]
	v_mul_f32_e32 v0, v5, v5
	v_mul_f32_e32 v1, v7, v7
	v_pk_add_f32 v[12:13], v[2:3], v[18:19]
	v_fmac_f32_e32 v0, v4, v4
	v_fmac_f32_e32 v1, v6, v6
	v_add_f32_e32 v0, v0, v1
	v_mul_f32_e32 v1, v15, v15
	v_mul_f32_e32 v2, v13, v13
	v_fmac_f32_e32 v1, v14, v14
	v_fmac_f32_e32 v2, v12, v12
	v_add_f32_e32 v1, v1, v2
	v_add_f32_e32 v0, v0, v1
	v_add_f32_e32 v3, v20, v0
	v_mov_b32_e32 v18, v3
	s_nop 1
	v_permlane16_swap_b32_e32 v3, v18
	v_lshl_add_u64 v[0:1], s[14:15], 0, v[210:211]
	v_lshl_add_u64 v[16:17], v[206:207], 1, v[0:1]
	v_cvt_pk_bf16_f32 v2, v4, v5
	v_cvt_pk_bf16_f32 v4, v14, v15
	s_waitcnt lgkmcnt(0)
	v_add_f32_e32 v0, v3, v18
	v_mov_b32_e32 v1, v0
	s_nop 1
	v_permlane32_swap_b32_e32 v0, v1
	v_cvt_pk_bf16_f32 v3, v6, v7
	v_cvt_pk_bf16_f32 v5, v12, v13
	global_store_dwordx4 v[16:17], v[8:11], off sc1
	global_store_dwordx4 v[16:17], v[2:5], off offset:256 sc1
	s_and_saveexec_b64 s[34:35], s[6:7]
	s_cbranch_execz .LBB0_808
	s_waitcnt lgkmcnt(0)
	v_add_f32_e32 v2, v0, v1
	v_lshlrev_b64 v[0:1], 6, v[208:209]
	v_lshl_add_u64 v[0:1], s[16:17], 0, v[0:1]
	v_lshl_add_u64 v[0:1], s[10:11], 2, v[0:1]
	s_lshl_b32 s12, s47, 2
	v_lshl_add_u64 v[0:1], v[0:1], 0, s[12:13]
	global_store_dword v[0:1], v2, off
	s_branch .LBB0_808

.LBB0_984:
	ds_read_b128 v[120:123], v244
	ds_read_b128 v[124:127], v244 offset:1024
	ds_read_b128 v[132:135], v244 offset:2048
	ds_read_b128 v[140:143], v244 offset:3072
	s_add_u32 s34, s30, 0xfff50080
	s_addc_u32 s35, s31, -1
	s_cmp_eq_u32 s59, 40
	s_cselect_b32 s37, s11, s35
	s_cselect_b32 s36, s10, s34
	s_cselect_b32 s35, s13, s58
	s_cselect_b32 s34, s12, s57
	v_lshl_add_u64 v[176:177], s[30:31], 0, v[202:203]
	s_add_i32 m0, s41, 0xc000
	ds_read_b128 v[144:147], v245
	ds_read_b128 v[148:151], v245 offset:1024
	ds_read_b128 v[152:155], v245 offset:2048
	ds_read_b128 v[156:159], v245 offset:3072
	ds_read_b128 v[160:163], v245 offset:4096
	ds_read_b128 v[164:167], v245 offset:5120
	ds_read_b128 v[168:171], v245 offset:6144
	ds_read_b128 v[172:175], v245 offset:7168
	global_load_lds_dwordx4 v[176:177], off
	v_lshl_add_u64 v[176:177], s[30:31], 0, v[204:205]
	s_add_i32 m0, s41, 0xe000
	s_nop 0
	global_load_lds_dwordx4 v[176:177], off
	s_waitcnt lgkmcnt(8)
	s_barrier
	s_waitcnt lgkmcnt(0)
	s_setprio 1
	s_waitcnt lgkmcnt(0)
	v_mfma_f32_16x16x32_bf16 v[136:139], v[120:123], v[144:147], v[136:139]
	v_mfma_f32_16x16x32_bf16 v[128:131], v[132:135], v[144:147], v[128:131]
	v_mfma_f32_16x16x32_bf16 v[108:111], v[120:123], v[152:155], v[108:111]
	v_mfma_f32_16x16x32_bf16 v[104:107], v[132:135], v[152:155], v[104:107]
	v_mfma_f32_16x16x32_bf16 v[92:95], v[120:123], v[160:163], v[92:95]
	v_mfma_f32_16x16x32_bf16 v[88:91], v[132:135], v[160:163], v[88:91]
	v_mfma_f32_16x16x32_bf16 v[76:79], v[120:123], v[168:171], v[76:79]
	v_mfma_f32_16x16x32_bf16 v[72:75], v[132:135], v[168:171], v[72:75]
	v_mfma_f32_16x16x32_bf16 v[136:139], v[124:127], v[148:151], v[136:139]
	v_mfma_f32_16x16x32_bf16 v[128:131], v[140:143], v[148:151], v[128:131]
	v_mfma_f32_16x16x32_bf16 v[108:111], v[124:127], v[156:159], v[108:111]
	v_mfma_f32_16x16x32_bf16 v[104:107], v[140:143], v[156:159], v[104:107]
	v_mfma_f32_16x16x32_bf16 v[92:95], v[124:127], v[164:167], v[92:95]
	v_mfma_f32_16x16x32_bf16 v[88:91], v[140:143], v[164:167], v[88:91]
	v_mfma_f32_16x16x32_bf16 v[76:79], v[124:127], v[172:175], v[76:79]
	v_mfma_f32_16x16x32_bf16 v[72:75], v[140:143], v[172:175], v[72:75]
	s_setprio 0
	s_barrier
	s_add_i32 s64, s51, s40
	v_lshl_add_u64 v[206:207], s[34:35], 0, v[196:197]
	s_mov_b32 m0, s64
	ds_read_b128 v[176:179], v246
	ds_read_b128 v[180:183], v246 offset:1024
	ds_read_b128 v[184:187], v246 offset:2048
	ds_read_b128 v[188:191], v246 offset:3072
	global_load_lds_dwordx4 v[206:207], off
	v_lshl_add_u64 v[208:209], s[34:35], 0, v[200:201]
	s_add_i32 m0, s64, 0x2000
	s_nop 0
	global_load_lds_dwordx4 v[208:209], off
	s_barrier
	s_waitcnt lgkmcnt(0)
	s_setprio 1
	s_waitcnt lgkmcnt(0)
	v_mfma_f32_16x16x32_bf16 v[116:119], v[176:179], v[144:147], v[116:119]
	v_mfma_f32_16x16x32_bf16 v[112:115], v[184:187], v[144:147], v[112:115]
	v_mfma_f32_16x16x32_bf16 v[100:103], v[176:179], v[152:155], v[100:103]
	v_mfma_f32_16x16x32_bf16 v[96:99], v[184:187], v[152:155], v[96:99]
	v_mfma_f32_16x16x32_bf16 v[84:87], v[176:179], v[160:163], v[84:87]
	v_mfma_f32_16x16x32_bf16 v[80:83], v[184:187], v[160:163], v[80:83]
	v_mfma_f32_16x16x32_bf16 v[68:71], v[176:179], v[168:171], v[68:71]
	v_mfma_f32_16x16x32_bf16 v[64:67], v[184:187], v[168:171], v[64:67]
	v_mfma_f32_16x16x32_bf16 v[116:119], v[180:183], v[148:151], v[116:119]
	v_mfma_f32_16x16x32_bf16 v[112:115], v[188:191], v[148:151], v[112:115]
	v_mfma_f32_16x16x32_bf16 v[100:103], v[180:183], v[156:159], v[100:103]
	v_mfma_f32_16x16x32_bf16 v[96:99], v[188:191], v[156:159], v[96:99]
	v_mfma_f32_16x16x32_bf16 v[84:87], v[180:183], v[164:167], v[84:87]
	v_mfma_f32_16x16x32_bf16 v[80:83], v[188:191], v[164:167], v[80:83]
	v_mfma_f32_16x16x32_bf16 v[68:71], v[180:183], v[172:175], v[68:71]
	v_mfma_f32_16x16x32_bf16 v[64:67], v[188:191], v[172:175], v[64:67]
	s_setprio 0
	s_mov_b32 m0, s41
	v_lshl_add_u64 v[210:211], s[36:37], 0, v[194:195]
	s_barrier
	ds_read_b128 v[144:147], v245 offset:16384
	ds_read_b128 v[148:151], v245 offset:17408
	ds_read_b128 v[152:155], v245 offset:18432
	ds_read_b128 v[156:159], v245 offset:19456
	ds_read_b128 v[160:163], v245 offset:20480
	ds_read_b128 v[164:167], v245 offset:21504
	ds_read_b128 v[168:171], v245 offset:22528
	ds_read_b128 v[172:175], v245 offset:23552
	global_load_lds_dwordx4 v[210:211], off
	v_lshl_add_u64 v[212:213], s[36:37], 0, v[198:199]
	s_mov_b32 m0, s42
	s_nop 0
	global_load_lds_dwordx4 v[212:213], off
	s_barrier
	s_waitcnt lgkmcnt(0)
	s_setprio 1
	s_waitcnt lgkmcnt(0)
	v_mfma_f32_16x16x32_bf16 v[60:63], v[120:123], v[144:147], v[60:63]
	v_mfma_f32_16x16x32_bf16 v[56:59], v[132:135], v[144:147], v[56:59]
	v_mfma_f32_16x16x32_bf16 v[44:47], v[120:123], v[152:155], v[44:47]
	v_mfma_f32_16x16x32_bf16 v[40:43], v[132:135], v[152:155], v[40:43]
	v_mfma_f32_16x16x32_bf16 v[28:31], v[120:123], v[160:163], v[28:31]
	v_mfma_f32_16x16x32_bf16 v[24:27], v[132:135], v[160:163], v[24:27]
	v_mfma_f32_16x16x32_bf16 v[12:15], v[120:123], v[168:171], v[12:15]
	v_mfma_f32_16x16x32_bf16 v[8:11], v[132:135], v[168:171], v[8:11]
	v_mfma_f32_16x16x32_bf16 v[60:63], v[124:127], v[148:151], v[60:63]
	v_mfma_f32_16x16x32_bf16 v[56:59], v[140:143], v[148:151], v[56:59]
	v_mfma_f32_16x16x32_bf16 v[44:47], v[124:127], v[156:159], v[44:47]
	v_mfma_f32_16x16x32_bf16 v[40:43], v[140:143], v[156:159], v[40:43]
	v_mfma_f32_16x16x32_bf16 v[28:31], v[124:127], v[164:167], v[28:31]
	v_mfma_f32_16x16x32_bf16 v[24:27], v[140:143], v[164:167], v[24:27]
	v_mfma_f32_16x16x32_bf16 v[12:15], v[124:127], v[172:175], v[12:15]
	v_mfma_f32_16x16x32_bf16 v[8:11], v[140:143], v[172:175], v[8:11]
	s_setprio 0
	s_barrier
	s_add_u32 s64, s34, 0xb0000
	s_addc_u32 s65, s35, 0
	s_add_i32 s66, s52, s40
	v_lshl_add_u64 v[120:121], s[64:65], 0, v[196:197]
	s_mov_b32 m0, s66
	s_nop 0
	global_load_lds_dwordx4 v[120:121], off
	v_lshl_add_u64 v[120:121], s[64:65], 0, v[200:201]
	s_add_i32 m0, s66, 0x2000
	s_nop 0
	global_load_lds_dwordx4 v[120:121], off
	s_waitcnt vmcnt(6)
	s_barrier
	s_setprio 1
	v_mfma_f32_16x16x32_bf16 v[52:55], v[176:179], v[144:147], v[52:55]
	v_mfma_f32_16x16x32_bf16 v[48:51], v[184:187], v[144:147], v[48:51]
	v_mfma_f32_16x16x32_bf16 v[36:39], v[176:179], v[152:155], v[36:39]
	v_mfma_f32_16x16x32_bf16 v[32:35], v[184:187], v[152:155], v[32:35]
	v_mfma_f32_16x16x32_bf16 v[20:23], v[176:179], v[160:163], v[20:23]
	v_mfma_f32_16x16x32_bf16 v[16:19], v[184:187], v[160:163], v[16:19]
	v_mfma_f32_16x16x32_bf16 v[4:7], v[176:179], v[168:171], v[4:7]
	v_mfma_f32_16x16x32_bf16 v[0:3], v[184:187], v[168:171], v[0:3]
	v_mfma_f32_16x16x32_bf16 v[52:55], v[180:183], v[148:151], v[52:55]
	v_mfma_f32_16x16x32_bf16 v[48:51], v[188:191], v[148:151], v[48:51]
	v_mfma_f32_16x16x32_bf16 v[36:39], v[180:183], v[156:159], v[36:39]
	v_mfma_f32_16x16x32_bf16 v[32:35], v[188:191], v[156:159], v[32:35]
	v_mfma_f32_16x16x32_bf16 v[20:23], v[180:183], v[164:167], v[20:23]
	v_mfma_f32_16x16x32_bf16 v[16:19], v[188:191], v[164:167], v[16:19]
	v_mfma_f32_16x16x32_bf16 v[4:7], v[180:183], v[172:175], v[4:7]
	v_mfma_f32_16x16x32_bf16 v[0:3], v[188:191], v[172:175], v[0:3]
	s_setprio 0
	s_add_i32 s64, 0, 0x18000
	v_add_u32_e32 v140, s64, v242
	s_barrier
	ds_read_b128 v[120:123], v140
	ds_read_b128 v[124:127], v140 offset:1024
	ds_read_b128 v[132:135], v140 offset:2048
	ds_read_b128 v[140:143], v140 offset:3072
	s_add_u32 s36, s36, 0xb0000
	s_addc_u32 s37, s37, 0
	s_mov_b32 m0, s43
	v_lshl_add_u64 v[176:177], s[36:37], 0, v[194:195]
	ds_read_b128 v[144:147], v245 offset:32768
	ds_read_b128 v[148:151], v245 offset:33792
	ds_read_b128 v[152:155], v245 offset:34816
	ds_read_b128 v[156:159], v245 offset:35840
	ds_read_b128 v[160:163], v245 offset:36864
	ds_read_b128 v[164:167], v245 offset:37888
	ds_read_b128 v[168:171], v245 offset:38912
	ds_read_b128 v[172:175], v245 offset:39936
	global_load_lds_dwordx4 v[176:177], off
	v_lshl_add_u64 v[176:177], s[36:37], 0, v[198:199]
	s_mov_b32 m0, s44
	s_nop 0
	global_load_lds_dwordx4 v[176:177], off
	s_waitcnt lgkmcnt(8)
	s_barrier
	s_waitcnt lgkmcnt(0)
	s_setprio 1
	s_waitcnt lgkmcnt(0)
	v_mfma_f32_16x16x32_bf16 v[136:139], v[120:123], v[144:147], v[136:139]
	v_mfma_f32_16x16x32_bf16 v[128:131], v[132:135], v[144:147], v[128:131]
	v_mfma_f32_16x16x32_bf16 v[108:111], v[120:123], v[152:155], v[108:111]
	v_mfma_f32_16x16x32_bf16 v[104:107], v[132:135], v[152:155], v[104:107]
	v_mfma_f32_16x16x32_bf16 v[92:95], v[120:123], v[160:163], v[92:95]
	v_mfma_f32_16x16x32_bf16 v[88:91], v[132:135], v[160:163], v[88:91]
	v_mfma_f32_16x16x32_bf16 v[76:79], v[120:123], v[168:171], v[76:79]
	v_mfma_f32_16x16x32_bf16 v[72:75], v[132:135], v[168:171], v[72:75]
	v_mfma_f32_16x16x32_bf16 v[136:139], v[124:127], v[148:151], v[136:139]
	v_mfma_f32_16x16x32_bf16 v[128:131], v[140:143], v[148:151], v[128:131]
	v_mfma_f32_16x16x32_bf16 v[108:111], v[124:127], v[156:159], v[108:111]
	v_mfma_f32_16x16x32_bf16 v[104:107], v[140:143], v[156:159], v[104:107]
	v_mfma_f32_16x16x32_bf16 v[92:95], v[124:127], v[164:167], v[92:95]
	v_mfma_f32_16x16x32_bf16 v[88:91], v[140:143], v[164:167], v[88:91]
	v_mfma_f32_16x16x32_bf16 v[76:79], v[124:127], v[172:175], v[76:79]
	v_mfma_f32_16x16x32_bf16 v[72:75], v[140:143], v[172:175], v[72:75]
	s_setprio 0
	s_barrier
	s_add_i32 s36, 0, 0x1c000
	s_add_i32 s37, s64, s40
	v_add_u32_e32 v188, s36, v242
	v_lshl_add_u64 v[206:207], v[206:207], 0, s[28:29]
	s_mov_b32 m0, s37
	ds_read_b128 v[176:179], v188
	ds_read_b128 v[180:183], v188 offset:1024
	ds_read_b128 v[184:187], v188 offset:2048
	ds_read_b128 v[188:191], v188 offset:3072
	global_load_lds_dwordx4 v[206:207], off
	v_lshl_add_u64 v[206:207], v[208:209], 0, s[28:29]
	s_add_i32 m0, s37, 0x2000
	s_nop 0
	global_load_lds_dwordx4 v[206:207], off
	s_barrier
	s_waitcnt lgkmcnt(0)
	s_setprio 1
	s_waitcnt lgkmcnt(0)
	v_mfma_f32_16x16x32_bf16 v[116:119], v[176:179], v[144:147], v[116:119]
	v_mfma_f32_16x16x32_bf16 v[112:115], v[184:187], v[144:147], v[112:115]
	v_mfma_f32_16x16x32_bf16 v[100:103], v[176:179], v[152:155], v[100:103]
	v_mfma_f32_16x16x32_bf16 v[96:99], v[184:187], v[152:155], v[96:99]
	v_mfma_f32_16x16x32_bf16 v[84:87], v[176:179], v[160:163], v[84:87]
	v_mfma_f32_16x16x32_bf16 v[80:83], v[184:187], v[160:163], v[80:83]
	v_mfma_f32_16x16x32_bf16 v[68:71], v[176:179], v[168:171], v[68:71]
	v_mfma_f32_16x16x32_bf16 v[64:67], v[184:187], v[168:171], v[64:67]
	v_mfma_f32_16x16x32_bf16 v[116:119], v[180:183], v[148:151], v[116:119]
	v_mfma_f32_16x16x32_bf16 v[112:115], v[188:191], v[148:151], v[112:115]
	v_mfma_f32_16x16x32_bf16 v[100:103], v[180:183], v[156:159], v[100:103]
	v_mfma_f32_16x16x32_bf16 v[96:99], v[188:191], v[156:159], v[96:99]
	v_mfma_f32_16x16x32_bf16 v[84:87], v[180:183], v[164:167], v[84:87]
	v_mfma_f32_16x16x32_bf16 v[80:83], v[188:191], v[164:167], v[80:83]
	v_mfma_f32_16x16x32_bf16 v[68:71], v[180:183], v[172:175], v[68:71]
	v_mfma_f32_16x16x32_bf16 v[64:67], v[188:191], v[172:175], v[64:67]
	s_setprio 0
	s_mov_b32 m0, s46
	v_lshl_add_u64 v[206:207], v[210:211], 0, s[28:29]
	s_barrier
	ds_read_b128 v[144:147], v245 offset:49152
	ds_read_b128 v[148:151], v245 offset:50176
	ds_read_b128 v[152:155], v245 offset:51200
	ds_read_b128 v[156:159], v245 offset:52224
	ds_read_b128 v[160:163], v245 offset:53248
	ds_read_b128 v[164:167], v245 offset:54272
	ds_read_b128 v[168:171], v245 offset:55296
	ds_read_b128 v[172:175], v245 offset:56320
	global_load_lds_dwordx4 v[206:207], off
	v_lshl_add_u64 v[206:207], v[212:213], 0, s[28:29]
	s_mov_b32 m0, s47
	s_nop 0
	global_load_lds_dwordx4 v[206:207], off
	s_barrier
	s_waitcnt lgkmcnt(0)
	s_setprio 1
	s_waitcnt lgkmcnt(0)
	v_mfma_f32_16x16x32_bf16 v[60:63], v[120:123], v[144:147], v[60:63]
	v_mfma_f32_16x16x32_bf16 v[56:59], v[132:135], v[144:147], v[56:59]
	v_mfma_f32_16x16x32_bf16 v[44:47], v[120:123], v[152:155], v[44:47]
	v_mfma_f32_16x16x32_bf16 v[40:43], v[132:135], v[152:155], v[40:43]
	v_mfma_f32_16x16x32_bf16 v[28:31], v[120:123], v[160:163], v[28:31]
	v_mfma_f32_16x16x32_bf16 v[24:27], v[132:135], v[160:163], v[24:27]
	v_mfma_f32_16x16x32_bf16 v[12:15], v[120:123], v[168:171], v[12:15]
	v_mfma_f32_16x16x32_bf16 v[8:11], v[132:135], v[168:171], v[8:11]
	v_mfma_f32_16x16x32_bf16 v[60:63], v[124:127], v[148:151], v[60:63]
	v_mfma_f32_16x16x32_bf16 v[56:59], v[140:143], v[148:151], v[56:59]
	v_mfma_f32_16x16x32_bf16 v[44:47], v[124:127], v[156:159], v[44:47]
	v_mfma_f32_16x16x32_bf16 v[40:43], v[140:143], v[156:159], v[40:43]
	v_mfma_f32_16x16x32_bf16 v[28:31], v[124:127], v[164:167], v[28:31]
	v_mfma_f32_16x16x32_bf16 v[24:27], v[140:143], v[164:167], v[24:27]
	v_mfma_f32_16x16x32_bf16 v[12:15], v[124:127], v[172:175], v[12:15]
	v_mfma_f32_16x16x32_bf16 v[8:11], v[140:143], v[172:175], v[8:11]
	s_setprio 0
	s_barrier
	s_add_u32 s34, s34, 0xb0080
	s_addc_u32 s35, s35, 0
	s_add_i32 s36, s36, s40
	v_lshl_add_u64 v[120:121], s[34:35], 0, v[196:197]
	s_mov_b32 m0, s36
	s_nop 0
	global_load_lds_dwordx4 v[120:121], off
	v_lshl_add_u64 v[120:121], s[34:35], 0, v[200:201]
	s_add_i32 m0, s36, 0x2000
	s_nop 0
	global_load_lds_dwordx4 v[120:121], off
	s_waitcnt vmcnt(6)
	s_barrier
	s_setprio 1
	v_mfma_f32_16x16x32_bf16 v[52:55], v[176:179], v[144:147], v[52:55]
	v_mfma_f32_16x16x32_bf16 v[48:51], v[184:187], v[144:147], v[48:51]
	v_mfma_f32_16x16x32_bf16 v[36:39], v[176:179], v[152:155], v[36:39]
	v_mfma_f32_16x16x32_bf16 v[32:35], v[184:187], v[152:155], v[32:35]
	v_mfma_f32_16x16x32_bf16 v[20:23], v[176:179], v[160:163], v[20:23]
	v_mfma_f32_16x16x32_bf16 v[16:19], v[184:187], v[160:163], v[16:19]
	v_mfma_f32_16x16x32_bf16 v[4:7], v[176:179], v[168:171], v[4:7]
	v_mfma_f32_16x16x32_bf16 v[0:3], v[184:187], v[168:171], v[0:3]
	v_mfma_f32_16x16x32_bf16 v[52:55], v[180:183], v[148:151], v[52:55]
	v_mfma_f32_16x16x32_bf16 v[48:51], v[188:191], v[148:151], v[48:51]
	v_mfma_f32_16x16x32_bf16 v[36:39], v[180:183], v[156:159], v[36:39]
	v_mfma_f32_16x16x32_bf16 v[32:35], v[188:191], v[156:159], v[32:35]
	v_mfma_f32_16x16x32_bf16 v[20:23], v[180:183], v[164:167], v[20:23]
	v_mfma_f32_16x16x32_bf16 v[16:19], v[188:191], v[164:167], v[16:19]
	v_mfma_f32_16x16x32_bf16 v[4:7], v[180:183], v[172:175], v[4:7]
	v_mfma_f32_16x16x32_bf16 v[0:3], v[188:191], v[172:175], v[0:3]
	s_setprio 0
	s_add_i32 s59, s59, 2
	s_add_u32 s30, s30, 0x100
	s_addc_u32 s31, s31, 0
	s_add_u32 s57, s57, 0x100
	s_addc_u32 s58, s58, 0
	s_cmp_gt_u32 s59, 41
	s_barrier
	s_cbranch_scc0 .LBB0_984
	v_lshl_or_b32 v206, s16, 8, v243
	v_lshl_add_u32 v236, s56, 8, v193
	v_ashrrev_i32_e32 v207, 31, v206
	v_lshlrev_b64 v[238:239], 1, v[206:207]
	v_ashrrev_i32_e32 v237, 31, v236
	v_lshl_add_u64 v[124:125], s[24:25], 0, v[238:239]
	v_lshlrev_b64 v[240:241], 11, v[236:237]
	v_lshl_add_u64 v[120:121], v[124:125], 0, v[240:241]
	global_load_dwordx4 v[188:191], v[120:121], off
	global_load_dwordx4 v[184:187], v[120:121], off offset:256
	v_or_b32_e32 v232, 16, v236
	v_ashrrev_i32_e32 v233, 31, v232
	v_or_b32_e32 v228, 32, v236
	v_lshlrev_b64 v[234:235], 11, v[232:233]
	v_ashrrev_i32_e32 v229, 31, v228
	v_or_b32_e32 v224, 48, v236
	v_lshl_add_u64 v[120:121], v[124:125], 0, v[234:235]
	v_lshlrev_b64 v[230:231], 11, v[228:229]
	v_ashrrev_i32_e32 v225, 31, v224
	v_add_u32_e32 v220, 0x80, v236
	global_load_dwordx4 v[180:183], v[120:121], off
	global_load_dwordx4 v[176:179], v[120:121], off offset:256
	v_lshl_add_u64 v[120:121], v[124:125], 0, v[230:231]
	v_lshlrev_b64 v[226:227], 11, v[224:225]
	v_ashrrev_i32_e32 v221, 31, v220
	v_add_u32_e32 v216, 0x90, v236
	global_load_dwordx4 v[172:175], v[120:121], off
	global_load_dwordx4 v[168:171], v[120:121], off offset:256
	v_lshl_add_u64 v[120:121], v[124:125], 0, v[226:227]
	v_lshlrev_b64 v[222:223], 11, v[220:221]
	v_ashrrev_i32_e32 v217, 31, v216
	v_add_u32_e32 v212, 0xa0, v236
	v_add_u32_e32 v208, 0xb0, v236
	global_load_dwordx4 v[164:167], v[120:121], off
	global_load_dwordx4 v[160:163], v[120:121], off offset:256
	v_lshl_add_u64 v[120:121], v[124:125], 0, v[222:223]
	v_lshlrev_b64 v[218:219], 11, v[216:217]
	v_ashrrev_i32_e32 v213, 31, v212
	v_ashrrev_i32_e32 v209, 31, v208
	global_load_dwordx4 v[156:159], v[120:121], off
	global_load_dwordx4 v[152:155], v[120:121], off offset:256
	v_lshl_add_u64 v[120:121], v[124:125], 0, v[218:219]
	v_lshlrev_b64 v[214:215], 11, v[212:213]
	v_lshlrev_b64 v[210:211], 11, v[208:209]
	global_load_dwordx4 v[148:151], v[120:121], off
	global_load_dwordx4 v[144:147], v[120:121], off offset:256
	v_lshl_add_u64 v[120:121], v[124:125], 0, v[214:215]
	v_lshl_add_u64 v[124:125], v[124:125], 0, v[210:211]
	global_load_dwordx4 v[132:135], v[120:121], off
	s_nop 0
	global_load_dwordx4 v[120:123], v[120:121], off offset:256
	s_nop 0
	global_load_dwordx4 v[140:143], v[124:125], off
	s_nop 0
	global_load_dwordx4 v[124:127], v[124:125], off offset:256
	v_and_b32_e32 v249, 64, v247
	v_xor_b32_e32 v248, 16, v247
	v_add_u32_e32 v249, 64, v249
	v_cmp_lt_i32_e32 vcc, v248, v249
	v_xor_b32_e32 v250, 32, v247
	s_lshl_b32 s30, s16, 2
	v_cndmask_b32_e32 v248, v247, v248, vcc
	v_cmp_lt_i32_e32 vcc, v250, v249
	v_lshlrev_b32_e32 v248, 2, v248
	s_ashr_i32 s31, s30, 31
	v_cndmask_b32_e32 v249, v247, v250, vcc
	v_lshlrev_b32_e32 v249, 2, v249
	s_waitcnt vmcnt(0)
	v_lshlrev_b32_e32 v250, 16, v188
	v_and_b32_e32 v251, 0xffff0000, v188
	v_lshlrev_b32_e32 v188, 16, v189
	v_and_b32_e32 v189, 0xffff0000, v189
	v_lshlrev_b32_e32 v252, 16, v190
	v_and_b32_e32 v253, 0xffff0000, v190
	v_lshlrev_b32_e32 v190, 16, v191
	v_and_b32_e32 v191, 0xffff0000, v191
	v_pk_add_f32 v[138:139], v[138:139], v[188:189]
	v_pk_add_f32 v[136:137], v[136:137], v[250:251]
	v_pk_add_f32 v[188:189], v[130:131], v[190:191]
	v_pk_add_f32 v[130:131], v[128:129], v[252:253]
	v_mul_f32_e32 v128, v137, v137
	v_mul_f32_e32 v129, v139, v139
	v_fmac_f32_e32 v128, v136, v136
	v_fmac_f32_e32 v129, v138, v138
	v_add_f32_e32 v128, v128, v129
	v_mul_f32_e32 v129, v131, v131
	v_mul_f32_e32 v190, v189, v189
	v_fmac_f32_e32 v129, v130, v130
	v_fmac_f32_e32 v190, v188, v188
	v_add_f32_e32 v129, v129, v190
	v_add_f32_e32 v190, v128, v129
	v_cvt_pk_bf16_f32 v128, v136, v137
	v_lshl_add_u64 v[136:137], s[24:25], 0, v[240:241]
	v_cvt_pk_bf16_f32 v129, v138, v139
	v_cvt_pk_bf16_f32 v130, v130, v131
	v_cvt_pk_bf16_f32 v131, v188, v189
	v_lshl_add_u64 v[136:137], v[136:137], 0, v[238:239]
	global_store_dwordx4 v[136:137], v[128:131], off sc1
	v_lshlrev_b32_e32 v138, 16, v186
	v_and_b32_e32 v139, 0xffff0000, v186
	v_lshlrev_b32_e32 v128, 16, v184
	v_and_b32_e32 v129, 0xffff0000, v184
	v_lshlrev_b32_e32 v130, 16, v185
	v_and_b32_e32 v131, 0xffff0000, v185
	v_lshlrev_b32_e32 v184, 16, v187
	v_and_b32_e32 v185, 0xffff0000, v187
	v_pk_add_f32 v[118:119], v[118:119], v[130:131]
	v_pk_add_f32 v[116:117], v[116:117], v[128:129]
	v_pk_add_f32 v[128:129], v[114:115], v[184:185]
	v_pk_add_f32 v[114:115], v[112:113], v[138:139]
	v_mul_f32_e32 v112, v117, v117
	v_mul_f32_e32 v113, v119, v119
	v_fmac_f32_e32 v112, v116, v116
	v_fmac_f32_e32 v113, v118, v118
	v_add_f32_e32 v112, v112, v113
	v_mul_f32_e32 v113, v115, v115
	v_mul_f32_e32 v130, v129, v129
	v_fmac_f32_e32 v113, v114, v114
	v_fmac_f32_e32 v130, v128, v128
	v_add_f32_e32 v113, v113, v130
	v_add_f32_e32 v112, v112, v113
	v_add_f32_e32 v130, v190, v112
	v_cvt_pk_bf16_f32 v112, v116, v117
	v_cvt_pk_bf16_f32 v113, v118, v119
	v_cvt_pk_bf16_f32 v114, v114, v115
	v_cvt_pk_bf16_f32 v115, v128, v129
	global_store_dwordx4 v[136:137], v[112:115], off offset:256 sc1
	s_nop 1
	v_mov_b32_e32 v112, v130
	s_nop 1
	v_permlane16_swap_b32_e32 v130, v112
	s_waitcnt lgkmcnt(0)
	v_add_f32_e32 v112, v130, v112
	v_mov_b32_e32 v113, v112
	s_nop 1
	v_permlane32_swap_b32_e32 v112, v113
	s_and_saveexec_b64 s[34:35], s[6:7]
	s_cbranch_execz .LBB0_987
	v_lshlrev_b64 v[114:115], 6, v[236:237]
	v_lshl_add_u64 v[114:115], s[26:27], 0, v[114:115]
	v_lshl_add_u64 v[114:115], s[30:31], 2, v[114:115]
	s_lshl_b32 s16, s45, 2
	v_lshl_add_u64 v[114:115], v[114:115], 0, s[16:17]
	s_waitcnt lgkmcnt(0)
	v_add_f32_e32 v112, v112, v113
	global_store_dword v[114:115], v112, off
.LBB0_987:
	s_or_b64 exec, exec, s[34:35]
	v_lshlrev_b32_e32 v112, 16, v180
	s_waitcnt lgkmcnt(0)
	v_and_b32_e32 v113, 0xffff0000, v180
	v_lshlrev_b32_e32 v114, 16, v181
	v_and_b32_e32 v115, 0xffff0000, v181
	v_lshlrev_b32_e32 v116, 16, v182
	v_and_b32_e32 v117, 0xffff0000, v182
	v_lshlrev_b32_e32 v118, 16, v183
	v_and_b32_e32 v119, 0xffff0000, v183
	v_pk_add_f32 v[110:111], v[110:111], v[114:115]
	v_pk_add_f32 v[108:109], v[108:109], v[112:113]
	v_pk_add_f32 v[112:113], v[106:107], v[118:119]
	v_pk_add_f32 v[106:107], v[104:105], v[116:117]
	v_mul_f32_e32 v104, v109, v109
	v_mul_f32_e32 v105, v111, v111
	v_fmac_f32_e32 v104, v108, v108
	v_fmac_f32_e32 v105, v110, v110
	v_add_f32_e32 v104, v104, v105
	v_mul_f32_e32 v105, v107, v107
	v_mul_f32_e32 v114, v113, v113
	v_fmac_f32_e32 v105, v106, v106
	v_fmac_f32_e32 v114, v112, v112
	v_add_f32_e32 v105, v105, v114
	v_add_f32_e32 v116, v104, v105
	v_cvt_pk_bf16_f32 v104, v108, v109
	v_cvt_pk_bf16_f32 v105, v110, v111
	v_lshlrev_b32_e32 v108, 16, v176
	v_and_b32_e32 v109, 0xffff0000, v176
	v_lshlrev_b32_e32 v110, 16, v177
	v_and_b32_e32 v111, 0xffff0000, v177
	v_cvt_pk_bf16_f32 v106, v106, v107
	v_cvt_pk_bf16_f32 v107, v112, v113
	v_lshlrev_b32_e32 v112, 16, v178
	v_and_b32_e32 v113, 0xffff0000, v178
	v_pk_add_f32 v[102:103], v[102:103], v[110:111]
	v_pk_add_f32 v[100:101], v[100:101], v[108:109]
	v_lshlrev_b32_e32 v114, 16, v179
	v_and_b32_e32 v115, 0xffff0000, v179
	v_pk_add_f32 v[110:111], v[96:97], v[112:113]
	v_mul_f32_e32 v96, v101, v101
	v_mul_f32_e32 v97, v103, v103
	v_pk_add_f32 v[108:109], v[98:99], v[114:115]
	v_fmac_f32_e32 v96, v100, v100
	v_fmac_f32_e32 v97, v102, v102
	v_add_f32_e32 v96, v96, v97
	v_mul_f32_e32 v97, v111, v111
	v_mul_f32_e32 v98, v109, v109
	v_fmac_f32_e32 v97, v110, v110
	v_fmac_f32_e32 v98, v108, v108
	v_add_f32_e32 v97, v97, v98
	v_add_f32_e32 v96, v96, v97
	v_add_f32_e32 v99, v116, v96
	v_mov_b32_e32 v114, v99
	s_nop 1
	v_permlane16_swap_b32_e32 v99, v114
	v_lshl_add_u64 v[96:97], s[24:25], 0, v[234:235]
	v_lshl_add_u64 v[112:113], v[206:207], 1, v[96:97]
	v_cvt_pk_bf16_f32 v98, v100, v101
	v_cvt_pk_bf16_f32 v100, v110, v111
	s_waitcnt lgkmcnt(0)
	v_add_f32_e32 v96, v99, v114
	v_mov_b32_e32 v97, v96
	s_nop 1
	v_permlane32_swap_b32_e32 v96, v97
	v_cvt_pk_bf16_f32 v99, v102, v103
	v_cvt_pk_bf16_f32 v101, v108, v109
	global_store_dwordx4 v[112:113], v[104:107], off sc1
	global_store_dwordx4 v[112:113], v[98:101], off offset:256 sc1
	s_and_saveexec_b64 s[34:35], s[6:7]
	s_cbranch_execz .LBB0_989
	v_lshlrev_b64 v[98:99], 6, v[232:233]
	v_lshl_add_u64 v[98:99], s[26:27], 0, v[98:99]
	v_lshl_add_u64 v[98:99], s[30:31], 2, v[98:99]
	s_lshl_b32 s16, s45, 2
	v_lshl_add_u64 v[98:99], v[98:99], 0, s[16:17]
	s_waitcnt lgkmcnt(0)
	v_add_f32_e32 v96, v96, v97
	global_store_dword v[98:99], v96, off
.LBB0_989:
	s_or_b64 exec, exec, s[34:35]
	v_lshlrev_b32_e32 v96, 16, v172
	s_waitcnt lgkmcnt(0)
	v_and_b32_e32 v97, 0xffff0000, v172
	v_lshlrev_b32_e32 v98, 16, v173
	v_and_b32_e32 v99, 0xffff0000, v173
	v_lshlrev_b32_e32 v100, 16, v174
	v_and_b32_e32 v101, 0xffff0000, v174
	v_lshlrev_b32_e32 v102, 16, v175
	v_and_b32_e32 v103, 0xffff0000, v175
	v_pk_add_f32 v[94:95], v[94:95], v[98:99]
	v_pk_add_f32 v[92:93], v[92:93], v[96:97]
	v_pk_add_f32 v[96:97], v[90:91], v[102:103]
	v_pk_add_f32 v[90:91], v[88:89], v[100:101]
	v_mul_f32_e32 v88, v93, v93
	v_mul_f32_e32 v89, v95, v95
	v_fmac_f32_e32 v88, v92, v92
	v_fmac_f32_e32 v89, v94, v94
	v_add_f32_e32 v88, v88, v89
	v_mul_f32_e32 v89, v91, v91
	v_mul_f32_e32 v98, v97, v97
	v_fmac_f32_e32 v89, v90, v90
	v_fmac_f32_e32 v98, v96, v96
	v_add_f32_e32 v89, v89, v98
	v_add_f32_e32 v100, v88, v89
	v_cvt_pk_bf16_f32 v88, v92, v93
	v_cvt_pk_bf16_f32 v89, v94, v95
	v_lshlrev_b32_e32 v92, 16, v168
	v_and_b32_e32 v93, 0xffff0000, v168
	v_lshlrev_b32_e32 v94, 16, v169
	v_and_b32_e32 v95, 0xffff0000, v169
	v_cvt_pk_bf16_f32 v90, v90, v91
	v_cvt_pk_bf16_f32 v91, v96, v97
	v_lshlrev_b32_e32 v96, 16, v170
	v_and_b32_e32 v97, 0xffff0000, v170
	v_pk_add_f32 v[86:87], v[86:87], v[94:95]
	v_pk_add_f32 v[84:85], v[84:85], v[92:93]
	v_lshlrev_b32_e32 v98, 16, v171
	v_and_b32_e32 v99, 0xffff0000, v171
	v_pk_add_f32 v[94:95], v[80:81], v[96:97]
	v_mul_f32_e32 v80, v85, v85
	v_mul_f32_e32 v81, v87, v87
	v_pk_add_f32 v[92:93], v[82:83], v[98:99]
	v_fmac_f32_e32 v80, v84, v84
	v_fmac_f32_e32 v81, v86, v86
	v_add_f32_e32 v80, v80, v81
	v_mul_f32_e32 v81, v95, v95
	v_mul_f32_e32 v82, v93, v93
	v_fmac_f32_e32 v81, v94, v94
	v_fmac_f32_e32 v82, v92, v92
	v_add_f32_e32 v81, v81, v82
	v_add_f32_e32 v80, v80, v81
	v_add_f32_e32 v83, v100, v80
	v_mov_b32_e32 v98, v83
	s_nop 1
	v_permlane16_swap_b32_e32 v83, v98
	v_lshl_add_u64 v[80:81], s[24:25], 0, v[230:231]
	v_lshl_add_u64 v[96:97], v[206:207], 1, v[80:81]
	v_cvt_pk_bf16_f32 v82, v84, v85
	v_cvt_pk_bf16_f32 v84, v94, v95
	s_waitcnt lgkmcnt(0)
	v_add_f32_e32 v80, v83, v98
	v_mov_b32_e32 v81, v80
	s_nop 1
	v_permlane32_swap_b32_e32 v80, v81
	v_cvt_pk_bf16_f32 v83, v86, v87
	v_cvt_pk_bf16_f32 v85, v92, v93
	global_store_dwordx4 v[96:97], v[88:91], off sc1
	global_store_dwordx4 v[96:97], v[82:85], off offset:256 sc1
	s_and_saveexec_b64 s[34:35], s[6:7]
	s_cbranch_execz .LBB0_991
	v_lshlrev_b64 v[82:83], 6, v[228:229]
	v_lshl_add_u64 v[82:83], s[26:27], 0, v[82:83]
	v_lshl_add_u64 v[82:83], s[30:31], 2, v[82:83]
	s_lshl_b32 s16, s45, 2
	v_lshl_add_u64 v[82:83], v[82:83], 0, s[16:17]
	s_waitcnt lgkmcnt(0)
	v_add_f32_e32 v80, v80, v81
	global_store_dword v[82:83], v80, off
.LBB0_991:
	s_or_b64 exec, exec, s[34:35]
	v_lshlrev_b32_e32 v80, 16, v164
	s_waitcnt lgkmcnt(0)
	v_and_b32_e32 v81, 0xffff0000, v164
	v_lshlrev_b32_e32 v82, 16, v165
	v_and_b32_e32 v83, 0xffff0000, v165
	v_lshlrev_b32_e32 v84, 16, v166
	v_and_b32_e32 v85, 0xffff0000, v166
	v_lshlrev_b32_e32 v86, 16, v167
	v_and_b32_e32 v87, 0xffff0000, v167
	v_pk_add_f32 v[78:79], v[78:79], v[82:83]
	v_pk_add_f32 v[76:77], v[76:77], v[80:81]
	v_pk_add_f32 v[80:81], v[74:75], v[86:87]
	v_pk_add_f32 v[74:75], v[72:73], v[84:85]
	v_mul_f32_e32 v72, v77, v77
	v_mul_f32_e32 v73, v79, v79
	v_fmac_f32_e32 v72, v76, v76
	v_fmac_f32_e32 v73, v78, v78
	v_add_f32_e32 v72, v72, v73
	v_mul_f32_e32 v73, v75, v75
	v_mul_f32_e32 v82, v81, v81
	v_fmac_f32_e32 v73, v74, v74
	v_fmac_f32_e32 v82, v80, v80
	v_add_f32_e32 v73, v73, v82
	v_add_f32_e32 v84, v72, v73
	v_cvt_pk_bf16_f32 v72, v76, v77
	v_cvt_pk_bf16_f32 v73, v78, v79
	v_lshlrev_b32_e32 v76, 16, v160
	v_and_b32_e32 v77, 0xffff0000, v160
	v_lshlrev_b32_e32 v78, 16, v161
	v_and_b32_e32 v79, 0xffff0000, v161
	v_cvt_pk_bf16_f32 v74, v74, v75
	v_cvt_pk_bf16_f32 v75, v80, v81
	v_lshlrev_b32_e32 v80, 16, v162
	v_and_b32_e32 v81, 0xffff0000, v162
	v_pk_add_f32 v[70:71], v[70:71], v[78:79]
	v_pk_add_f32 v[68:69], v[68:69], v[76:77]
	v_lshlrev_b32_e32 v82, 16, v163
	v_and_b32_e32 v83, 0xffff0000, v163
	v_pk_add_f32 v[78:79], v[64:65], v[80:81]
	v_mul_f32_e32 v64, v69, v69
	v_mul_f32_e32 v65, v71, v71
	v_pk_add_f32 v[76:77], v[66:67], v[82:83]
	v_fmac_f32_e32 v64, v68, v68
	v_fmac_f32_e32 v65, v70, v70
	v_add_f32_e32 v64, v64, v65
	v_mul_f32_e32 v65, v79, v79
	v_mul_f32_e32 v66, v77, v77
	v_fmac_f32_e32 v65, v78, v78
	v_fmac_f32_e32 v66, v76, v76
	v_add_f32_e32 v65, v65, v66
	v_add_f32_e32 v64, v64, v65
	v_add_f32_e32 v67, v84, v64
	v_mov_b32_e32 v82, v67
	s_nop 1
	v_permlane16_swap_b32_e32 v67, v82
	v_lshl_add_u64 v[64:65], s[24:25], 0, v[226:227]
	v_lshl_add_u64 v[80:81], v[206:207], 1, v[64:65]
	v_cvt_pk_bf16_f32 v66, v68, v69
	v_cvt_pk_bf16_f32 v68, v78, v79
	s_waitcnt lgkmcnt(0)
	v_add_f32_e32 v64, v67, v82
	v_mov_b32_e32 v65, v64
	s_nop 1
	v_permlane32_swap_b32_e32 v64, v65
	v_cvt_pk_bf16_f32 v67, v70, v71
	v_cvt_pk_bf16_f32 v69, v76, v77
	global_store_dwordx4 v[80:81], v[72:75], off sc1
	global_store_dwordx4 v[80:81], v[66:69], off offset:256 sc1
	s_and_saveexec_b64 s[34:35], s[6:7]
	s_cbranch_execz .LBB0_993
	v_lshlrev_b64 v[66:67], 6, v[224:225]
	v_lshl_add_u64 v[66:67], s[26:27], 0, v[66:67]
	v_lshl_add_u64 v[66:67], s[30:31], 2, v[66:67]
	s_lshl_b32 s16, s45, 2
	v_lshl_add_u64 v[66:67], v[66:67], 0, s[16:17]
	s_waitcnt lgkmcnt(0)
	v_add_f32_e32 v64, v64, v65
	global_store_dword v[66:67], v64, off
.LBB0_993:
	s_or_b64 exec, exec, s[34:35]
	v_lshlrev_b32_e32 v64, 16, v156
	s_waitcnt lgkmcnt(0)
	v_and_b32_e32 v65, 0xffff0000, v156
	v_lshlrev_b32_e32 v66, 16, v157
	v_and_b32_e32 v67, 0xffff0000, v157
	v_lshlrev_b32_e32 v68, 16, v158
	v_and_b32_e32 v69, 0xffff0000, v158
	v_lshlrev_b32_e32 v70, 16, v159
	v_and_b32_e32 v71, 0xffff0000, v159
	v_pk_add_f32 v[62:63], v[62:63], v[66:67]
	v_pk_add_f32 v[60:61], v[60:61], v[64:65]
	v_pk_add_f32 v[64:65], v[58:59], v[70:71]
	v_pk_add_f32 v[58:59], v[56:57], v[68:69]
	v_mul_f32_e32 v56, v61, v61
	v_mul_f32_e32 v57, v63, v63
	v_fmac_f32_e32 v56, v60, v60
	v_fmac_f32_e32 v57, v62, v62
	v_add_f32_e32 v56, v56, v57
	v_mul_f32_e32 v57, v59, v59
	v_mul_f32_e32 v66, v65, v65
	v_fmac_f32_e32 v57, v58, v58
	v_fmac_f32_e32 v66, v64, v64
	v_add_f32_e32 v57, v57, v66
	v_add_f32_e32 v68, v56, v57
	v_cvt_pk_bf16_f32 v56, v60, v61
	v_cvt_pk_bf16_f32 v57, v62, v63
	v_lshlrev_b32_e32 v60, 16, v152
	v_and_b32_e32 v61, 0xffff0000, v152
	v_lshlrev_b32_e32 v62, 16, v153
	v_and_b32_e32 v63, 0xffff0000, v153
	v_cvt_pk_bf16_f32 v58, v58, v59
	v_cvt_pk_bf16_f32 v59, v64, v65
	v_lshlrev_b32_e32 v64, 16, v154
	v_and_b32_e32 v65, 0xffff0000, v154
	v_pk_add_f32 v[54:55], v[54:55], v[62:63]
	v_pk_add_f32 v[52:53], v[52:53], v[60:61]
	v_lshlrev_b32_e32 v66, 16, v155
	v_and_b32_e32 v67, 0xffff0000, v155
	v_pk_add_f32 v[62:63], v[48:49], v[64:65]
	v_mul_f32_e32 v48, v53, v53
	v_mul_f32_e32 v49, v55, v55
	v_pk_add_f32 v[60:61], v[50:51], v[66:67]
	v_fmac_f32_e32 v48, v52, v52
	v_fmac_f32_e32 v49, v54, v54
	v_add_f32_e32 v48, v48, v49
	v_mul_f32_e32 v49, v63, v63
	v_mul_f32_e32 v50, v61, v61
	v_fmac_f32_e32 v49, v62, v62
	v_fmac_f32_e32 v50, v60, v60
	v_add_f32_e32 v49, v49, v50
	v_add_f32_e32 v48, v48, v49
	v_add_f32_e32 v51, v68, v48
	v_mov_b32_e32 v66, v51
	s_nop 1
	v_permlane16_swap_b32_e32 v51, v66
	v_lshl_add_u64 v[48:49], s[24:25], 0, v[222:223]
	v_lshl_add_u64 v[64:65], v[206:207], 1, v[48:49]
	v_cvt_pk_bf16_f32 v50, v52, v53
	v_cvt_pk_bf16_f32 v52, v62, v63
	s_waitcnt lgkmcnt(0)
	v_add_f32_e32 v48, v51, v66
	v_mov_b32_e32 v49, v48
	s_nop 1
	v_permlane32_swap_b32_e32 v48, v49
	v_cvt_pk_bf16_f32 v51, v54, v55
	v_cvt_pk_bf16_f32 v53, v60, v61
	global_store_dwordx4 v[64:65], v[56:59], off sc1
	global_store_dwordx4 v[64:65], v[50:53], off offset:256 sc1
	s_and_saveexec_b64 s[34:35], s[6:7]
	s_cbranch_execz .LBB0_995
	v_lshlrev_b64 v[50:51], 6, v[220:221]
	v_lshl_add_u64 v[50:51], s[26:27], 0, v[50:51]
	v_lshl_add_u64 v[50:51], s[30:31], 2, v[50:51]
	s_lshl_b32 s16, s45, 2
	v_lshl_add_u64 v[50:51], v[50:51], 0, s[16:17]
	s_waitcnt lgkmcnt(0)
	v_add_f32_e32 v48, v48, v49
	global_store_dword v[50:51], v48, off
.LBB0_995:
	s_or_b64 exec, exec, s[34:35]
	v_lshlrev_b32_e32 v48, 16, v148
	s_waitcnt lgkmcnt(0)
	v_and_b32_e32 v49, 0xffff0000, v148
	v_lshlrev_b32_e32 v50, 16, v149
	v_and_b32_e32 v51, 0xffff0000, v149
	v_lshlrev_b32_e32 v52, 16, v150
	v_and_b32_e32 v53, 0xffff0000, v150
	v_lshlrev_b32_e32 v54, 16, v151
	v_and_b32_e32 v55, 0xffff0000, v151
	v_pk_add_f32 v[46:47], v[46:47], v[50:51]
	v_pk_add_f32 v[44:45], v[44:45], v[48:49]
	v_pk_add_f32 v[48:49], v[42:43], v[54:55]
	v_pk_add_f32 v[42:43], v[40:41], v[52:53]
	v_mul_f32_e32 v40, v45, v45
	v_mul_f32_e32 v41, v47, v47
	v_fmac_f32_e32 v40, v44, v44
	v_fmac_f32_e32 v41, v46, v46
	v_add_f32_e32 v40, v40, v41
	v_mul_f32_e32 v41, v43, v43
	v_mul_f32_e32 v50, v49, v49
	v_fmac_f32_e32 v41, v42, v42
	v_fmac_f32_e32 v50, v48, v48
	v_add_f32_e32 v41, v41, v50
	v_add_f32_e32 v52, v40, v41
	v_cvt_pk_bf16_f32 v40, v44, v45
	v_cvt_pk_bf16_f32 v41, v46, v47
	v_lshlrev_b32_e32 v44, 16, v144
	v_and_b32_e32 v45, 0xffff0000, v144
	v_lshlrev_b32_e32 v46, 16, v145
	v_and_b32_e32 v47, 0xffff0000, v145
	v_cvt_pk_bf16_f32 v42, v42, v43
	v_cvt_pk_bf16_f32 v43, v48, v49
	v_lshlrev_b32_e32 v48, 16, v146
	v_and_b32_e32 v49, 0xffff0000, v146
	v_pk_add_f32 v[38:39], v[38:39], v[46:47]
	v_pk_add_f32 v[36:37], v[36:37], v[44:45]
	v_lshlrev_b32_e32 v50, 16, v147
	v_and_b32_e32 v51, 0xffff0000, v147
	v_pk_add_f32 v[46:47], v[32:33], v[48:49]
	v_mul_f32_e32 v32, v37, v37
	v_mul_f32_e32 v33, v39, v39
	v_pk_add_f32 v[44:45], v[34:35], v[50:51]
	v_fmac_f32_e32 v32, v36, v36
	v_fmac_f32_e32 v33, v38, v38
	v_add_f32_e32 v32, v32, v33
	v_mul_f32_e32 v33, v47, v47
	v_mul_f32_e32 v34, v45, v45
	v_fmac_f32_e32 v33, v46, v46
	v_fmac_f32_e32 v34, v44, v44
	v_add_f32_e32 v33, v33, v34
	v_add_f32_e32 v32, v32, v33
	v_add_f32_e32 v35, v52, v32
	v_mov_b32_e32 v50, v35
	s_nop 1
	v_permlane16_swap_b32_e32 v35, v50
	v_lshl_add_u64 v[32:33], s[24:25], 0, v[218:219]
	v_lshl_add_u64 v[48:49], v[206:207], 1, v[32:33]
	v_cvt_pk_bf16_f32 v34, v36, v37
	v_cvt_pk_bf16_f32 v36, v46, v47
	s_waitcnt lgkmcnt(0)
	v_add_f32_e32 v32, v35, v50
	v_mov_b32_e32 v33, v32
	s_nop 1
	v_permlane32_swap_b32_e32 v32, v33
	v_cvt_pk_bf16_f32 v35, v38, v39
	v_cvt_pk_bf16_f32 v37, v44, v45
	global_store_dwordx4 v[48:49], v[40:43], off sc1
	global_store_dwordx4 v[48:49], v[34:37], off offset:256 sc1
	s_and_saveexec_b64 s[34:35], s[6:7]
	s_cbranch_execz .LBB0_997
	v_lshlrev_b64 v[34:35], 6, v[216:217]
	v_lshl_add_u64 v[34:35], s[26:27], 0, v[34:35]
	v_lshl_add_u64 v[34:35], s[30:31], 2, v[34:35]
	s_lshl_b32 s16, s45, 2
	v_lshl_add_u64 v[34:35], v[34:35], 0, s[16:17]
	s_waitcnt lgkmcnt(0)
	v_add_f32_e32 v32, v32, v33
	global_store_dword v[34:35], v32, off
.LBB0_997:
	s_or_b64 exec, exec, s[34:35]
	v_lshlrev_b32_e32 v32, 16, v132
	s_waitcnt lgkmcnt(0)
	v_and_b32_e32 v33, 0xffff0000, v132
	v_lshlrev_b32_e32 v34, 16, v133
	v_and_b32_e32 v35, 0xffff0000, v133
	v_lshlrev_b32_e32 v36, 16, v134
	v_and_b32_e32 v37, 0xffff0000, v134
	v_lshlrev_b32_e32 v38, 16, v135
	v_and_b32_e32 v39, 0xffff0000, v135
	v_pk_add_f32 v[30:31], v[30:31], v[34:35]
	v_pk_add_f32 v[28:29], v[28:29], v[32:33]
	v_pk_add_f32 v[32:33], v[26:27], v[38:39]
	v_pk_add_f32 v[26:27], v[24:25], v[36:37]
	v_mul_f32_e32 v24, v29, v29
	v_mul_f32_e32 v25, v31, v31
	v_fmac_f32_e32 v24, v28, v28
	v_fmac_f32_e32 v25, v30, v30
	v_add_f32_e32 v24, v24, v25
	v_mul_f32_e32 v25, v27, v27
	v_mul_f32_e32 v34, v33, v33
	v_fmac_f32_e32 v25, v26, v26
	v_fmac_f32_e32 v34, v32, v32
	v_add_f32_e32 v25, v25, v34
	v_add_f32_e32 v36, v24, v25
	v_cvt_pk_bf16_f32 v24, v28, v29
	v_cvt_pk_bf16_f32 v25, v30, v31
	v_lshlrev_b32_e32 v28, 16, v120
	v_and_b32_e32 v29, 0xffff0000, v120
	v_lshlrev_b32_e32 v30, 16, v121
	v_and_b32_e32 v31, 0xffff0000, v121
	v_cvt_pk_bf16_f32 v26, v26, v27
	v_cvt_pk_bf16_f32 v27, v32, v33
	v_lshlrev_b32_e32 v32, 16, v122
	v_and_b32_e32 v33, 0xffff0000, v122
	v_pk_add_f32 v[22:23], v[22:23], v[30:31]
	v_pk_add_f32 v[20:21], v[20:21], v[28:29]
	v_lshlrev_b32_e32 v34, 16, v123
	v_and_b32_e32 v35, 0xffff0000, v123
	v_pk_add_f32 v[30:31], v[16:17], v[32:33]
	v_mul_f32_e32 v16, v21, v21
	v_mul_f32_e32 v17, v23, v23
	v_pk_add_f32 v[28:29], v[18:19], v[34:35]
	v_fmac_f32_e32 v16, v20, v20
	v_fmac_f32_e32 v17, v22, v22
	v_add_f32_e32 v16, v16, v17
	v_mul_f32_e32 v17, v31, v31
	v_mul_f32_e32 v18, v29, v29
	v_fmac_f32_e32 v17, v30, v30
	v_fmac_f32_e32 v18, v28, v28
	v_add_f32_e32 v17, v17, v18
	v_add_f32_e32 v16, v16, v17
	v_add_f32_e32 v19, v36, v16
	v_mov_b32_e32 v34, v19
	s_nop 1
	v_permlane16_swap_b32_e32 v19, v34
	v_lshl_add_u64 v[16:17], s[24:25], 0, v[214:215]
	v_lshl_add_u64 v[32:33], v[206:207], 1, v[16:17]
	v_cvt_pk_bf16_f32 v18, v20, v21
	v_cvt_pk_bf16_f32 v20, v30, v31
	s_waitcnt lgkmcnt(0)
	v_add_f32_e32 v16, v19, v34
	v_mov_b32_e32 v17, v16
	s_nop 1
	v_permlane32_swap_b32_e32 v16, v17
	v_cvt_pk_bf16_f32 v19, v22, v23
	v_cvt_pk_bf16_f32 v21, v28, v29
	global_store_dwordx4 v[32:33], v[24:27], off sc1
	global_store_dwordx4 v[32:33], v[18:21], off offset:256 sc1
	s_and_saveexec_b64 s[34:35], s[6:7]
	s_cbranch_execz .LBB0_999
	v_lshlrev_b64 v[18:19], 6, v[212:213]
	v_lshl_add_u64 v[18:19], s[26:27], 0, v[18:19]
	v_lshl_add_u64 v[18:19], s[30:31], 2, v[18:19]
	s_lshl_b32 s16, s45, 2
	v_lshl_add_u64 v[18:19], v[18:19], 0, s[16:17]
	s_waitcnt lgkmcnt(0)
	v_add_f32_e32 v16, v16, v17
	global_store_dword v[18:19], v16, off
.LBB0_999:
	s_or_b64 exec, exec, s[34:35]
	v_lshlrev_b32_e32 v16, 16, v140
	s_waitcnt lgkmcnt(0)
	v_and_b32_e32 v17, 0xffff0000, v140
	v_lshlrev_b32_e32 v18, 16, v141
	v_and_b32_e32 v19, 0xffff0000, v141
	v_lshlrev_b32_e32 v20, 16, v142
	v_and_b32_e32 v21, 0xffff0000, v142
	v_lshlrev_b32_e32 v22, 16, v143
	v_and_b32_e32 v23, 0xffff0000, v143
	v_pk_add_f32 v[14:15], v[14:15], v[18:19]
	v_pk_add_f32 v[12:13], v[12:13], v[16:17]
	v_pk_add_f32 v[16:17], v[10:11], v[22:23]
	v_pk_add_f32 v[10:11], v[8:9], v[20:21]
	v_mul_f32_e32 v8, v13, v13
	v_mul_f32_e32 v9, v15, v15
	v_fmac_f32_e32 v8, v12, v12
	v_fmac_f32_e32 v9, v14, v14
	v_add_f32_e32 v8, v8, v9
	v_mul_f32_e32 v9, v11, v11
	v_mul_f32_e32 v18, v17, v17
	v_fmac_f32_e32 v9, v10, v10
	v_fmac_f32_e32 v18, v16, v16
	v_add_f32_e32 v9, v9, v18
	v_add_f32_e32 v20, v8, v9
	v_cvt_pk_bf16_f32 v8, v12, v13
	v_cvt_pk_bf16_f32 v9, v14, v15
	v_lshlrev_b32_e32 v12, 16, v124
	v_and_b32_e32 v13, 0xffff0000, v124
	v_lshlrev_b32_e32 v14, 16, v125
	v_and_b32_e32 v15, 0xffff0000, v125
	v_cvt_pk_bf16_f32 v10, v10, v11
	v_cvt_pk_bf16_f32 v11, v16, v17
	v_lshlrev_b32_e32 v16, 16, v126
	v_and_b32_e32 v17, 0xffff0000, v126
	v_pk_add_f32 v[6:7], v[6:7], v[14:15]
	v_pk_add_f32 v[4:5], v[4:5], v[12:13]
	v_lshlrev_b32_e32 v18, 16, v127
	v_and_b32_e32 v19, 0xffff0000, v127
	v_pk_add_f32 v[14:15], v[0:1], v[16:17]
	v_mul_f32_e32 v0, v5, v5
	v_mul_f32_e32 v1, v7, v7
	v_pk_add_f32 v[12:13], v[2:3], v[18:19]
	v_fmac_f32_e32 v0, v4, v4
	v_fmac_f32_e32 v1, v6, v6
	v_add_f32_e32 v0, v0, v1
	v_mul_f32_e32 v1, v15, v15
	v_mul_f32_e32 v2, v13, v13
	v_fmac_f32_e32 v1, v14, v14
	v_fmac_f32_e32 v2, v12, v12
	v_add_f32_e32 v1, v1, v2
	v_add_f32_e32 v0, v0, v1
	v_add_f32_e32 v3, v20, v0
	v_mov_b32_e32 v18, v3
	s_nop 1
	v_permlane16_swap_b32_e32 v3, v18
	v_lshl_add_u64 v[0:1], s[24:25], 0, v[210:211]
	v_lshl_add_u64 v[16:17], v[206:207], 1, v[0:1]
	v_cvt_pk_bf16_f32 v2, v4, v5
	v_cvt_pk_bf16_f32 v4, v14, v15
	s_waitcnt lgkmcnt(0)
	v_add_f32_e32 v0, v3, v18
	v_mov_b32_e32 v1, v0
	s_nop 1
	v_permlane32_swap_b32_e32 v0, v1
	v_cvt_pk_bf16_f32 v3, v6, v7
	v_cvt_pk_bf16_f32 v5, v12, v13
	global_store_dwordx4 v[16:17], v[8:11], off sc1
	global_store_dwordx4 v[16:17], v[2:5], off offset:256 sc1
	s_and_saveexec_b64 s[34:35], s[6:7]
	s_cbranch_execz .LBB0_972
	s_waitcnt lgkmcnt(0)
	v_add_f32_e32 v2, v0, v1
	v_lshlrev_b64 v[0:1], 6, v[208:209]
	v_lshl_add_u64 v[0:1], s[26:27], 0, v[0:1]
	v_lshl_add_u64 v[0:1], s[30:31], 2, v[0:1]
	s_lshl_b32 s16, s45, 2
	v_lshl_add_u64 v[0:1], v[0:1], 0, s[16:17]
	global_store_dword v[0:1], v2, off
	s_branch .LBB0_972

.LBB0_1392:
	v_lshl_add_u32 v130, v146, 2, s8
	ds_read2_b32 v[138:139], v130 offset1:16
	ds_read2_b32 v[140:141], v130 offset0:32 offset1:48
	ds_read2_b32 v[142:143], v130 offset0:64 offset1:80
	ds_read2_b32 v[144:145], v130 offset0:96 offset1:112
	s_lshl_b32 s48, s3, 5
	v_lshrrev_b32_e32 v148, 4, v150
	s_waitcnt lgkmcnt(0)
	v_pk_mul_f32 v[102:103], v[102:103], v[140:141] op_sel_hi:[1,0]
	v_pk_mul_f32 v[132:133], v[120:121], v[138:139] op_sel_hi:[1,0]
	v_pk_mul_f32 v[120:121], v[106:107], v[138:139] op_sel_hi:[1,0]
	v_mov_b32_e32 v106, v139
	v_pk_mul_f32 v[134:135], v[126:127], v[138:139] op_sel_hi:[1,0]
	v_pk_mul_f32 v[136:137], v[124:125], v[138:139] op_sel_hi:[1,0]
	v_pk_mul_f32 v[130:131], v[122:123], v[138:139] op_sel_hi:[1,0]
	v_pk_mul_f32 v[124:125], v[110:111], v[138:139] op_sel_hi:[1,0]
	v_pk_mul_f32 v[126:127], v[108:109], v[138:139] op_sel_hi:[1,0]
	v_pk_mul_f32 v[122:123], v[104:105], v[138:139] op_sel_hi:[1,0]
	v_pk_mul_f32 v[118:119], v[118:119], v[106:107] op_sel_hi:[1,0]
	v_pk_mul_f32 v[116:117], v[116:117], v[106:107] op_sel_hi:[1,0]
	v_pk_mul_f32 v[114:115], v[114:115], v[106:107] op_sel_hi:[1,0]
	v_pk_mul_f32 v[112:113], v[112:113], v[106:107] op_sel_hi:[1,0]
	v_pk_mul_f32 v[108:109], v[94:95], v[106:107] op_sel_hi:[1,0]
	v_pk_mul_f32 v[110:111], v[92:93], v[106:107] op_sel_hi:[1,0]
	v_pk_mul_f32 v[104:105], v[90:91], v[106:107] op_sel_hi:[1,0]
	v_pk_mul_f32 v[106:107], v[88:89], v[106:107] op_sel_hi:[1,0]
	v_pk_mul_f32 v[88:89], v[74:75], v[140:141] op_sel_hi:[1,0]
	v_mov_b32_e32 v74, v141
	v_pk_mul_f32 v[90:91], v[72:73], v[140:141] op_sel_hi:[1,0]
	v_pk_mul_f32 v[72:73], v[66:67], v[74:75] op_sel_hi:[1,0]
	v_pk_mul_f32 v[66:67], v[56:57], v[142:143] op_sel_hi:[1,0]
	v_pk_mul_f32 v[56:57], v[42:43], v[142:143] op_sel_hi:[1,0]
	v_mov_b32_e32 v42, v143
	v_mov_b32_e32 v138, v145
	v_pk_mul_f32 v[100:101], v[100:101], v[140:141] op_sel_hi:[1,0]
	v_pk_mul_f32 v[98:99], v[98:99], v[140:141] op_sel_hi:[1,0]
	v_pk_mul_f32 v[96:97], v[96:97], v[140:141] op_sel_hi:[1,0]
	v_pk_mul_f32 v[92:93], v[78:79], v[140:141] op_sel_hi:[1,0]
	v_pk_mul_f32 v[94:95], v[76:77], v[140:141] op_sel_hi:[1,0]
	v_pk_mul_f32 v[86:87], v[86:87], v[74:75] op_sel_hi:[1,0]
	v_pk_mul_f32 v[84:85], v[84:85], v[74:75] op_sel_hi:[1,0]
	v_pk_mul_f32 v[82:83], v[82:83], v[74:75] op_sel_hi:[1,0]
	v_pk_mul_f32 v[80:81], v[80:81], v[74:75] op_sel_hi:[1,0]
	v_pk_mul_f32 v[76:77], v[70:71], v[74:75] op_sel_hi:[1,0]
	v_pk_mul_f32 v[78:79], v[68:69], v[74:75] op_sel_hi:[1,0]
	v_pk_mul_f32 v[74:75], v[64:65], v[74:75] op_sel_hi:[1,0]
	v_pk_mul_f32 v[68:69], v[62:63], v[142:143] op_sel_hi:[1,0]
	v_pk_mul_f32 v[70:71], v[60:61], v[142:143] op_sel_hi:[1,0]
	v_pk_mul_f32 v[64:65], v[58:59], v[142:143] op_sel_hi:[1,0]
	v_pk_mul_f32 v[60:61], v[46:47], v[142:143] op_sel_hi:[1,0]
	v_pk_mul_f32 v[62:63], v[44:45], v[142:143] op_sel_hi:[1,0]
	v_pk_mul_f32 v[58:59], v[40:41], v[142:143] op_sel_hi:[1,0]
	v_pk_mul_f32 v[54:55], v[54:55], v[42:43] op_sel_hi:[1,0]
	v_pk_mul_f32 v[52:53], v[52:53], v[42:43] op_sel_hi:[1,0]
	v_pk_mul_f32 v[50:51], v[50:51], v[42:43] op_sel_hi:[1,0]
	v_pk_mul_f32 v[48:49], v[48:49], v[42:43] op_sel_hi:[1,0]
	v_pk_mul_f32 v[44:45], v[30:31], v[42:43] op_sel_hi:[1,0]
	v_pk_mul_f32 v[46:47], v[28:29], v[42:43] op_sel_hi:[1,0]
	v_pk_mul_f32 v[40:41], v[26:27], v[42:43] op_sel_hi:[1,0]
	v_pk_mul_f32 v[42:43], v[24:25], v[42:43] op_sel_hi:[1,0]
	v_pk_mul_f32 v[38:39], v[38:39], v[144:145] op_sel_hi:[1,0]
	v_pk_mul_f32 v[36:37], v[36:37], v[144:145] op_sel_hi:[1,0]
	v_pk_mul_f32 v[34:35], v[34:35], v[144:145] op_sel_hi:[1,0]
	v_pk_mul_f32 v[32:33], v[32:33], v[144:145] op_sel_hi:[1,0]
	v_pk_mul_f32 v[28:29], v[14:15], v[144:145] op_sel_hi:[1,0]
	v_pk_mul_f32 v[30:31], v[12:13], v[144:145] op_sel_hi:[1,0]
	v_pk_mul_f32 v[24:25], v[10:11], v[144:145] op_sel_hi:[1,0]
	v_pk_mul_f32 v[26:27], v[8:9], v[144:145] op_sel_hi:[1,0]
	v_pk_mul_f32 v[10:11], v[22:23], v[138:139] op_sel_hi:[1,0]
	v_pk_mul_f32 v[14:15], v[20:21], v[138:139] op_sel_hi:[1,0]
	v_pk_mul_f32 v[8:9], v[18:19], v[138:139] op_sel_hi:[1,0]
	v_pk_mul_f32 v[12:13], v[16:17], v[138:139] op_sel_hi:[1,0]
	v_pk_mul_f32 v[6:7], v[6:7], v[138:139] op_sel_hi:[1,0]
	v_pk_mul_f32 v[4:5], v[4:5], v[138:139] op_sel_hi:[1,0]
	v_pk_mul_f32 v[2:3], v[2:3], v[138:139] op_sel_hi:[1,0]
	v_pk_mul_f32 v[0:1], v[0:1], v[138:139] op_sel_hi:[1,0]
	s_cmp_eq_u32 s27, 0
	v_cmp_gt_u32_e32 vcc, 16, v150
	v_add_u32_e32 v149, 0, v129
	v_mul_f32_e32 v153, v127, v127
	v_mul_f32_e32 v154, v125, v125
	v_mul_f32_e32 v151, v123, v123
	v_mul_f32_e32 v152, v121, v121
	s_cbranch_scc1 .LBB0_1474
	v_mbcnt_lo_u32_b32 v16, -1, 0
	v_mbcnt_hi_u32_b32 v21, -1, v16
	v_and_b32_e32 v17, 64, v21
	v_xor_b32_e32 v16, 16, v21
	v_add_u32_e32 v129, 64, v17
	v_cmp_lt_i32_e64 s[6:7], v16, v129
	v_fma_f32 v17, v124, v124, v154
	v_mov_b32_e32 v18, v137
	v_cndmask_b32_e64 v16, v21, v16, s[6:7]
	v_lshlrev_b32_e32 v20, 2, v16
	v_fma_f32 v16, v126, v126, v153
	v_mov_b32_e32 v19, v133
	v_add_f32_e32 v141, v16, v17
	v_mov_b32_e32 v16, v136
	v_mov_b32_e32 v17, v132
	v_pk_mul_f32 v[18:19], v[18:19], v[18:19]
	v_mov_b32_e32 v22, v135
	v_mov_b32_e32 v23, v131
	v_pk_fma_f32 v[16:17], v[16:17], v[16:17], v[18:19]
	v_mov_b32_e32 v18, v134
	v_mov_b32_e32 v19, v130
	v_pk_mul_f32 v[22:23], v[22:23], v[22:23]
	v_mov_b32_e32 v138, v121
	v_pk_fma_f32 v[18:19], v[18:19], v[18:19], v[22:23]
	v_mov_b32_e32 v22, v123
	v_pk_add_f32 v[16:17], v[16:17], v[18:19]
	v_mov_b32_e32 v18, v122
	v_mov_b32_e32 v19, v126
	v_mov_b32_e32 v23, v127
	v_pk_add_f32 v[18:19], v[18:19], v[22:23]
	v_mov_b32_e32 v22, v120
	v_mov_b32_e32 v23, v124
	v_mov_b32_e32 v139, v125
	v_pk_add_f32 v[22:23], v[22:23], v[138:139]
	v_pk_add_f32 v[16:17], v[16:17], v[16:17] op_sel:[0,1] op_sel_hi:[1,0]
	v_pk_add_f32 v[18:19], v[18:19], v[22:23]
	s_cmp_gt_u32 s3, 1
	v_add_f32_e32 v17, 0, v19
	v_add_f32_e32 v17, v18, v17
	v_fma_f32 v18, v122, v122, v151
	v_fma_f32 v19, v120, v120, v152
	v_add_f32_e32 v18, v18, v19
	v_add_f32_e32 v18, v141, v18
	s_cselect_b64 s[8:9], -1, 0
	v_xor_b32_e32 v140, 32, v21
	v_cndmask_b32_e64 v23, v18, 0, s[8:9]
	v_cndmask_b32_e64 v17, v17, 0, s[8:9]
	v_mov_b32_e32 v18, v16
	s_nop 1
	v_permlane16_swap_b32_e32 v16, v18
	v_mov_b32_e32 v19, v17
	s_nop 1
	v_permlane16_swap_b32_e32 v17, v19
	v_cmp_lt_i32_e64 s[6:7], v140, v129
	v_mov_b32_e32 v129, v23
	s_nop 1
	v_permlane16_swap_b32_e32 v23, v129
	s_waitcnt lgkmcnt(0)
	v_pk_add_f32 v[16:17], v[16:17], v[18:19]
	v_cndmask_b32_e64 v21, v21, v140, s[6:7]
	v_lshlrev_b32_e32 v22, 2, v21
	v_add_f32_e32 v23, v23, v129
	v_mov_b32_e32 v18, v16
	s_nop 1
	v_permlane32_swap_b32_e32 v16, v18
	v_mov_b32_e32 v19, v17
	s_nop 1
	v_permlane32_swap_b32_e32 v17, v19
	v_mov_b32_e32 v129, v23
	s_nop 1
	v_permlane32_swap_b32_e32 v23, v129
	v_lshl_add_u32 v21, s3, 4, v149
	s_and_saveexec_b64 s[6:7], vcc
	s_cbranch_execz .LBB0_1395
	s_waitcnt lgkmcnt(0)
	v_pk_add_f32 v[16:17], v[16:17], v[18:19]
	v_add_f32_e32 v18, v23, v129
	v_mov_b32_e32 v19, 0
	ds_write_b128 v21, v[16:19]
.LBB0_1395:
	s_or_b64 exec, exec, s[6:7]
	v_mul_f32_e32 v16, v111, v111
	v_mul_f32_e32 v17, v109, v109
	v_fmac_f32_e32 v16, v110, v110
	v_fmac_f32_e32 v17, v108, v108
	s_waitcnt lgkmcnt(0)
	v_mov_b32_e32 v18, v117
	v_mov_b32_e32 v19, v113
	v_add_f32_e32 v23, v16, v17
	v_mov_b32_e32 v16, v116
	v_mov_b32_e32 v17, v112
	v_pk_mul_f32 v[18:19], v[18:19], v[18:19]
	v_mov_b32_e32 v138, v119
	v_mov_b32_e32 v139, v115
	v_pk_fma_f32 v[16:17], v[16:17], v[16:17], v[18:19]
	v_mov_b32_e32 v18, v118
	v_mov_b32_e32 v19, v114
	v_pk_mul_f32 v[138:139], v[138:139], v[138:139]
	v_mov_b32_e32 v140, v105
	v_pk_fma_f32 v[18:19], v[18:19], v[18:19], v[138:139]
	v_mov_b32_e32 v138, v107
	v_pk_add_f32 v[16:17], v[16:17], v[18:19]
	v_mov_b32_e32 v18, v106
	v_mov_b32_e32 v19, v110
	v_mov_b32_e32 v139, v111
	v_pk_add_f32 v[18:19], v[18:19], v[138:139]
	v_mov_b32_e32 v138, v104
	v_mov_b32_e32 v139, v108
	v_mov_b32_e32 v141, v109
	v_pk_add_f32 v[138:139], v[138:139], v[140:141]
	v_pk_add_f32 v[16:17], v[16:17], v[16:17] op_sel:[0,1] op_sel_hi:[1,0]
	v_pk_add_f32 v[18:19], v[18:19], v[138:139]
	s_nop 0
	v_add_f32_e32 v17, 0, v19
	v_add_f32_e32 v17, v18, v17
	v_mul_f32_e32 v18, v107, v107
	v_mul_f32_e32 v19, v105, v105
	v_fmac_f32_e32 v18, v106, v106
	v_fmac_f32_e32 v19, v104, v104
	v_add_f32_e32 v129, v18, v19
	v_add_f32_e32 v23, v23, v129
	v_cndmask_b32_e64 v17, v17, 0, s[8:9]
	v_cndmask_b32_e64 v23, v23, 0, s[8:9]
	v_mov_b32_e32 v18, v16
	s_nop 1
	v_permlane16_swap_b32_e32 v16, v18
	v_mov_b32_e32 v19, v17
	s_nop 1
	v_permlane16_swap_b32_e32 v17, v19
	v_mov_b32_e32 v129, v23
	s_nop 1
	v_permlane16_swap_b32_e32 v23, v129
	s_waitcnt lgkmcnt(0)
	v_pk_add_f32 v[16:17], v[16:17], v[18:19]
	v_add_f32_e32 v23, v23, v129
	v_mov_b32_e32 v18, v16
	s_nop 1
	v_permlane32_swap_b32_e32 v16, v18
	v_mov_b32_e32 v19, v17
	s_nop 1
	v_permlane32_swap_b32_e32 v17, v19
	v_mov_b32_e32 v129, v23
	s_nop 1
	v_permlane32_swap_b32_e32 v23, v129
	s_and_saveexec_b64 s[6:7], vcc
	s_cbranch_execz .LBB0_1397
	s_waitcnt lgkmcnt(0)
	v_pk_add_f32 v[16:17], v[16:17], v[18:19]
	v_add_f32_e32 v18, v23, v129
	v_mov_b32_e32 v19, 0
	ds_write_b128 v21, v[16:19] offset:1024
.LBB0_1397:
	s_or_b64 exec, exec, s[6:7]
	v_mul_f32_e32 v16, v95, v95
	v_mul_f32_e32 v17, v93, v93
	v_fmac_f32_e32 v16, v94, v94
	v_fmac_f32_e32 v17, v92, v92
	s_waitcnt lgkmcnt(0)
	v_mov_b32_e32 v18, v101
	v_mov_b32_e32 v19, v97
	v_add_f32_e32 v23, v16, v17
	v_mov_b32_e32 v16, v100
	v_mov_b32_e32 v17, v96
	v_pk_mul_f32 v[18:19], v[18:19], v[18:19]
	v_mov_b32_e32 v138, v103
	v_mov_b32_e32 v139, v99
	v_pk_fma_f32 v[16:17], v[16:17], v[16:17], v[18:19]
	v_mov_b32_e32 v18, v102
	v_mov_b32_e32 v19, v98
	v_pk_mul_f32 v[138:139], v[138:139], v[138:139]
	v_mov_b32_e32 v140, v89
	v_pk_fma_f32 v[18:19], v[18:19], v[18:19], v[138:139]
	v_mov_b32_e32 v138, v91
	v_pk_add_f32 v[16:17], v[16:17], v[18:19]
	v_mov_b32_e32 v18, v90
	v_mov_b32_e32 v19, v94
	v_mov_b32_e32 v139, v95
	v_pk_add_f32 v[18:19], v[18:19], v[138:139]
	v_mov_b32_e32 v138, v88
	v_mov_b32_e32 v139, v92
	v_mov_b32_e32 v141, v93
	v_pk_add_f32 v[138:139], v[138:139], v[140:141]
	v_pk_add_f32 v[16:17], v[16:17], v[16:17] op_sel:[0,1] op_sel_hi:[1,0]
	v_pk_add_f32 v[18:19], v[18:19], v[138:139]
	s_nop 0
	v_add_f32_e32 v17, 0, v19
	v_add_f32_e32 v17, v18, v17
	v_mul_f32_e32 v18, v91, v91
	v_mul_f32_e32 v19, v89, v89
	v_fmac_f32_e32 v18, v90, v90
	v_fmac_f32_e32 v19, v88, v88
	v_add_f32_e32 v129, v18, v19
	v_add_f32_e32 v23, v23, v129
	v_cndmask_b32_e64 v17, v17, 0, s[8:9]
	v_cndmask_b32_e64 v23, v23, 0, s[8:9]
	v_mov_b32_e32 v18, v16
	s_nop 1
	v_permlane16_swap_b32_e32 v16, v18
	v_mov_b32_e32 v19, v17
	s_nop 1
	v_permlane16_swap_b32_e32 v17, v19
	v_mov_b32_e32 v129, v23
	s_nop 1
	v_permlane16_swap_b32_e32 v23, v129
	s_waitcnt lgkmcnt(0)
	v_pk_add_f32 v[16:17], v[16:17], v[18:19]
	v_add_f32_e32 v23, v23, v129
	v_mov_b32_e32 v18, v16
	s_nop 1
	v_permlane32_swap_b32_e32 v16, v18
	v_mov_b32_e32 v19, v17
	s_nop 1
	v_permlane32_swap_b32_e32 v17, v19
	v_mov_b32_e32 v129, v23
	s_nop 1
	v_permlane32_swap_b32_e32 v23, v129
	s_and_saveexec_b64 s[6:7], vcc
	s_cbranch_execz .LBB0_1399
	s_waitcnt lgkmcnt(0)
	v_pk_add_f32 v[16:17], v[16:17], v[18:19]
	v_add_f32_e32 v18, v23, v129
	v_mov_b32_e32 v19, 0
	ds_write_b128 v21, v[16:19] offset:2048
.LBB0_1399:
	s_or_b64 exec, exec, s[6:7]
	v_mul_f32_e32 v16, v79, v79
	v_mul_f32_e32 v17, v77, v77
	v_fmac_f32_e32 v16, v78, v78
	v_fmac_f32_e32 v17, v76, v76
	s_waitcnt lgkmcnt(0)
	v_mov_b32_e32 v18, v85
	v_mov_b32_e32 v19, v81
	v_add_f32_e32 v23, v16, v17
	v_mov_b32_e32 v16, v84
	v_mov_b32_e32 v17, v80
	v_pk_mul_f32 v[18:19], v[18:19], v[18:19]
	v_mov_b32_e32 v138, v87
	v_mov_b32_e32 v139, v83
	v_pk_fma_f32 v[16:17], v[16:17], v[16:17], v[18:19]
	v_mov_b32_e32 v18, v86
	v_mov_b32_e32 v19, v82
	v_pk_mul_f32 v[138:139], v[138:139], v[138:139]
	v_mov_b32_e32 v140, v73
	v_pk_fma_f32 v[18:19], v[18:19], v[18:19], v[138:139]
	v_mov_b32_e32 v138, v75
	v_pk_add_f32 v[16:17], v[16:17], v[18:19]
	v_mov_b32_e32 v18, v74
	v_mov_b32_e32 v19, v78
	v_mov_b32_e32 v139, v79
	v_pk_add_f32 v[18:19], v[18:19], v[138:139]
	v_mov_b32_e32 v138, v72
	v_mov_b32_e32 v139, v76
	v_mov_b32_e32 v141, v77
	v_pk_add_f32 v[138:139], v[138:139], v[140:141]
	v_pk_add_f32 v[16:17], v[16:17], v[16:17] op_sel:[0,1] op_sel_hi:[1,0]
	v_pk_add_f32 v[18:19], v[18:19], v[138:139]
	s_nop 0
	v_add_f32_e32 v17, 0, v19
	v_add_f32_e32 v17, v18, v17
	v_mul_f32_e32 v18, v75, v75
	v_mul_f32_e32 v19, v73, v73
	v_fmac_f32_e32 v18, v74, v74
	v_fmac_f32_e32 v19, v72, v72
	v_add_f32_e32 v129, v18, v19
	v_add_f32_e32 v23, v23, v129
	v_cndmask_b32_e64 v17, v17, 0, s[8:9]
	v_cndmask_b32_e64 v23, v23, 0, s[8:9]
	v_mov_b32_e32 v18, v16
	s_nop 1
	v_permlane16_swap_b32_e32 v16, v18
	v_mov_b32_e32 v19, v17
	s_nop 1
	v_permlane16_swap_b32_e32 v17, v19
	v_mov_b32_e32 v129, v23
	s_nop 1
	v_permlane16_swap_b32_e32 v23, v129
	s_waitcnt lgkmcnt(0)
	v_pk_add_f32 v[16:17], v[16:17], v[18:19]
	v_add_f32_e32 v23, v23, v129
	v_mov_b32_e32 v18, v16
	s_nop 1
	v_permlane32_swap_b32_e32 v16, v18
	v_mov_b32_e32 v19, v17
	s_nop 1
	v_permlane32_swap_b32_e32 v17, v19
	v_mov_b32_e32 v129, v23
	s_nop 1
	v_permlane32_swap_b32_e32 v23, v129
	s_and_saveexec_b64 s[6:7], vcc
	s_cbranch_execz .LBB0_1401
	s_waitcnt lgkmcnt(0)
	v_pk_add_f32 v[16:17], v[16:17], v[18:19]
	v_add_f32_e32 v18, v23, v129
	v_mov_b32_e32 v19, 0
	ds_write_b128 v21, v[16:19] offset:3072
.LBB0_1401:
	s_or_b64 exec, exec, s[6:7]
	v_mul_f32_e32 v16, v63, v63
	v_mul_f32_e32 v17, v61, v61
	v_fmac_f32_e32 v16, v62, v62
	v_fmac_f32_e32 v17, v60, v60
	s_waitcnt lgkmcnt(0)
	v_mov_b32_e32 v18, v71
	v_mov_b32_e32 v19, v67
	v_add_f32_e32 v23, v16, v17
	v_mov_b32_e32 v16, v70
	v_mov_b32_e32 v17, v66
	v_pk_mul_f32 v[18:19], v[18:19], v[18:19]
	v_mov_b32_e32 v138, v69
	v_mov_b32_e32 v139, v65
	v_pk_fma_f32 v[16:17], v[16:17], v[16:17], v[18:19]
	v_mov_b32_e32 v18, v68
	v_mov_b32_e32 v19, v64
	v_pk_mul_f32 v[138:139], v[138:139], v[138:139]
	v_mov_b32_e32 v140, v57
	v_pk_fma_f32 v[18:19], v[18:19], v[18:19], v[138:139]
	v_mov_b32_e32 v138, v59
	v_pk_add_f32 v[16:17], v[16:17], v[18:19]
	v_mov_b32_e32 v18, v58
	v_mov_b32_e32 v19, v62
	v_mov_b32_e32 v139, v63
	v_pk_add_f32 v[18:19], v[18:19], v[138:139]
	v_mov_b32_e32 v138, v56
	v_mov_b32_e32 v139, v60
	v_mov_b32_e32 v141, v61
	v_pk_add_f32 v[138:139], v[138:139], v[140:141]
	v_pk_add_f32 v[16:17], v[16:17], v[16:17] op_sel:[0,1] op_sel_hi:[1,0]
	v_pk_add_f32 v[18:19], v[18:19], v[138:139]
	s_nop 0
	v_add_f32_e32 v17, 0, v19
	v_add_f32_e32 v17, v18, v17
	v_mul_f32_e32 v18, v59, v59
	v_mul_f32_e32 v19, v57, v57
	v_fmac_f32_e32 v18, v58, v58
	v_fmac_f32_e32 v19, v56, v56
	v_add_f32_e32 v129, v18, v19
	v_add_f32_e32 v23, v23, v129
	v_cndmask_b32_e64 v17, v17, 0, s[8:9]
	v_cndmask_b32_e64 v23, v23, 0, s[8:9]
	v_mov_b32_e32 v18, v16
	s_nop 1
	v_permlane16_swap_b32_e32 v16, v18
	v_mov_b32_e32 v19, v17
	s_nop 1
	v_permlane16_swap_b32_e32 v17, v19
	v_mov_b32_e32 v129, v23
	s_nop 1
	v_permlane16_swap_b32_e32 v23, v129
	s_waitcnt lgkmcnt(0)
	v_pk_add_f32 v[16:17], v[16:17], v[18:19]
	v_add_f32_e32 v23, v23, v129
	v_mov_b32_e32 v18, v16
	s_nop 1
	v_permlane32_swap_b32_e32 v16, v18
	v_mov_b32_e32 v19, v17
	s_nop 1
	v_permlane32_swap_b32_e32 v17, v19
	v_mov_b32_e32 v129, v23
	s_nop 1
	v_permlane32_swap_b32_e32 v23, v129
	s_and_saveexec_b64 s[6:7], vcc
	s_cbranch_execz .LBB0_1403
	s_waitcnt lgkmcnt(0)
	v_pk_add_f32 v[16:17], v[16:17], v[18:19]
	v_add_f32_e32 v18, v23, v129
	v_mov_b32_e32 v19, 0
	ds_write_b128 v21, v[16:19] offset:8192
.LBB0_1403:
	s_or_b64 exec, exec, s[6:7]
	v_mul_f32_e32 v16, v47, v47
	v_mul_f32_e32 v17, v45, v45
	v_fmac_f32_e32 v16, v46, v46
	v_fmac_f32_e32 v17, v44, v44
	s_waitcnt lgkmcnt(0)
	v_mov_b32_e32 v18, v53
	v_mov_b32_e32 v19, v49
	v_add_f32_e32 v23, v16, v17
	v_mov_b32_e32 v16, v52
	v_mov_b32_e32 v17, v48
	v_pk_mul_f32 v[18:19], v[18:19], v[18:19]
	v_mov_b32_e32 v138, v55
	v_mov_b32_e32 v139, v51
	v_pk_fma_f32 v[16:17], v[16:17], v[16:17], v[18:19]
	v_mov_b32_e32 v18, v54
	v_mov_b32_e32 v19, v50
	v_pk_mul_f32 v[138:139], v[138:139], v[138:139]
	v_mov_b32_e32 v140, v41
	v_pk_fma_f32 v[18:19], v[18:19], v[18:19], v[138:139]
	v_mov_b32_e32 v138, v43
	v_pk_add_f32 v[16:17], v[16:17], v[18:19]
	v_mov_b32_e32 v18, v42
	v_mov_b32_e32 v19, v46
	v_mov_b32_e32 v139, v47
	v_pk_add_f32 v[18:19], v[18:19], v[138:139]
	v_mov_b32_e32 v138, v40
	v_mov_b32_e32 v139, v44
	v_mov_b32_e32 v141, v45
	v_pk_add_f32 v[138:139], v[138:139], v[140:141]
	v_pk_add_f32 v[16:17], v[16:17], v[16:17] op_sel:[0,1] op_sel_hi:[1,0]
	v_pk_add_f32 v[18:19], v[18:19], v[138:139]
	s_nop 0
	v_add_f32_e32 v17, 0, v19
	v_add_f32_e32 v17, v18, v17
	v_mul_f32_e32 v18, v43, v43
	v_mul_f32_e32 v19, v41, v41
	v_fmac_f32_e32 v18, v42, v42
	v_fmac_f32_e32 v19, v40, v40
	v_add_f32_e32 v129, v18, v19
	v_add_f32_e32 v23, v23, v129
	v_cndmask_b32_e64 v17, v17, 0, s[8:9]
	v_cndmask_b32_e64 v23, v23, 0, s[8:9]
	v_mov_b32_e32 v18, v16
	s_nop 1
	v_permlane16_swap_b32_e32 v16, v18
	v_mov_b32_e32 v19, v17
	s_nop 1
	v_permlane16_swap_b32_e32 v17, v19
	v_mov_b32_e32 v129, v23
	s_nop 1
	v_permlane16_swap_b32_e32 v23, v129
	s_waitcnt lgkmcnt(0)
	v_pk_add_f32 v[16:17], v[16:17], v[18:19]
	v_add_f32_e32 v23, v23, v129
	v_mov_b32_e32 v18, v16
	s_nop 1
	v_permlane32_swap_b32_e32 v16, v18
	v_mov_b32_e32 v19, v17
	s_nop 1
	v_permlane32_swap_b32_e32 v17, v19
	v_mov_b32_e32 v129, v23
	s_nop 1
	v_permlane32_swap_b32_e32 v23, v129
	s_and_saveexec_b64 s[6:7], vcc
	s_cbranch_execz .LBB0_1405
	s_waitcnt lgkmcnt(0)
	v_pk_add_f32 v[16:17], v[16:17], v[18:19]
	v_add_f32_e32 v18, v23, v129
	v_mov_b32_e32 v19, 0
	ds_write_b128 v21, v[16:19] offset:9216
.LBB0_1405:
	s_or_b64 exec, exec, s[6:7]
	v_mul_f32_e32 v16, v31, v31
	v_mul_f32_e32 v17, v29, v29
	v_fmac_f32_e32 v16, v30, v30
	v_fmac_f32_e32 v17, v28, v28
	s_waitcnt lgkmcnt(0)
	v_mov_b32_e32 v18, v37
	v_mov_b32_e32 v19, v33
	v_add_f32_e32 v23, v16, v17
	v_mov_b32_e32 v16, v36
	v_mov_b32_e32 v17, v32
	v_pk_mul_f32 v[18:19], v[18:19], v[18:19]
	v_mov_b32_e32 v138, v39
	v_mov_b32_e32 v139, v35
	v_pk_fma_f32 v[16:17], v[16:17], v[16:17], v[18:19]
	v_mov_b32_e32 v18, v38
	v_mov_b32_e32 v19, v34
	v_pk_mul_f32 v[138:139], v[138:139], v[138:139]
	v_mov_b32_e32 v140, v25
	v_pk_fma_f32 v[18:19], v[18:19], v[18:19], v[138:139]
	v_mov_b32_e32 v138, v27
	v_pk_add_f32 v[16:17], v[16:17], v[18:19]
	v_mov_b32_e32 v18, v26
	v_mov_b32_e32 v19, v30
	v_mov_b32_e32 v139, v31
	v_pk_add_f32 v[18:19], v[18:19], v[138:139]
	v_mov_b32_e32 v138, v24
	v_mov_b32_e32 v139, v28
	v_mov_b32_e32 v141, v29
	v_pk_add_f32 v[138:139], v[138:139], v[140:141]
	v_pk_add_f32 v[16:17], v[16:17], v[16:17] op_sel:[0,1] op_sel_hi:[1,0]
	v_pk_add_f32 v[18:19], v[18:19], v[138:139]
	s_nop 0
	v_add_f32_e32 v17, 0, v19
	v_add_f32_e32 v17, v18, v17
	v_mul_f32_e32 v18, v27, v27
	v_mul_f32_e32 v19, v25, v25
	v_fmac_f32_e32 v18, v26, v26
	v_fmac_f32_e32 v19, v24, v24
	v_add_f32_e32 v129, v18, v19
	v_add_f32_e32 v23, v23, v129
	v_cndmask_b32_e64 v17, v17, 0, s[8:9]
	v_cndmask_b32_e64 v23, v23, 0, s[8:9]
	v_mov_b32_e32 v18, v16
	s_nop 1
	v_permlane16_swap_b32_e32 v16, v18
	v_mov_b32_e32 v19, v17
	s_nop 1
	v_permlane16_swap_b32_e32 v17, v19
	v_mov_b32_e32 v129, v23
	s_nop 1
	v_permlane16_swap_b32_e32 v23, v129
	s_waitcnt lgkmcnt(0)
	v_pk_add_f32 v[16:17], v[16:17], v[18:19]
	v_add_f32_e32 v23, v23, v129
	v_mov_b32_e32 v18, v16
	s_nop 1
	v_permlane32_swap_b32_e32 v16, v18
	v_mov_b32_e32 v19, v17
	s_nop 1
	v_permlane32_swap_b32_e32 v17, v19
	v_mov_b32_e32 v129, v23
	s_nop 1
	v_permlane32_swap_b32_e32 v23, v129
	s_and_saveexec_b64 s[6:7], vcc
	s_cbranch_execz .LBB0_1407
	s_waitcnt lgkmcnt(0)
	v_pk_add_f32 v[16:17], v[16:17], v[18:19]
	v_add_f32_e32 v18, v23, v129
	v_mov_b32_e32 v19, 0
	ds_write_b128 v21, v[16:19] offset:10240
.LBB0_1407:
	s_or_b64 exec, exec, s[6:7]
	v_mul_f32_e32 v16, v5, v5
	v_mul_f32_e32 v17, v7, v7
	v_fmac_f32_e32 v16, v4, v4
	v_fmac_f32_e32 v17, v6, v6
	s_waitcnt lgkmcnt(0)
	v_mov_b32_e32 v18, v15
	v_mov_b32_e32 v19, v13
	v_add_f32_e32 v23, v16, v17
	v_mov_b32_e32 v16, v14
	v_mov_b32_e32 v17, v12
	v_pk_mul_f32 v[18:19], v[18:19], v[18:19]
	v_mov_b32_e32 v138, v11
	v_mov_b32_e32 v139, v9
	v_pk_fma_f32 v[16:17], v[16:17], v[16:17], v[18:19]
	v_mov_b32_e32 v18, v10
	v_mov_b32_e32 v19, v8
	v_pk_mul_f32 v[138:139], v[138:139], v[138:139]
	v_mov_b32_e32 v140, v3
	v_pk_fma_f32 v[18:19], v[18:19], v[18:19], v[138:139]
	v_mov_b32_e32 v138, v1
	v_pk_add_f32 v[16:17], v[16:17], v[18:19]
	v_mov_b32_e32 v18, v0
	v_mov_b32_e32 v19, v4
	v_mov_b32_e32 v139, v5
	v_pk_add_f32 v[18:19], v[18:19], v[138:139]
	v_mov_b32_e32 v138, v2
	v_mov_b32_e32 v139, v6
	v_mov_b32_e32 v141, v7
	v_pk_add_f32 v[138:139], v[138:139], v[140:141]
	v_pk_add_f32 v[16:17], v[16:17], v[16:17] op_sel:[0,1] op_sel_hi:[1,0]
	v_pk_add_f32 v[18:19], v[18:19], v[138:139]
	s_nop 0
	v_add_f32_e32 v17, 0, v19
	v_add_f32_e32 v17, v18, v17
	v_mul_f32_e32 v18, v1, v1
	v_mul_f32_e32 v19, v3, v3
	v_fmac_f32_e32 v18, v0, v0
	v_fmac_f32_e32 v19, v2, v2
	v_add_f32_e32 v129, v18, v19
	v_add_f32_e32 v23, v23, v129
	v_cndmask_b32_e64 v17, v17, 0, s[8:9]
	v_cndmask_b32_e64 v23, v23, 0, s[8:9]
	v_mov_b32_e32 v18, v16
	s_nop 1
	v_permlane16_swap_b32_e32 v16, v18
	v_mov_b32_e32 v19, v17
	s_nop 1
	v_permlane16_swap_b32_e32 v17, v19
	v_mov_b32_e32 v20, v23
	s_nop 1
	v_permlane16_swap_b32_e32 v23, v20
	s_waitcnt lgkmcnt(0)
	v_pk_add_f32 v[16:17], v[16:17], v[18:19]
	v_add_f32_e32 v20, v23, v20
	v_mov_b32_e32 v18, v16
	s_nop 1
	v_permlane32_swap_b32_e32 v16, v18
	v_mov_b32_e32 v19, v17
	s_nop 1
	v_permlane32_swap_b32_e32 v17, v19
	v_mov_b32_e32 v22, v20
	s_nop 1
	v_permlane32_swap_b32_e32 v20, v22
	s_and_saveexec_b64 s[6:7], vcc
	s_cbranch_execz .LBB0_1409
	s_waitcnt lgkmcnt(0)
	v_pk_add_f32 v[16:17], v[16:17], v[18:19]
	v_add_f32_e32 v18, v20, v22
	v_mov_b32_e32 v19, 0
	ds_write_b128 v21, v[16:19] offset:11264

.LBB0_1474:
	s_cbranch_execz .LBB0_1492
	v_mul_f32_e32 v19, v137, v137
	v_mul_f32_e32 v20, v135, v135
	v_mbcnt_lo_u32_b32 v16, -1, 0
	v_fmac_f32_e32 v19, v136, v136
	v_fmac_f32_e32 v20, v134, v134
	v_mbcnt_hi_u32_b32 v17, -1, v16
	v_add_f32_e32 v19, v19, v20
	v_mul_f32_e32 v20, v133, v133
	v_mul_f32_e32 v21, v131, v131
	v_and_b32_e32 v18, 64, v17
	v_fmac_f32_e32 v20, v132, v132
	v_fmac_f32_e32 v21, v130, v130
	v_xor_b32_e32 v16, 16, v17
	v_add_u32_e32 v18, 64, v18
	v_add_f32_e32 v20, v20, v21
	v_fmac_f32_e32 v153, v126, v126
	v_fmac_f32_e32 v154, v124, v124
	v_cmp_lt_i32_e32 vcc, v16, v18
	v_add_f32_e32 v19, v19, v20
	v_add_f32_e32 v20, v153, v154
	v_fmac_f32_e32 v151, v122, v122
	v_fmac_f32_e32 v152, v120, v120
	v_cndmask_b32_e32 v16, v17, v16, vcc
	v_add_f32_e32 v19, v20, v19
	v_add_f32_e32 v20, v151, v152
	v_lshlrev_b32_e32 v16, 2, v16
	v_add_f32_e32 v19, v20, v19
	v_mov_b32_e32 v20, v19
	s_nop 1
	v_permlane16_swap_b32_e32 v19, v20
	v_xor_b32_e32 v21, 32, v17
	v_cmp_lt_i32_e32 vcc, v21, v18
	s_waitcnt lgkmcnt(0)
	v_add_f32_e32 v19, v19, v20
	v_cndmask_b32_e32 v17, v17, v21, vcc
	v_lshlrev_b32_e32 v18, 2, v17
	v_mov_b32_e32 v20, v19
	s_nop 1
	v_permlane32_swap_b32_e32 v19, v20
	v_cmp_gt_u32_e32 vcc, 16, v150
	v_lshl_add_u32 v17, s3, 4, v149
	s_and_saveexec_b64 s[6:7], vcc
	s_cbranch_execz .LBB0_1477
	v_mov_b32_e32 v21, 0
	s_waitcnt lgkmcnt(0)
	v_add_f32_e32 v20, v19, v20
	v_mov_b32_e32 v22, v21
	v_mov_b32_e32 v23, v21
	ds_write_b128 v17, v[20:23]
.LBB0_1477:
	s_or_b64 exec, exec, s[6:7]
	v_mul_f32_e32 v19, v117, v117
	s_waitcnt lgkmcnt(0)
	v_mul_f32_e32 v20, v119, v119
	v_fmac_f32_e32 v19, v116, v116
	v_fmac_f32_e32 v20, v118, v118
	v_add_f32_e32 v19, v19, v20
	v_mul_f32_e32 v20, v113, v113
	v_mul_f32_e32 v21, v115, v115
	v_fmac_f32_e32 v20, v112, v112
	v_fmac_f32_e32 v21, v114, v114
	v_add_f32_e32 v20, v20, v21
	v_add_f32_e32 v19, v19, v20
	v_mul_f32_e32 v20, v111, v111
	v_mul_f32_e32 v21, v109, v109
	v_fmac_f32_e32 v20, v110, v110
	v_fmac_f32_e32 v21, v108, v108
	v_add_f32_e32 v20, v20, v21
	v_add_f32_e32 v19, v20, v19
	v_mul_f32_e32 v20, v107, v107
	v_mul_f32_e32 v21, v105, v105
	v_fmac_f32_e32 v20, v106, v106
	v_fmac_f32_e32 v21, v104, v104
	v_add_f32_e32 v20, v20, v21
	v_add_f32_e32 v19, v20, v19
	v_mov_b32_e32 v20, v19
	s_nop 1
	v_permlane16_swap_b32_e32 v19, v20
	s_waitcnt lgkmcnt(0)
	v_add_f32_e32 v19, v19, v20
	v_mov_b32_e32 v20, v19
	s_nop 1
	v_permlane32_swap_b32_e32 v19, v20
	s_and_saveexec_b64 s[6:7], vcc
	s_cbranch_execz .LBB0_1479
	v_mov_b32_e32 v21, 0
	s_waitcnt lgkmcnt(0)
	v_add_f32_e32 v20, v19, v20
	v_mov_b32_e32 v22, v21
	v_mov_b32_e32 v23, v21
	ds_write_b128 v17, v[20:23] offset:1024
.LBB0_1479:
	s_or_b64 exec, exec, s[6:7]
	v_mul_f32_e32 v19, v101, v101
	s_waitcnt lgkmcnt(0)
	v_mul_f32_e32 v20, v103, v103
	v_fmac_f32_e32 v19, v100, v100
	v_fmac_f32_e32 v20, v102, v102
	v_add_f32_e32 v19, v19, v20
	v_mul_f32_e32 v20, v97, v97
	v_mul_f32_e32 v21, v99, v99
	v_fmac_f32_e32 v20, v96, v96
	v_fmac_f32_e32 v21, v98, v98
	v_add_f32_e32 v20, v20, v21
	v_add_f32_e32 v19, v19, v20
	v_mul_f32_e32 v20, v95, v95
	v_mul_f32_e32 v21, v93, v93
	v_fmac_f32_e32 v20, v94, v94
	v_fmac_f32_e32 v21, v92, v92
	v_add_f32_e32 v20, v20, v21
	v_add_f32_e32 v19, v20, v19
	v_mul_f32_e32 v20, v91, v91
	v_mul_f32_e32 v21, v89, v89
	v_fmac_f32_e32 v20, v90, v90
	v_fmac_f32_e32 v21, v88, v88
	v_add_f32_e32 v20, v20, v21
	v_add_f32_e32 v19, v20, v19
	v_mov_b32_e32 v20, v19
	s_nop 1
	v_permlane16_swap_b32_e32 v19, v20
	s_waitcnt lgkmcnt(0)
	v_add_f32_e32 v19, v19, v20
	v_mov_b32_e32 v20, v19
	s_nop 1
	v_permlane32_swap_b32_e32 v19, v20
	s_and_saveexec_b64 s[6:7], vcc
	s_cbranch_execz .LBB0_1481
	v_mov_b32_e32 v21, 0
	s_waitcnt lgkmcnt(0)
	v_add_f32_e32 v20, v19, v20
	v_mov_b32_e32 v22, v21
	v_mov_b32_e32 v23, v21
	ds_write_b128 v17, v[20:23] offset:2048
.LBB0_1481:
	s_or_b64 exec, exec, s[6:7]
	v_mul_f32_e32 v19, v85, v85
	s_waitcnt lgkmcnt(0)
	v_mul_f32_e32 v20, v87, v87
	v_fmac_f32_e32 v19, v84, v84
	v_fmac_f32_e32 v20, v86, v86
	v_add_f32_e32 v19, v19, v20
	v_mul_f32_e32 v20, v81, v81
	v_mul_f32_e32 v21, v83, v83
	v_fmac_f32_e32 v20, v80, v80
	v_fmac_f32_e32 v21, v82, v82
	v_add_f32_e32 v20, v20, v21
	v_add_f32_e32 v19, v19, v20
	v_mul_f32_e32 v20, v79, v79
	v_mul_f32_e32 v21, v77, v77
	v_fmac_f32_e32 v20, v78, v78
	v_fmac_f32_e32 v21, v76, v76
	v_add_f32_e32 v20, v20, v21
	v_add_f32_e32 v19, v20, v19
	v_mul_f32_e32 v20, v75, v75
	v_mul_f32_e32 v21, v73, v73
	v_fmac_f32_e32 v20, v74, v74
	v_fmac_f32_e32 v21, v72, v72
	v_add_f32_e32 v20, v20, v21
	v_add_f32_e32 v19, v20, v19
	v_mov_b32_e32 v20, v19
	s_nop 1
	v_permlane16_swap_b32_e32 v19, v20
	s_waitcnt lgkmcnt(0)
	v_add_f32_e32 v19, v19, v20
	v_mov_b32_e32 v20, v19
	s_nop 1
	v_permlane32_swap_b32_e32 v19, v20
	s_and_saveexec_b64 s[6:7], vcc
	s_cbranch_execz .LBB0_1483
	v_mov_b32_e32 v21, 0
	s_waitcnt lgkmcnt(0)
	v_add_f32_e32 v20, v19, v20
	v_mov_b32_e32 v22, v21
	v_mov_b32_e32 v23, v21
	ds_write_b128 v17, v[20:23] offset:3072
.LBB0_1483:
	s_or_b64 exec, exec, s[6:7]
	v_mul_f32_e32 v19, v71, v71
	s_waitcnt lgkmcnt(0)
	v_mul_f32_e32 v20, v69, v69
	v_fmac_f32_e32 v19, v70, v70
	v_fmac_f32_e32 v20, v68, v68
	v_add_f32_e32 v19, v19, v20
	v_mul_f32_e32 v20, v67, v67
	v_mul_f32_e32 v21, v65, v65
	v_fmac_f32_e32 v20, v66, v66
	v_fmac_f32_e32 v21, v64, v64
	v_add_f32_e32 v20, v20, v21
	v_add_f32_e32 v19, v19, v20
	v_mul_f32_e32 v20, v63, v63
	v_mul_f32_e32 v21, v61, v61
	v_fmac_f32_e32 v20, v62, v62
	v_fmac_f32_e32 v21, v60, v60
	v_add_f32_e32 v20, v20, v21
	v_add_f32_e32 v19, v20, v19
	v_mul_f32_e32 v20, v59, v59
	v_mul_f32_e32 v21, v57, v57
	v_fmac_f32_e32 v20, v58, v58
	v_fmac_f32_e32 v21, v56, v56
	v_add_f32_e32 v20, v20, v21
	v_add_f32_e32 v19, v20, v19
	v_mov_b32_e32 v20, v19
	s_nop 1
	v_permlane16_swap_b32_e32 v19, v20
	s_waitcnt lgkmcnt(0)
	v_add_f32_e32 v19, v19, v20
	v_mov_b32_e32 v20, v19
	s_nop 1
	v_permlane32_swap_b32_e32 v19, v20
	s_and_saveexec_b64 s[6:7], vcc
	s_cbranch_execz .LBB0_1485
	v_mov_b32_e32 v21, 0
	s_waitcnt lgkmcnt(0)
	v_add_f32_e32 v20, v19, v20
	v_mov_b32_e32 v22, v21
	v_mov_b32_e32 v23, v21
	ds_write_b128 v17, v[20:23] offset:8192
.LBB0_1485:
	s_or_b64 exec, exec, s[6:7]
	v_mul_f32_e32 v19, v53, v53
	s_waitcnt lgkmcnt(0)
	v_mul_f32_e32 v20, v55, v55
	v_fmac_f32_e32 v19, v52, v52
	v_fmac_f32_e32 v20, v54, v54
	v_add_f32_e32 v19, v19, v20
	v_mul_f32_e32 v20, v49, v49
	v_mul_f32_e32 v21, v51, v51
	v_fmac_f32_e32 v20, v48, v48
	v_fmac_f32_e32 v21, v50, v50
	v_add_f32_e32 v20, v20, v21
	v_add_f32_e32 v19, v19, v20
	v_mul_f32_e32 v20, v47, v47
	v_mul_f32_e32 v21, v45, v45
	v_fmac_f32_e32 v20, v46, v46
	v_fmac_f32_e32 v21, v44, v44
	v_add_f32_e32 v20, v20, v21
	v_add_f32_e32 v19, v20, v19
	v_mul_f32_e32 v20, v43, v43
	v_mul_f32_e32 v21, v41, v41
	v_fmac_f32_e32 v20, v42, v42
	v_fmac_f32_e32 v21, v40, v40
	v_add_f32_e32 v20, v20, v21
	v_add_f32_e32 v19, v20, v19
	v_mov_b32_e32 v20, v19
	s_nop 1
	v_permlane16_swap_b32_e32 v19, v20
	s_waitcnt lgkmcnt(0)
	v_add_f32_e32 v19, v19, v20
	v_mov_b32_e32 v20, v19
	s_nop 1
	v_permlane32_swap_b32_e32 v19, v20
	s_and_saveexec_b64 s[6:7], vcc
	s_cbranch_execz .LBB0_1487
	v_mov_b32_e32 v21, 0
	s_waitcnt lgkmcnt(0)
	v_add_f32_e32 v20, v19, v20
	v_mov_b32_e32 v22, v21
	v_mov_b32_e32 v23, v21
	ds_write_b128 v17, v[20:23] offset:9216
.LBB0_1487:
	s_or_b64 exec, exec, s[6:7]
	v_mul_f32_e32 v19, v37, v37
	s_waitcnt lgkmcnt(0)
	v_mul_f32_e32 v20, v39, v39
	v_fmac_f32_e32 v19, v36, v36
	v_fmac_f32_e32 v20, v38, v38
	v_add_f32_e32 v19, v19, v20
	v_mul_f32_e32 v20, v33, v33
	v_mul_f32_e32 v21, v35, v35
	v_fmac_f32_e32 v20, v32, v32
	v_fmac_f32_e32 v21, v34, v34
	v_add_f32_e32 v20, v20, v21
	v_add_f32_e32 v19, v19, v20
	v_mul_f32_e32 v20, v31, v31
	v_mul_f32_e32 v21, v29, v29
	v_fmac_f32_e32 v20, v30, v30
	v_fmac_f32_e32 v21, v28, v28
	v_add_f32_e32 v20, v20, v21
	v_add_f32_e32 v19, v20, v19
	v_mul_f32_e32 v20, v27, v27
	v_mul_f32_e32 v21, v25, v25
	v_fmac_f32_e32 v20, v26, v26
	v_fmac_f32_e32 v21, v24, v24
	v_add_f32_e32 v20, v20, v21
	v_add_f32_e32 v19, v20, v19
	v_mov_b32_e32 v20, v19
	s_nop 1
	v_permlane16_swap_b32_e32 v19, v20
	s_waitcnt lgkmcnt(0)
	v_add_f32_e32 v19, v19, v20
	v_mov_b32_e32 v20, v19
	s_nop 1
	v_permlane32_swap_b32_e32 v19, v20
	s_and_saveexec_b64 s[6:7], vcc
	s_cbranch_execz .LBB0_1489
	v_mov_b32_e32 v21, 0
	s_waitcnt lgkmcnt(0)
	v_add_f32_e32 v20, v19, v20
	v_mov_b32_e32 v22, v21
	v_mov_b32_e32 v23, v21
	ds_write_b128 v17, v[20:23] offset:10240
.LBB0_1489:
	s_or_b64 exec, exec, s[6:7]
	v_mul_f32_e32 v19, v15, v15
	s_waitcnt lgkmcnt(0)
	v_mul_f32_e32 v20, v11, v11
	v_fmac_f32_e32 v19, v14, v14
	v_fmac_f32_e32 v20, v10, v10
	v_add_f32_e32 v19, v19, v20
	v_mul_f32_e32 v20, v13, v13
	v_mul_f32_e32 v21, v9, v9
	v_fmac_f32_e32 v20, v12, v12
	v_fmac_f32_e32 v21, v8, v8
	v_add_f32_e32 v20, v20, v21
	v_add_f32_e32 v19, v19, v20
	v_mul_f32_e32 v20, v5, v5
	v_mul_f32_e32 v21, v7, v7
	v_fmac_f32_e32 v20, v4, v4
	v_fmac_f32_e32 v21, v6, v6
	v_add_f32_e32 v20, v20, v21
	v_add_f32_e32 v19, v20, v19
	v_mul_f32_e32 v20, v1, v1
	v_mul_f32_e32 v21, v3, v3
	v_fmac_f32_e32 v20, v0, v0
	v_fmac_f32_e32 v21, v2, v2
	v_add_f32_e32 v20, v20, v21
	v_add_f32_e32 v19, v20, v19
	v_mov_b32_e32 v16, v19
	s_nop 1
	v_permlane16_swap_b32_e32 v19, v16
	s_waitcnt lgkmcnt(0)
	v_add_f32_e32 v16, v19, v16
	v_mov_b32_e32 v18, v16
	s_nop 1
	v_permlane32_swap_b32_e32 v16, v18
	s_and_saveexec_b64 s[6:7], vcc
	s_cbranch_execz .LBB0_1491
	v_mov_b32_e32 v19, 0
	s_waitcnt lgkmcnt(0)
	v_add_f32_e32 v18, v16, v18
	v_mov_b32_e32 v20, v19
	v_mov_b32_e32 v21, v19
	ds_write_b128 v17, v[18:21] offset:11264

.LBB0_2700:
	ds_read_b128 v[120:123], v244
	ds_read_b128 v[124:127], v244 offset:1024
	ds_read_b128 v[132:135], v244 offset:2048
	ds_read_b128 v[140:143], v244 offset:3072
	s_add_u32 s38, s36, 0xfff80080
	s_addc_u32 s39, s37, -1
	s_cmp_eq_u32 s66, 28
	s_cselect_b32 s41, s27, s39
	s_cselect_b32 s40, s35, s38
	s_cselect_b32 s39, s25, s65
	s_cselect_b32 s38, s63, s64
	v_lshl_add_u64 v[176:177], s[36:37], 0, v[202:203]
	s_add_i32 m0, s47, 0xc000
	ds_read_b128 v[144:147], v245
	ds_read_b128 v[148:151], v245 offset:1024
	ds_read_b128 v[152:155], v245 offset:2048
	ds_read_b128 v[156:159], v245 offset:3072
	ds_read_b128 v[160:163], v245 offset:4096
	ds_read_b128 v[164:167], v245 offset:5120
	ds_read_b128 v[168:171], v245 offset:6144
	ds_read_b128 v[172:175], v245 offset:7168
	global_load_lds_dwordx4 v[176:177], off
	v_lshl_add_u64 v[176:177], s[36:37], 0, v[204:205]
	s_add_i32 m0, s47, 0xe000
	s_nop 0
	global_load_lds_dwordx4 v[176:177], off
	s_waitcnt lgkmcnt(8)
	s_barrier
	s_waitcnt lgkmcnt(0)
	s_setprio 1
	s_waitcnt lgkmcnt(0)
	v_mfma_f32_16x16x32_bf16 v[136:139], v[120:123], v[144:147], v[136:139]
	v_mfma_f32_16x16x32_bf16 v[128:131], v[132:135], v[144:147], v[128:131]
	v_mfma_f32_16x16x32_bf16 v[108:111], v[120:123], v[152:155], v[108:111]
	v_mfma_f32_16x16x32_bf16 v[104:107], v[132:135], v[152:155], v[104:107]
	v_mfma_f32_16x16x32_bf16 v[92:95], v[120:123], v[160:163], v[92:95]
	v_mfma_f32_16x16x32_bf16 v[88:91], v[132:135], v[160:163], v[88:91]
	v_mfma_f32_16x16x32_bf16 v[76:79], v[120:123], v[168:171], v[76:79]
	v_mfma_f32_16x16x32_bf16 v[72:75], v[132:135], v[168:171], v[72:75]
	v_mfma_f32_16x16x32_bf16 v[136:139], v[124:127], v[148:151], v[136:139]
	v_mfma_f32_16x16x32_bf16 v[128:131], v[140:143], v[148:151], v[128:131]
	v_mfma_f32_16x16x32_bf16 v[108:111], v[124:127], v[156:159], v[108:111]
	v_mfma_f32_16x16x32_bf16 v[104:107], v[140:143], v[156:159], v[104:107]
	v_mfma_f32_16x16x32_bf16 v[92:95], v[124:127], v[164:167], v[92:95]
	v_mfma_f32_16x16x32_bf16 v[88:91], v[140:143], v[164:167], v[88:91]
	v_mfma_f32_16x16x32_bf16 v[76:79], v[124:127], v[172:175], v[76:79]
	v_mfma_f32_16x16x32_bf16 v[72:75], v[140:143], v[172:175], v[72:75]
	s_setprio 0
	s_barrier
	s_add_i32 s67, s57, s46
	v_lshl_add_u64 v[206:207], s[38:39], 0, v[196:197]
	s_mov_b32 m0, s67
	ds_read_b128 v[176:179], v246
	ds_read_b128 v[180:183], v246 offset:1024
	ds_read_b128 v[184:187], v246 offset:2048
	ds_read_b128 v[188:191], v246 offset:3072
	global_load_lds_dwordx4 v[206:207], off
	v_lshl_add_u64 v[208:209], s[38:39], 0, v[200:201]
	s_add_i32 m0, s67, 0x2000
	s_nop 0
	global_load_lds_dwordx4 v[208:209], off
	s_barrier
	s_waitcnt lgkmcnt(0)
	s_setprio 1
	s_waitcnt lgkmcnt(0)
	v_mfma_f32_16x16x32_bf16 v[116:119], v[176:179], v[144:147], v[116:119]
	v_mfma_f32_16x16x32_bf16 v[112:115], v[184:187], v[144:147], v[112:115]
	v_mfma_f32_16x16x32_bf16 v[100:103], v[176:179], v[152:155], v[100:103]
	v_mfma_f32_16x16x32_bf16 v[96:99], v[184:187], v[152:155], v[96:99]
	v_mfma_f32_16x16x32_bf16 v[84:87], v[176:179], v[160:163], v[84:87]
	v_mfma_f32_16x16x32_bf16 v[80:83], v[184:187], v[160:163], v[80:83]
	v_mfma_f32_16x16x32_bf16 v[68:71], v[176:179], v[168:171], v[68:71]
	v_mfma_f32_16x16x32_bf16 v[64:67], v[184:187], v[168:171], v[64:67]
	v_mfma_f32_16x16x32_bf16 v[116:119], v[180:183], v[148:151], v[116:119]
	v_mfma_f32_16x16x32_bf16 v[112:115], v[188:191], v[148:151], v[112:115]
	v_mfma_f32_16x16x32_bf16 v[100:103], v[180:183], v[156:159], v[100:103]
	v_mfma_f32_16x16x32_bf16 v[96:99], v[188:191], v[156:159], v[96:99]
	v_mfma_f32_16x16x32_bf16 v[84:87], v[180:183], v[164:167], v[84:87]
	v_mfma_f32_16x16x32_bf16 v[80:83], v[188:191], v[164:167], v[80:83]
	v_mfma_f32_16x16x32_bf16 v[68:71], v[180:183], v[172:175], v[68:71]
	v_mfma_f32_16x16x32_bf16 v[64:67], v[188:191], v[172:175], v[64:67]
	s_setprio 0
	s_mov_b32 m0, s47
	v_lshl_add_u64 v[210:211], s[40:41], 0, v[194:195]
	s_barrier
	ds_read_b128 v[144:147], v245 offset:16384
	ds_read_b128 v[148:151], v245 offset:17408
	ds_read_b128 v[152:155], v245 offset:18432
	ds_read_b128 v[156:159], v245 offset:19456
	ds_read_b128 v[160:163], v245 offset:20480
	ds_read_b128 v[164:167], v245 offset:21504
	ds_read_b128 v[168:171], v245 offset:22528
	ds_read_b128 v[172:175], v245 offset:23552
	global_load_lds_dwordx4 v[210:211], off
	v_lshl_add_u64 v[212:213], s[40:41], 0, v[198:199]
	s_mov_b32 m0, s48
	s_nop 0
	global_load_lds_dwordx4 v[212:213], off
	s_barrier
	s_waitcnt lgkmcnt(0)
	s_setprio 1
	s_waitcnt lgkmcnt(0)
	v_mfma_f32_16x16x32_bf16 v[60:63], v[120:123], v[144:147], v[60:63]
	v_mfma_f32_16x16x32_bf16 v[56:59], v[132:135], v[144:147], v[56:59]
	v_mfma_f32_16x16x32_bf16 v[44:47], v[120:123], v[152:155], v[44:47]
	v_mfma_f32_16x16x32_bf16 v[40:43], v[132:135], v[152:155], v[40:43]
	v_mfma_f32_16x16x32_bf16 v[28:31], v[120:123], v[160:163], v[28:31]
	v_mfma_f32_16x16x32_bf16 v[24:27], v[132:135], v[160:163], v[24:27]
	v_mfma_f32_16x16x32_bf16 v[12:15], v[120:123], v[168:171], v[12:15]
	v_mfma_f32_16x16x32_bf16 v[8:11], v[132:135], v[168:171], v[8:11]
	v_mfma_f32_16x16x32_bf16 v[60:63], v[124:127], v[148:151], v[60:63]
	v_mfma_f32_16x16x32_bf16 v[56:59], v[140:143], v[148:151], v[56:59]
	v_mfma_f32_16x16x32_bf16 v[44:47], v[124:127], v[156:159], v[44:47]
	v_mfma_f32_16x16x32_bf16 v[40:43], v[140:143], v[156:159], v[40:43]
	v_mfma_f32_16x16x32_bf16 v[28:31], v[124:127], v[164:167], v[28:31]
	v_mfma_f32_16x16x32_bf16 v[24:27], v[140:143], v[164:167], v[24:27]
	v_mfma_f32_16x16x32_bf16 v[12:15], v[124:127], v[172:175], v[12:15]
	v_mfma_f32_16x16x32_bf16 v[8:11], v[140:143], v[172:175], v[8:11]
	s_setprio 0
	s_barrier
	s_add_u32 s68, s38, 0x80000
	s_addc_u32 s69, s39, 0
	s_add_i32 s67, s58, s46
	v_lshl_add_u64 v[120:121], s[68:69], 0, v[196:197]
	s_mov_b32 m0, s67
	s_nop 0
	global_load_lds_dwordx4 v[120:121], off
	v_lshl_add_u64 v[120:121], s[68:69], 0, v[200:201]
	s_add_i32 m0, s67, 0x2000
	s_nop 0
	global_load_lds_dwordx4 v[120:121], off
	s_waitcnt vmcnt(6)
	s_barrier
	s_setprio 1
	v_mfma_f32_16x16x32_bf16 v[52:55], v[176:179], v[144:147], v[52:55]
	v_mfma_f32_16x16x32_bf16 v[48:51], v[184:187], v[144:147], v[48:51]
	v_mfma_f32_16x16x32_bf16 v[36:39], v[176:179], v[152:155], v[36:39]
	v_mfma_f32_16x16x32_bf16 v[32:35], v[184:187], v[152:155], v[32:35]
	v_mfma_f32_16x16x32_bf16 v[20:23], v[176:179], v[160:163], v[20:23]
	v_mfma_f32_16x16x32_bf16 v[16:19], v[184:187], v[160:163], v[16:19]
	v_mfma_f32_16x16x32_bf16 v[4:7], v[176:179], v[168:171], v[4:7]
	v_mfma_f32_16x16x32_bf16 v[0:3], v[184:187], v[168:171], v[0:3]
	v_mfma_f32_16x16x32_bf16 v[52:55], v[180:183], v[148:151], v[52:55]
	v_mfma_f32_16x16x32_bf16 v[48:51], v[188:191], v[148:151], v[48:51]
	v_mfma_f32_16x16x32_bf16 v[36:39], v[180:183], v[156:159], v[36:39]
	v_mfma_f32_16x16x32_bf16 v[32:35], v[188:191], v[156:159], v[32:35]
	v_mfma_f32_16x16x32_bf16 v[20:23], v[180:183], v[164:167], v[20:23]
	v_mfma_f32_16x16x32_bf16 v[16:19], v[188:191], v[164:167], v[16:19]
	v_mfma_f32_16x16x32_bf16 v[4:7], v[180:183], v[172:175], v[4:7]
	v_mfma_f32_16x16x32_bf16 v[0:3], v[188:191], v[172:175], v[0:3]
	s_setprio 0
	s_add_i32 s67, 0, 0x18000
	v_add_u32_e32 v140, s67, v242
	s_barrier
	ds_read_b128 v[120:123], v140
	ds_read_b128 v[124:127], v140 offset:1024
	ds_read_b128 v[132:135], v140 offset:2048
	ds_read_b128 v[140:143], v140 offset:3072
	s_add_u32 s40, s40, 0x80000
	s_addc_u32 s41, s41, 0
	s_mov_b32 m0, s49
	v_lshl_add_u64 v[176:177], s[40:41], 0, v[194:195]
	ds_read_b128 v[144:147], v245 offset:32768
	ds_read_b128 v[148:151], v245 offset:33792
	ds_read_b128 v[152:155], v245 offset:34816
	ds_read_b128 v[156:159], v245 offset:35840
	ds_read_b128 v[160:163], v245 offset:36864
	ds_read_b128 v[164:167], v245 offset:37888
	ds_read_b128 v[168:171], v245 offset:38912
	ds_read_b128 v[172:175], v245 offset:39936
	global_load_lds_dwordx4 v[176:177], off
	v_lshl_add_u64 v[176:177], s[40:41], 0, v[198:199]
	s_mov_b32 m0, s50
	s_nop 0
	global_load_lds_dwordx4 v[176:177], off
	s_waitcnt lgkmcnt(8)
	s_barrier
	s_waitcnt lgkmcnt(0)
	s_setprio 1
	s_waitcnt lgkmcnt(0)
	v_mfma_f32_16x16x32_bf16 v[136:139], v[120:123], v[144:147], v[136:139]
	v_mfma_f32_16x16x32_bf16 v[128:131], v[132:135], v[144:147], v[128:131]
	v_mfma_f32_16x16x32_bf16 v[108:111], v[120:123], v[152:155], v[108:111]
	v_mfma_f32_16x16x32_bf16 v[104:107], v[132:135], v[152:155], v[104:107]
	v_mfma_f32_16x16x32_bf16 v[92:95], v[120:123], v[160:163], v[92:95]
	v_mfma_f32_16x16x32_bf16 v[88:91], v[132:135], v[160:163], v[88:91]
	v_mfma_f32_16x16x32_bf16 v[76:79], v[120:123], v[168:171], v[76:79]
	v_mfma_f32_16x16x32_bf16 v[72:75], v[132:135], v[168:171], v[72:75]
	v_mfma_f32_16x16x32_bf16 v[136:139], v[124:127], v[148:151], v[136:139]
	v_mfma_f32_16x16x32_bf16 v[128:131], v[140:143], v[148:151], v[128:131]
	v_mfma_f32_16x16x32_bf16 v[108:111], v[124:127], v[156:159], v[108:111]
	v_mfma_f32_16x16x32_bf16 v[104:107], v[140:143], v[156:159], v[104:107]
	v_mfma_f32_16x16x32_bf16 v[92:95], v[124:127], v[164:167], v[92:95]
	v_mfma_f32_16x16x32_bf16 v[88:91], v[140:143], v[164:167], v[88:91]
	v_mfma_f32_16x16x32_bf16 v[76:79], v[124:127], v[172:175], v[76:79]
	v_mfma_f32_16x16x32_bf16 v[72:75], v[140:143], v[172:175], v[72:75]
	s_setprio 0
	s_barrier
	s_add_i32 s40, 0, 0x1c000
	s_add_i32 s41, s67, s46
	v_add_u32_e32 v188, s40, v242
	v_lshl_add_u64 v[206:207], v[206:207], 0, s[16:17]
	s_mov_b32 m0, s41
	ds_read_b128 v[176:179], v188
	ds_read_b128 v[180:183], v188 offset:1024
	ds_read_b128 v[184:187], v188 offset:2048
	ds_read_b128 v[188:191], v188 offset:3072
	global_load_lds_dwordx4 v[206:207], off
	v_lshl_add_u64 v[206:207], v[208:209], 0, s[16:17]
	s_add_i32 m0, s41, 0x2000
	s_nop 0
	global_load_lds_dwordx4 v[206:207], off
	s_barrier
	s_waitcnt lgkmcnt(0)
	s_setprio 1
	s_waitcnt lgkmcnt(0)
	v_mfma_f32_16x16x32_bf16 v[116:119], v[176:179], v[144:147], v[116:119]
	v_mfma_f32_16x16x32_bf16 v[112:115], v[184:187], v[144:147], v[112:115]
	v_mfma_f32_16x16x32_bf16 v[100:103], v[176:179], v[152:155], v[100:103]
	v_mfma_f32_16x16x32_bf16 v[96:99], v[184:187], v[152:155], v[96:99]
	v_mfma_f32_16x16x32_bf16 v[84:87], v[176:179], v[160:163], v[84:87]
	v_mfma_f32_16x16x32_bf16 v[80:83], v[184:187], v[160:163], v[80:83]
	v_mfma_f32_16x16x32_bf16 v[68:71], v[176:179], v[168:171], v[68:71]
	v_mfma_f32_16x16x32_bf16 v[64:67], v[184:187], v[168:171], v[64:67]
	v_mfma_f32_16x16x32_bf16 v[116:119], v[180:183], v[148:151], v[116:119]
	v_mfma_f32_16x16x32_bf16 v[112:115], v[188:191], v[148:151], v[112:115]
	v_mfma_f32_16x16x32_bf16 v[100:103], v[180:183], v[156:159], v[100:103]
	v_mfma_f32_16x16x32_bf16 v[96:99], v[188:191], v[156:159], v[96:99]
	v_mfma_f32_16x16x32_bf16 v[84:87], v[180:183], v[164:167], v[84:87]
	v_mfma_f32_16x16x32_bf16 v[80:83], v[188:191], v[164:167], v[80:83]
	v_mfma_f32_16x16x32_bf16 v[68:71], v[180:183], v[172:175], v[68:71]
	v_mfma_f32_16x16x32_bf16 v[64:67], v[188:191], v[172:175], v[64:67]
	s_setprio 0
	s_mov_b32 m0, s52
	v_lshl_add_u64 v[206:207], v[210:211], 0, s[16:17]
	s_barrier
	ds_read_b128 v[144:147], v245 offset:49152
	ds_read_b128 v[148:151], v245 offset:50176
	ds_read_b128 v[152:155], v245 offset:51200
	ds_read_b128 v[156:159], v245 offset:52224
	ds_read_b128 v[160:163], v245 offset:53248
	ds_read_b128 v[164:167], v245 offset:54272
	ds_read_b128 v[168:171], v245 offset:55296
	ds_read_b128 v[172:175], v245 offset:56320
	global_load_lds_dwordx4 v[206:207], off
	v_lshl_add_u64 v[206:207], v[212:213], 0, s[16:17]
	s_mov_b32 m0, s53
	s_nop 0
	global_load_lds_dwordx4 v[206:207], off
	s_barrier
	s_waitcnt lgkmcnt(0)
	s_setprio 1
	s_waitcnt lgkmcnt(0)
	v_mfma_f32_16x16x32_bf16 v[60:63], v[120:123], v[144:147], v[60:63]
	v_mfma_f32_16x16x32_bf16 v[56:59], v[132:135], v[144:147], v[56:59]
	v_mfma_f32_16x16x32_bf16 v[44:47], v[120:123], v[152:155], v[44:47]
	v_mfma_f32_16x16x32_bf16 v[40:43], v[132:135], v[152:155], v[40:43]
	v_mfma_f32_16x16x32_bf16 v[28:31], v[120:123], v[160:163], v[28:31]
	v_mfma_f32_16x16x32_bf16 v[24:27], v[132:135], v[160:163], v[24:27]
	v_mfma_f32_16x16x32_bf16 v[12:15], v[120:123], v[168:171], v[12:15]
	v_mfma_f32_16x16x32_bf16 v[8:11], v[132:135], v[168:171], v[8:11]
	v_mfma_f32_16x16x32_bf16 v[60:63], v[124:127], v[148:151], v[60:63]
	v_mfma_f32_16x16x32_bf16 v[56:59], v[140:143], v[148:151], v[56:59]
	v_mfma_f32_16x16x32_bf16 v[44:47], v[124:127], v[156:159], v[44:47]
	v_mfma_f32_16x16x32_bf16 v[40:43], v[140:143], v[156:159], v[40:43]
	v_mfma_f32_16x16x32_bf16 v[28:31], v[124:127], v[164:167], v[28:31]
	v_mfma_f32_16x16x32_bf16 v[24:27], v[140:143], v[164:167], v[24:27]
	v_mfma_f32_16x16x32_bf16 v[12:15], v[124:127], v[172:175], v[12:15]
	v_mfma_f32_16x16x32_bf16 v[8:11], v[140:143], v[172:175], v[8:11]
	s_setprio 0
	s_barrier
	s_add_u32 s38, s38, 0x80080
	s_addc_u32 s39, s39, 0
	s_add_i32 s40, s40, s46
	v_lshl_add_u64 v[120:121], s[38:39], 0, v[196:197]
	s_mov_b32 m0, s40
	s_nop 0
	global_load_lds_dwordx4 v[120:121], off
	v_lshl_add_u64 v[120:121], s[38:39], 0, v[200:201]
	s_add_i32 m0, s40, 0x2000
	s_nop 0
	global_load_lds_dwordx4 v[120:121], off
	s_waitcnt vmcnt(6)
	s_barrier
	s_setprio 1
	v_mfma_f32_16x16x32_bf16 v[52:55], v[176:179], v[144:147], v[52:55]
	v_mfma_f32_16x16x32_bf16 v[48:51], v[184:187], v[144:147], v[48:51]
	v_mfma_f32_16x16x32_bf16 v[36:39], v[176:179], v[152:155], v[36:39]
	v_mfma_f32_16x16x32_bf16 v[32:35], v[184:187], v[152:155], v[32:35]
	v_mfma_f32_16x16x32_bf16 v[20:23], v[176:179], v[160:163], v[20:23]
	v_mfma_f32_16x16x32_bf16 v[16:19], v[184:187], v[160:163], v[16:19]
	v_mfma_f32_16x16x32_bf16 v[4:7], v[176:179], v[168:171], v[4:7]
	v_mfma_f32_16x16x32_bf16 v[0:3], v[184:187], v[168:171], v[0:3]
	v_mfma_f32_16x16x32_bf16 v[52:55], v[180:183], v[148:151], v[52:55]
	v_mfma_f32_16x16x32_bf16 v[48:51], v[188:191], v[148:151], v[48:51]
	v_mfma_f32_16x16x32_bf16 v[36:39], v[180:183], v[156:159], v[36:39]
	v_mfma_f32_16x16x32_bf16 v[32:35], v[188:191], v[156:159], v[32:35]
	v_mfma_f32_16x16x32_bf16 v[20:23], v[180:183], v[164:167], v[20:23]
	v_mfma_f32_16x16x32_bf16 v[16:19], v[188:191], v[164:167], v[16:19]
	v_mfma_f32_16x16x32_bf16 v[4:7], v[180:183], v[172:175], v[4:7]
	v_mfma_f32_16x16x32_bf16 v[0:3], v[188:191], v[172:175], v[0:3]
	s_setprio 0
	s_add_i32 s66, s66, 2
	s_add_u32 s36, s36, 0x100
	s_addc_u32 s37, s37, 0
	s_add_u32 s64, s64, 0x100
	s_addc_u32 s65, s65, 0
	s_cmp_gt_u32 s66, 29
	s_barrier
	s_cbranch_scc0 .LBB0_2700
	v_lshl_or_b32 v206, s10, 8, v243
	v_lshl_add_u32 v236, s34, 8, v193
	v_ashrrev_i32_e32 v207, 31, v206
	v_lshlrev_b64 v[238:239], 1, v[206:207]
	v_ashrrev_i32_e32 v237, 31, v236
	v_lshl_add_u64 v[124:125], s[12:13], 0, v[238:239]
	v_lshlrev_b64 v[240:241], 11, v[236:237]
	v_lshl_add_u64 v[120:121], v[124:125], 0, v[240:241]
	global_load_dwordx4 v[188:191], v[120:121], off
	global_load_dwordx4 v[184:187], v[120:121], off offset:256
	v_or_b32_e32 v232, 16, v236
	v_ashrrev_i32_e32 v233, 31, v232
	v_or_b32_e32 v228, 32, v236
	v_lshlrev_b64 v[234:235], 11, v[232:233]
	v_ashrrev_i32_e32 v229, 31, v228
	v_or_b32_e32 v224, 48, v236
	v_lshl_add_u64 v[120:121], v[124:125], 0, v[234:235]
	v_lshlrev_b64 v[230:231], 11, v[228:229]
	v_ashrrev_i32_e32 v225, 31, v224
	v_add_u32_e32 v220, 0x80, v236
	global_load_dwordx4 v[180:183], v[120:121], off
	global_load_dwordx4 v[176:179], v[120:121], off offset:256
	v_lshl_add_u64 v[120:121], v[124:125], 0, v[230:231]
	v_lshlrev_b64 v[226:227], 11, v[224:225]
	v_ashrrev_i32_e32 v221, 31, v220
	v_add_u32_e32 v216, 0x90, v236
	global_load_dwordx4 v[172:175], v[120:121], off
	global_load_dwordx4 v[168:171], v[120:121], off offset:256
	v_lshl_add_u64 v[120:121], v[124:125], 0, v[226:227]
	v_lshlrev_b64 v[222:223], 11, v[220:221]
	v_ashrrev_i32_e32 v217, 31, v216
	v_add_u32_e32 v212, 0xa0, v236
	v_add_u32_e32 v208, 0xb0, v236
	global_load_dwordx4 v[164:167], v[120:121], off
	global_load_dwordx4 v[160:163], v[120:121], off offset:256
	v_lshl_add_u64 v[120:121], v[124:125], 0, v[222:223]
	v_lshlrev_b64 v[218:219], 11, v[216:217]
	v_ashrrev_i32_e32 v213, 31, v212
	v_ashrrev_i32_e32 v209, 31, v208
	global_load_dwordx4 v[156:159], v[120:121], off
	global_load_dwordx4 v[152:155], v[120:121], off offset:256
	v_lshl_add_u64 v[120:121], v[124:125], 0, v[218:219]
	v_lshlrev_b64 v[214:215], 11, v[212:213]
	v_lshlrev_b64 v[210:211], 11, v[208:209]
	global_load_dwordx4 v[148:151], v[120:121], off
	global_load_dwordx4 v[144:147], v[120:121], off offset:256
	v_lshl_add_u64 v[120:121], v[124:125], 0, v[214:215]
	v_lshl_add_u64 v[124:125], v[124:125], 0, v[210:211]
	global_load_dwordx4 v[132:135], v[120:121], off
	s_nop 0
	global_load_dwordx4 v[120:123], v[120:121], off offset:256
	s_nop 0
	global_load_dwordx4 v[140:143], v[124:125], off
	s_nop 0
	global_load_dwordx4 v[124:127], v[124:125], off offset:256
	v_and_b32_e32 v249, 64, v247
	v_xor_b32_e32 v248, 16, v247
	v_add_u32_e32 v249, 64, v249
	v_cmp_lt_i32_e32 vcc, v248, v249
	v_xor_b32_e32 v250, 32, v247
	s_lshl_b32 s34, s10, 2
	v_cndmask_b32_e32 v248, v247, v248, vcc
	v_cmp_lt_i32_e32 vcc, v250, v249
	v_lshlrev_b32_e32 v248, 2, v248
	s_ashr_i32 s35, s34, 31
	v_cndmask_b32_e32 v249, v247, v250, vcc
	v_lshlrev_b32_e32 v249, 2, v249
	s_waitcnt vmcnt(0)
	v_lshlrev_b32_e32 v250, 16, v188
	v_and_b32_e32 v251, 0xffff0000, v188
	v_lshlrev_b32_e32 v188, 16, v189
	v_and_b32_e32 v189, 0xffff0000, v189
	v_lshlrev_b32_e32 v252, 16, v190
	v_and_b32_e32 v253, 0xffff0000, v190
	v_lshlrev_b32_e32 v190, 16, v191
	v_and_b32_e32 v191, 0xffff0000, v191
	v_pk_add_f32 v[138:139], v[138:139], v[188:189]
	v_pk_add_f32 v[136:137], v[136:137], v[250:251]
	v_pk_add_f32 v[188:189], v[130:131], v[190:191]
	v_pk_add_f32 v[130:131], v[128:129], v[252:253]
	v_mul_f32_e32 v128, v137, v137
	v_mul_f32_e32 v129, v139, v139
	v_fmac_f32_e32 v128, v136, v136
	v_fmac_f32_e32 v129, v138, v138
	v_add_f32_e32 v128, v128, v129
	v_mul_f32_e32 v129, v131, v131
	v_mul_f32_e32 v190, v189, v189
	v_fmac_f32_e32 v129, v130, v130
	v_fmac_f32_e32 v190, v188, v188
	v_add_f32_e32 v129, v129, v190
	v_add_f32_e32 v190, v128, v129
	v_cvt_pk_bf16_f32 v128, v136, v137
	v_lshl_add_u64 v[136:137], s[12:13], 0, v[240:241]
	v_cvt_pk_bf16_f32 v129, v138, v139
	v_cvt_pk_bf16_f32 v130, v130, v131
	v_cvt_pk_bf16_f32 v131, v188, v189
	v_lshl_add_u64 v[136:137], v[136:137], 0, v[238:239]
	global_store_dwordx4 v[136:137], v[128:131], off sc1
	v_lshlrev_b32_e32 v138, 16, v186
	v_and_b32_e32 v139, 0xffff0000, v186
	v_lshlrev_b32_e32 v128, 16, v184
	v_and_b32_e32 v129, 0xffff0000, v184
	v_lshlrev_b32_e32 v130, 16, v185
	v_and_b32_e32 v131, 0xffff0000, v185
	v_lshlrev_b32_e32 v184, 16, v187
	v_and_b32_e32 v185, 0xffff0000, v187
	v_pk_add_f32 v[118:119], v[118:119], v[130:131]
	v_pk_add_f32 v[116:117], v[116:117], v[128:129]
	v_pk_add_f32 v[128:129], v[114:115], v[184:185]
	v_pk_add_f32 v[114:115], v[112:113], v[138:139]
	v_mul_f32_e32 v112, v117, v117
	v_mul_f32_e32 v113, v119, v119
	v_fmac_f32_e32 v112, v116, v116
	v_fmac_f32_e32 v113, v118, v118
	v_add_f32_e32 v112, v112, v113
	v_mul_f32_e32 v113, v115, v115
	v_mul_f32_e32 v130, v129, v129
	v_fmac_f32_e32 v113, v114, v114
	v_fmac_f32_e32 v130, v128, v128
	v_add_f32_e32 v113, v113, v130
	v_add_f32_e32 v112, v112, v113
	v_add_f32_e32 v130, v190, v112
	v_cvt_pk_bf16_f32 v112, v116, v117
	v_cvt_pk_bf16_f32 v113, v118, v119
	v_cvt_pk_bf16_f32 v114, v114, v115
	v_cvt_pk_bf16_f32 v115, v128, v129
	global_store_dwordx4 v[136:137], v[112:115], off offset:256 sc1
	s_nop 1
	v_mov_b32_e32 v112, v130
	s_nop 1
	v_permlane16_swap_b32_e32 v130, v112
	s_waitcnt lgkmcnt(0)
	v_add_f32_e32 v112, v130, v112
	v_mov_b32_e32 v113, v112
	s_nop 1
	v_permlane32_swap_b32_e32 v112, v113
	s_and_saveexec_b64 s[36:37], s[6:7]
	s_cbranch_execz .LBB0_2703
	v_lshlrev_b64 v[114:115], 6, v[236:237]
	v_lshl_add_u64 v[114:115], s[14:15], 0, v[114:115]
	v_lshl_add_u64 v[114:115], s[34:35], 2, v[114:115]
	s_lshl_b32 s10, s51, 2
	v_lshl_add_u64 v[114:115], v[114:115], 0, s[10:11]
	s_waitcnt lgkmcnt(0)
	v_add_f32_e32 v112, v112, v113
	global_store_dword v[114:115], v112, off
.LBB0_2703:
	s_or_b64 exec, exec, s[36:37]
	v_lshlrev_b32_e32 v112, 16, v180
	s_waitcnt lgkmcnt(0)
	v_and_b32_e32 v113, 0xffff0000, v180
	v_lshlrev_b32_e32 v114, 16, v181
	v_and_b32_e32 v115, 0xffff0000, v181
	v_lshlrev_b32_e32 v116, 16, v182
	v_and_b32_e32 v117, 0xffff0000, v182
	v_lshlrev_b32_e32 v118, 16, v183
	v_and_b32_e32 v119, 0xffff0000, v183
	v_pk_add_f32 v[110:111], v[110:111], v[114:115]
	v_pk_add_f32 v[108:109], v[108:109], v[112:113]
	v_pk_add_f32 v[112:113], v[106:107], v[118:119]
	v_pk_add_f32 v[106:107], v[104:105], v[116:117]
	v_mul_f32_e32 v104, v109, v109
	v_mul_f32_e32 v105, v111, v111
	v_fmac_f32_e32 v104, v108, v108
	v_fmac_f32_e32 v105, v110, v110
	v_add_f32_e32 v104, v104, v105
	v_mul_f32_e32 v105, v107, v107
	v_mul_f32_e32 v114, v113, v113
	v_fmac_f32_e32 v105, v106, v106
	v_fmac_f32_e32 v114, v112, v112
	v_add_f32_e32 v105, v105, v114
	v_add_f32_e32 v116, v104, v105
	v_cvt_pk_bf16_f32 v104, v108, v109
	v_cvt_pk_bf16_f32 v105, v110, v111
	v_lshlrev_b32_e32 v108, 16, v176
	v_and_b32_e32 v109, 0xffff0000, v176
	v_lshlrev_b32_e32 v110, 16, v177
	v_and_b32_e32 v111, 0xffff0000, v177
	v_cvt_pk_bf16_f32 v106, v106, v107
	v_cvt_pk_bf16_f32 v107, v112, v113
	v_lshlrev_b32_e32 v112, 16, v178
	v_and_b32_e32 v113, 0xffff0000, v178
	v_pk_add_f32 v[102:103], v[102:103], v[110:111]
	v_pk_add_f32 v[100:101], v[100:101], v[108:109]
	v_lshlrev_b32_e32 v114, 16, v179
	v_and_b32_e32 v115, 0xffff0000, v179
	v_pk_add_f32 v[110:111], v[96:97], v[112:113]
	v_mul_f32_e32 v96, v101, v101
	v_mul_f32_e32 v97, v103, v103
	v_pk_add_f32 v[108:109], v[98:99], v[114:115]
	v_fmac_f32_e32 v96, v100, v100
	v_fmac_f32_e32 v97, v102, v102
	v_add_f32_e32 v96, v96, v97
	v_mul_f32_e32 v97, v111, v111
	v_mul_f32_e32 v98, v109, v109
	v_fmac_f32_e32 v97, v110, v110
	v_fmac_f32_e32 v98, v108, v108
	v_add_f32_e32 v97, v97, v98
	v_add_f32_e32 v96, v96, v97
	v_add_f32_e32 v99, v116, v96
	v_mov_b32_e32 v114, v99
	s_nop 1
	v_permlane16_swap_b32_e32 v99, v114
	v_lshl_add_u64 v[96:97], s[12:13], 0, v[234:235]
	v_lshl_add_u64 v[112:113], v[206:207], 1, v[96:97]
	v_cvt_pk_bf16_f32 v98, v100, v101
	v_cvt_pk_bf16_f32 v100, v110, v111
	s_waitcnt lgkmcnt(0)
	v_add_f32_e32 v96, v99, v114
	v_mov_b32_e32 v97, v96
	s_nop 1
	v_permlane32_swap_b32_e32 v96, v97
	v_cvt_pk_bf16_f32 v99, v102, v103
	v_cvt_pk_bf16_f32 v101, v108, v109
	global_store_dwordx4 v[112:113], v[104:107], off sc1
	global_store_dwordx4 v[112:113], v[98:101], off offset:256 sc1
	s_and_saveexec_b64 s[36:37], s[6:7]
	s_cbranch_execz .LBB0_2705
	v_lshlrev_b64 v[98:99], 6, v[232:233]
	v_lshl_add_u64 v[98:99], s[14:15], 0, v[98:99]
	v_lshl_add_u64 v[98:99], s[34:35], 2, v[98:99]
	s_lshl_b32 s10, s51, 2
	v_lshl_add_u64 v[98:99], v[98:99], 0, s[10:11]
	s_waitcnt lgkmcnt(0)
	v_add_f32_e32 v96, v96, v97
	global_store_dword v[98:99], v96, off
.LBB0_2705:
	s_or_b64 exec, exec, s[36:37]
	v_lshlrev_b32_e32 v96, 16, v172
	s_waitcnt lgkmcnt(0)
	v_and_b32_e32 v97, 0xffff0000, v172
	v_lshlrev_b32_e32 v98, 16, v173
	v_and_b32_e32 v99, 0xffff0000, v173
	v_lshlrev_b32_e32 v100, 16, v174
	v_and_b32_e32 v101, 0xffff0000, v174
	v_lshlrev_b32_e32 v102, 16, v175
	v_and_b32_e32 v103, 0xffff0000, v175
	v_pk_add_f32 v[94:95], v[94:95], v[98:99]
	v_pk_add_f32 v[92:93], v[92:93], v[96:97]
	v_pk_add_f32 v[96:97], v[90:91], v[102:103]
	v_pk_add_f32 v[90:91], v[88:89], v[100:101]
	v_mul_f32_e32 v88, v93, v93
	v_mul_f32_e32 v89, v95, v95
	v_fmac_f32_e32 v88, v92, v92
	v_fmac_f32_e32 v89, v94, v94
	v_add_f32_e32 v88, v88, v89
	v_mul_f32_e32 v89, v91, v91
	v_mul_f32_e32 v98, v97, v97
	v_fmac_f32_e32 v89, v90, v90
	v_fmac_f32_e32 v98, v96, v96
	v_add_f32_e32 v89, v89, v98
	v_add_f32_e32 v100, v88, v89
	v_cvt_pk_bf16_f32 v88, v92, v93
	v_cvt_pk_bf16_f32 v89, v94, v95
	v_lshlrev_b32_e32 v92, 16, v168
	v_and_b32_e32 v93, 0xffff0000, v168
	v_lshlrev_b32_e32 v94, 16, v169
	v_and_b32_e32 v95, 0xffff0000, v169
	v_cvt_pk_bf16_f32 v90, v90, v91
	v_cvt_pk_bf16_f32 v91, v96, v97
	v_lshlrev_b32_e32 v96, 16, v170
	v_and_b32_e32 v97, 0xffff0000, v170
	v_pk_add_f32 v[86:87], v[86:87], v[94:95]
	v_pk_add_f32 v[84:85], v[84:85], v[92:93]
	v_lshlrev_b32_e32 v98, 16, v171
	v_and_b32_e32 v99, 0xffff0000, v171
	v_pk_add_f32 v[94:95], v[80:81], v[96:97]
	v_mul_f32_e32 v80, v85, v85
	v_mul_f32_e32 v81, v87, v87
	v_pk_add_f32 v[92:93], v[82:83], v[98:99]
	v_fmac_f32_e32 v80, v84, v84
	v_fmac_f32_e32 v81, v86, v86
	v_add_f32_e32 v80, v80, v81
	v_mul_f32_e32 v81, v95, v95
	v_mul_f32_e32 v82, v93, v93
	v_fmac_f32_e32 v81, v94, v94
	v_fmac_f32_e32 v82, v92, v92
	v_add_f32_e32 v81, v81, v82
	v_add_f32_e32 v80, v80, v81
	v_add_f32_e32 v83, v100, v80
	v_mov_b32_e32 v98, v83
	s_nop 1
	v_permlane16_swap_b32_e32 v83, v98
	v_lshl_add_u64 v[80:81], s[12:13], 0, v[230:231]
	v_lshl_add_u64 v[96:97], v[206:207], 1, v[80:81]
	v_cvt_pk_bf16_f32 v82, v84, v85
	v_cvt_pk_bf16_f32 v84, v94, v95
	s_waitcnt lgkmcnt(0)
	v_add_f32_e32 v80, v83, v98
	v_mov_b32_e32 v81, v80
	s_nop 1
	v_permlane32_swap_b32_e32 v80, v81
	v_cvt_pk_bf16_f32 v83, v86, v87
	v_cvt_pk_bf16_f32 v85, v92, v93
	global_store_dwordx4 v[96:97], v[88:91], off sc1
	global_store_dwordx4 v[96:97], v[82:85], off offset:256 sc1
	s_and_saveexec_b64 s[36:37], s[6:7]
	s_cbranch_execz .LBB0_2707
	v_lshlrev_b64 v[82:83], 6, v[228:229]
	v_lshl_add_u64 v[82:83], s[14:15], 0, v[82:83]
	v_lshl_add_u64 v[82:83], s[34:35], 2, v[82:83]
	s_lshl_b32 s10, s51, 2
	v_lshl_add_u64 v[82:83], v[82:83], 0, s[10:11]
	s_waitcnt lgkmcnt(0)
	v_add_f32_e32 v80, v80, v81
	global_store_dword v[82:83], v80, off
.LBB0_2707:
	s_or_b64 exec, exec, s[36:37]
	v_lshlrev_b32_e32 v80, 16, v164
	s_waitcnt lgkmcnt(0)
	v_and_b32_e32 v81, 0xffff0000, v164
	v_lshlrev_b32_e32 v82, 16, v165
	v_and_b32_e32 v83, 0xffff0000, v165
	v_lshlrev_b32_e32 v84, 16, v166
	v_and_b32_e32 v85, 0xffff0000, v166
	v_lshlrev_b32_e32 v86, 16, v167
	v_and_b32_e32 v87, 0xffff0000, v167
	v_pk_add_f32 v[78:79], v[78:79], v[82:83]
	v_pk_add_f32 v[76:77], v[76:77], v[80:81]
	v_pk_add_f32 v[80:81], v[74:75], v[86:87]
	v_pk_add_f32 v[74:75], v[72:73], v[84:85]
	v_mul_f32_e32 v72, v77, v77
	v_mul_f32_e32 v73, v79, v79
	v_fmac_f32_e32 v72, v76, v76
	v_fmac_f32_e32 v73, v78, v78
	v_add_f32_e32 v72, v72, v73
	v_mul_f32_e32 v73, v75, v75
	v_mul_f32_e32 v82, v81, v81
	v_fmac_f32_e32 v73, v74, v74
	v_fmac_f32_e32 v82, v80, v80
	v_add_f32_e32 v73, v73, v82
	v_add_f32_e32 v84, v72, v73
	v_cvt_pk_bf16_f32 v72, v76, v77
	v_cvt_pk_bf16_f32 v73, v78, v79
	v_lshlrev_b32_e32 v76, 16, v160
	v_and_b32_e32 v77, 0xffff0000, v160
	v_lshlrev_b32_e32 v78, 16, v161
	v_and_b32_e32 v79, 0xffff0000, v161
	v_cvt_pk_bf16_f32 v74, v74, v75
	v_cvt_pk_bf16_f32 v75, v80, v81
	v_lshlrev_b32_e32 v80, 16, v162
	v_and_b32_e32 v81, 0xffff0000, v162
	v_pk_add_f32 v[70:71], v[70:71], v[78:79]
	v_pk_add_f32 v[68:69], v[68:69], v[76:77]
	v_lshlrev_b32_e32 v82, 16, v163
	v_and_b32_e32 v83, 0xffff0000, v163
	v_pk_add_f32 v[78:79], v[64:65], v[80:81]
	v_mul_f32_e32 v64, v69, v69
	v_mul_f32_e32 v65, v71, v71
	v_pk_add_f32 v[76:77], v[66:67], v[82:83]
	v_fmac_f32_e32 v64, v68, v68
	v_fmac_f32_e32 v65, v70, v70
	v_add_f32_e32 v64, v64, v65
	v_mul_f32_e32 v65, v79, v79
	v_mul_f32_e32 v66, v77, v77
	v_fmac_f32_e32 v65, v78, v78
	v_fmac_f32_e32 v66, v76, v76
	v_add_f32_e32 v65, v65, v66
	v_add_f32_e32 v64, v64, v65
	v_add_f32_e32 v67, v84, v64
	v_mov_b32_e32 v82, v67
	s_nop 1
	v_permlane16_swap_b32_e32 v67, v82
	v_lshl_add_u64 v[64:65], s[12:13], 0, v[226:227]
	v_lshl_add_u64 v[80:81], v[206:207], 1, v[64:65]
	v_cvt_pk_bf16_f32 v66, v68, v69
	v_cvt_pk_bf16_f32 v68, v78, v79
	s_waitcnt lgkmcnt(0)
	v_add_f32_e32 v64, v67, v82
	v_mov_b32_e32 v65, v64
	s_nop 1
	v_permlane32_swap_b32_e32 v64, v65
	v_cvt_pk_bf16_f32 v67, v70, v71
	v_cvt_pk_bf16_f32 v69, v76, v77
	global_store_dwordx4 v[80:81], v[72:75], off sc1
	global_store_dwordx4 v[80:81], v[66:69], off offset:256 sc1
	s_and_saveexec_b64 s[36:37], s[6:7]
	s_cbranch_execz .LBB0_2709
	v_lshlrev_b64 v[66:67], 6, v[224:225]
	v_lshl_add_u64 v[66:67], s[14:15], 0, v[66:67]
	v_lshl_add_u64 v[66:67], s[34:35], 2, v[66:67]
	s_lshl_b32 s10, s51, 2
	v_lshl_add_u64 v[66:67], v[66:67], 0, s[10:11]
	s_waitcnt lgkmcnt(0)
	v_add_f32_e32 v64, v64, v65
	global_store_dword v[66:67], v64, off
.LBB0_2709:
	s_or_b64 exec, exec, s[36:37]
	v_lshlrev_b32_e32 v64, 16, v156
	s_waitcnt lgkmcnt(0)
	v_and_b32_e32 v65, 0xffff0000, v156
	v_lshlrev_b32_e32 v66, 16, v157
	v_and_b32_e32 v67, 0xffff0000, v157
	v_lshlrev_b32_e32 v68, 16, v158
	v_and_b32_e32 v69, 0xffff0000, v158
	v_lshlrev_b32_e32 v70, 16, v159
	v_and_b32_e32 v71, 0xffff0000, v159
	v_pk_add_f32 v[62:63], v[62:63], v[66:67]
	v_pk_add_f32 v[60:61], v[60:61], v[64:65]
	v_pk_add_f32 v[64:65], v[58:59], v[70:71]
	v_pk_add_f32 v[58:59], v[56:57], v[68:69]
	v_mul_f32_e32 v56, v61, v61
	v_mul_f32_e32 v57, v63, v63
	v_fmac_f32_e32 v56, v60, v60
	v_fmac_f32_e32 v57, v62, v62
	v_add_f32_e32 v56, v56, v57
	v_mul_f32_e32 v57, v59, v59
	v_mul_f32_e32 v66, v65, v65
	v_fmac_f32_e32 v57, v58, v58
	v_fmac_f32_e32 v66, v64, v64
	v_add_f32_e32 v57, v57, v66
	v_add_f32_e32 v68, v56, v57
	v_cvt_pk_bf16_f32 v56, v60, v61
	v_cvt_pk_bf16_f32 v57, v62, v63
	v_lshlrev_b32_e32 v60, 16, v152
	v_and_b32_e32 v61, 0xffff0000, v152
	v_lshlrev_b32_e32 v62, 16, v153
	v_and_b32_e32 v63, 0xffff0000, v153
	v_cvt_pk_bf16_f32 v58, v58, v59
	v_cvt_pk_bf16_f32 v59, v64, v65
	v_lshlrev_b32_e32 v64, 16, v154
	v_and_b32_e32 v65, 0xffff0000, v154
	v_pk_add_f32 v[54:55], v[54:55], v[62:63]
	v_pk_add_f32 v[52:53], v[52:53], v[60:61]
	v_lshlrev_b32_e32 v66, 16, v155
	v_and_b32_e32 v67, 0xffff0000, v155
	v_pk_add_f32 v[62:63], v[48:49], v[64:65]
	v_mul_f32_e32 v48, v53, v53
	v_mul_f32_e32 v49, v55, v55
	v_pk_add_f32 v[60:61], v[50:51], v[66:67]
	v_fmac_f32_e32 v48, v52, v52
	v_fmac_f32_e32 v49, v54, v54
	v_add_f32_e32 v48, v48, v49
	v_mul_f32_e32 v49, v63, v63
	v_mul_f32_e32 v50, v61, v61
	v_fmac_f32_e32 v49, v62, v62
	v_fmac_f32_e32 v50, v60, v60
	v_add_f32_e32 v49, v49, v50
	v_add_f32_e32 v48, v48, v49
	v_add_f32_e32 v51, v68, v48
	v_mov_b32_e32 v66, v51
	s_nop 1
	v_permlane16_swap_b32_e32 v51, v66
	v_lshl_add_u64 v[48:49], s[12:13], 0, v[222:223]
	v_lshl_add_u64 v[64:65], v[206:207], 1, v[48:49]
	v_cvt_pk_bf16_f32 v50, v52, v53
	v_cvt_pk_bf16_f32 v52, v62, v63
	s_waitcnt lgkmcnt(0)
	v_add_f32_e32 v48, v51, v66
	v_mov_b32_e32 v49, v48
	s_nop 1
	v_permlane32_swap_b32_e32 v48, v49
	v_cvt_pk_bf16_f32 v51, v54, v55
	v_cvt_pk_bf16_f32 v53, v60, v61
	global_store_dwordx4 v[64:65], v[56:59], off sc1
	global_store_dwordx4 v[64:65], v[50:53], off offset:256 sc1
	s_and_saveexec_b64 s[36:37], s[6:7]
	s_cbranch_execz .LBB0_2711
	v_lshlrev_b64 v[50:51], 6, v[220:221]
	v_lshl_add_u64 v[50:51], s[14:15], 0, v[50:51]
	v_lshl_add_u64 v[50:51], s[34:35], 2, v[50:51]
	s_lshl_b32 s10, s51, 2
	v_lshl_add_u64 v[50:51], v[50:51], 0, s[10:11]
	s_waitcnt lgkmcnt(0)
	v_add_f32_e32 v48, v48, v49
	global_store_dword v[50:51], v48, off
.LBB0_2711:
	s_or_b64 exec, exec, s[36:37]
	v_lshlrev_b32_e32 v48, 16, v148
	s_waitcnt lgkmcnt(0)
	v_and_b32_e32 v49, 0xffff0000, v148
	v_lshlrev_b32_e32 v50, 16, v149
	v_and_b32_e32 v51, 0xffff0000, v149
	v_lshlrev_b32_e32 v52, 16, v150
	v_and_b32_e32 v53, 0xffff0000, v150
	v_lshlrev_b32_e32 v54, 16, v151
	v_and_b32_e32 v55, 0xffff0000, v151
	v_pk_add_f32 v[46:47], v[46:47], v[50:51]
	v_pk_add_f32 v[44:45], v[44:45], v[48:49]
	v_pk_add_f32 v[48:49], v[42:43], v[54:55]
	v_pk_add_f32 v[42:43], v[40:41], v[52:53]
	v_mul_f32_e32 v40, v45, v45
	v_mul_f32_e32 v41, v47, v47
	v_fmac_f32_e32 v40, v44, v44
	v_fmac_f32_e32 v41, v46, v46
	v_add_f32_e32 v40, v40, v41
	v_mul_f32_e32 v41, v43, v43
	v_mul_f32_e32 v50, v49, v49
	v_fmac_f32_e32 v41, v42, v42
	v_fmac_f32_e32 v50, v48, v48
	v_add_f32_e32 v41, v41, v50
	v_add_f32_e32 v52, v40, v41
	v_cvt_pk_bf16_f32 v40, v44, v45
	v_cvt_pk_bf16_f32 v41, v46, v47
	v_lshlrev_b32_e32 v44, 16, v144
	v_and_b32_e32 v45, 0xffff0000, v144
	v_lshlrev_b32_e32 v46, 16, v145
	v_and_b32_e32 v47, 0xffff0000, v145
	v_cvt_pk_bf16_f32 v42, v42, v43
	v_cvt_pk_bf16_f32 v43, v48, v49
	v_lshlrev_b32_e32 v48, 16, v146
	v_and_b32_e32 v49, 0xffff0000, v146
	v_pk_add_f32 v[38:39], v[38:39], v[46:47]
	v_pk_add_f32 v[36:37], v[36:37], v[44:45]
	v_lshlrev_b32_e32 v50, 16, v147
	v_and_b32_e32 v51, 0xffff0000, v147
	v_pk_add_f32 v[46:47], v[32:33], v[48:49]
	v_mul_f32_e32 v32, v37, v37
	v_mul_f32_e32 v33, v39, v39
	v_pk_add_f32 v[44:45], v[34:35], v[50:51]
	v_fmac_f32_e32 v32, v36, v36
	v_fmac_f32_e32 v33, v38, v38
	v_add_f32_e32 v32, v32, v33
	v_mul_f32_e32 v33, v47, v47
	v_mul_f32_e32 v34, v45, v45
	v_fmac_f32_e32 v33, v46, v46
	v_fmac_f32_e32 v34, v44, v44
	v_add_f32_e32 v33, v33, v34
	v_add_f32_e32 v32, v32, v33
	v_add_f32_e32 v35, v52, v32
	v_mov_b32_e32 v50, v35
	s_nop 1
	v_permlane16_swap_b32_e32 v35, v50
	v_lshl_add_u64 v[32:33], s[12:13], 0, v[218:219]
	v_lshl_add_u64 v[48:49], v[206:207], 1, v[32:33]
	v_cvt_pk_bf16_f32 v34, v36, v37
	v_cvt_pk_bf16_f32 v36, v46, v47
	s_waitcnt lgkmcnt(0)
	v_add_f32_e32 v32, v35, v50
	v_mov_b32_e32 v33, v32
	s_nop 1
	v_permlane32_swap_b32_e32 v32, v33
	v_cvt_pk_bf16_f32 v35, v38, v39
	v_cvt_pk_bf16_f32 v37, v44, v45
	global_store_dwordx4 v[48:49], v[40:43], off sc1
	global_store_dwordx4 v[48:49], v[34:37], off offset:256 sc1
	s_and_saveexec_b64 s[36:37], s[6:7]
	s_cbranch_execz .LBB0_2713
	v_lshlrev_b64 v[34:35], 6, v[216:217]
	v_lshl_add_u64 v[34:35], s[14:15], 0, v[34:35]
	v_lshl_add_u64 v[34:35], s[34:35], 2, v[34:35]
	s_lshl_b32 s10, s51, 2
	v_lshl_add_u64 v[34:35], v[34:35], 0, s[10:11]
	s_waitcnt lgkmcnt(0)
	v_add_f32_e32 v32, v32, v33
	global_store_dword v[34:35], v32, off
.LBB0_2713:
	s_or_b64 exec, exec, s[36:37]
	v_lshlrev_b32_e32 v32, 16, v132
	s_waitcnt lgkmcnt(0)
	v_and_b32_e32 v33, 0xffff0000, v132
	v_lshlrev_b32_e32 v34, 16, v133
	v_and_b32_e32 v35, 0xffff0000, v133
	v_lshlrev_b32_e32 v36, 16, v134
	v_and_b32_e32 v37, 0xffff0000, v134
	v_lshlrev_b32_e32 v38, 16, v135
	v_and_b32_e32 v39, 0xffff0000, v135
	v_pk_add_f32 v[30:31], v[30:31], v[34:35]
	v_pk_add_f32 v[28:29], v[28:29], v[32:33]
	v_pk_add_f32 v[32:33], v[26:27], v[38:39]
	v_pk_add_f32 v[26:27], v[24:25], v[36:37]
	v_mul_f32_e32 v24, v29, v29
	v_mul_f32_e32 v25, v31, v31
	v_fmac_f32_e32 v24, v28, v28
	v_fmac_f32_e32 v25, v30, v30
	v_add_f32_e32 v24, v24, v25
	v_mul_f32_e32 v25, v27, v27
	v_mul_f32_e32 v34, v33, v33
	v_fmac_f32_e32 v25, v26, v26
	v_fmac_f32_e32 v34, v32, v32
	v_add_f32_e32 v25, v25, v34
	v_add_f32_e32 v36, v24, v25
	v_cvt_pk_bf16_f32 v24, v28, v29
	v_cvt_pk_bf16_f32 v25, v30, v31
	v_lshlrev_b32_e32 v28, 16, v120
	v_and_b32_e32 v29, 0xffff0000, v120
	v_lshlrev_b32_e32 v30, 16, v121
	v_and_b32_e32 v31, 0xffff0000, v121
	v_cvt_pk_bf16_f32 v26, v26, v27
	v_cvt_pk_bf16_f32 v27, v32, v33
	v_lshlrev_b32_e32 v32, 16, v122
	v_and_b32_e32 v33, 0xffff0000, v122
	v_pk_add_f32 v[22:23], v[22:23], v[30:31]
	v_pk_add_f32 v[20:21], v[20:21], v[28:29]
	v_lshlrev_b32_e32 v34, 16, v123
	v_and_b32_e32 v35, 0xffff0000, v123
	v_pk_add_f32 v[30:31], v[16:17], v[32:33]
	v_mul_f32_e32 v16, v21, v21
	v_mul_f32_e32 v17, v23, v23
	v_pk_add_f32 v[28:29], v[18:19], v[34:35]
	v_fmac_f32_e32 v16, v20, v20
	v_fmac_f32_e32 v17, v22, v22
	v_add_f32_e32 v16, v16, v17
	v_mul_f32_e32 v17, v31, v31
	v_mul_f32_e32 v18, v29, v29
	v_fmac_f32_e32 v17, v30, v30
	v_fmac_f32_e32 v18, v28, v28
	v_add_f32_e32 v17, v17, v18
	v_add_f32_e32 v16, v16, v17
	v_add_f32_e32 v19, v36, v16
	v_mov_b32_e32 v34, v19
	s_nop 1
	v_permlane16_swap_b32_e32 v19, v34
	v_lshl_add_u64 v[16:17], s[12:13], 0, v[214:215]
	v_lshl_add_u64 v[32:33], v[206:207], 1, v[16:17]
	v_cvt_pk_bf16_f32 v18, v20, v21
	v_cvt_pk_bf16_f32 v20, v30, v31
	s_waitcnt lgkmcnt(0)
	v_add_f32_e32 v16, v19, v34
	v_mov_b32_e32 v17, v16
	s_nop 1
	v_permlane32_swap_b32_e32 v16, v17
	v_cvt_pk_bf16_f32 v19, v22, v23
	v_cvt_pk_bf16_f32 v21, v28, v29
	global_store_dwordx4 v[32:33], v[24:27], off sc1
	global_store_dwordx4 v[32:33], v[18:21], off offset:256 sc1
	s_and_saveexec_b64 s[36:37], s[6:7]
	s_cbranch_execz .LBB0_2715
	v_lshlrev_b64 v[18:19], 6, v[212:213]
	v_lshl_add_u64 v[18:19], s[14:15], 0, v[18:19]
	v_lshl_add_u64 v[18:19], s[34:35], 2, v[18:19]
	s_lshl_b32 s10, s51, 2
	v_lshl_add_u64 v[18:19], v[18:19], 0, s[10:11]
	s_waitcnt lgkmcnt(0)
	v_add_f32_e32 v16, v16, v17
	global_store_dword v[18:19], v16, off
.LBB0_2715:
	s_or_b64 exec, exec, s[36:37]
	v_lshlrev_b32_e32 v16, 16, v140
	s_waitcnt lgkmcnt(0)
	v_and_b32_e32 v17, 0xffff0000, v140
	v_lshlrev_b32_e32 v18, 16, v141
	v_and_b32_e32 v19, 0xffff0000, v141
	v_lshlrev_b32_e32 v20, 16, v142
	v_and_b32_e32 v21, 0xffff0000, v142
	v_lshlrev_b32_e32 v22, 16, v143
	v_and_b32_e32 v23, 0xffff0000, v143
	v_pk_add_f32 v[14:15], v[14:15], v[18:19]
	v_pk_add_f32 v[12:13], v[12:13], v[16:17]
	v_pk_add_f32 v[16:17], v[10:11], v[22:23]
	v_pk_add_f32 v[10:11], v[8:9], v[20:21]
	v_mul_f32_e32 v8, v13, v13
	v_mul_f32_e32 v9, v15, v15
	v_fmac_f32_e32 v8, v12, v12
	v_fmac_f32_e32 v9, v14, v14
	v_add_f32_e32 v8, v8, v9
	v_mul_f32_e32 v9, v11, v11
	v_mul_f32_e32 v18, v17, v17
	v_fmac_f32_e32 v9, v10, v10
	v_fmac_f32_e32 v18, v16, v16
	v_add_f32_e32 v9, v9, v18
	v_add_f32_e32 v20, v8, v9
	v_cvt_pk_bf16_f32 v8, v12, v13
	v_cvt_pk_bf16_f32 v9, v14, v15
	v_lshlrev_b32_e32 v12, 16, v124
	v_and_b32_e32 v13, 0xffff0000, v124
	v_lshlrev_b32_e32 v14, 16, v125
	v_and_b32_e32 v15, 0xffff0000, v125
	v_cvt_pk_bf16_f32 v10, v10, v11
	v_cvt_pk_bf16_f32 v11, v16, v17
	v_lshlrev_b32_e32 v16, 16, v126
	v_and_b32_e32 v17, 0xffff0000, v126
	v_pk_add_f32 v[6:7], v[6:7], v[14:15]
	v_pk_add_f32 v[4:5], v[4:5], v[12:13]
	v_lshlrev_b32_e32 v18, 16, v127
	v_and_b32_e32 v19, 0xffff0000, v127
	v_pk_add_f32 v[14:15], v[0:1], v[16:17]
	v_mul_f32_e32 v0, v5, v5
	v_mul_f32_e32 v1, v7, v7
	v_pk_add_f32 v[12:13], v[2:3], v[18:19]
	v_fmac_f32_e32 v0, v4, v4
	v_fmac_f32_e32 v1, v6, v6
	v_add_f32_e32 v0, v0, v1
	v_mul_f32_e32 v1, v15, v15
	v_mul_f32_e32 v2, v13, v13
	v_fmac_f32_e32 v1, v14, v14
	v_fmac_f32_e32 v2, v12, v12
	v_add_f32_e32 v1, v1, v2
	v_add_f32_e32 v0, v0, v1
	v_add_f32_e32 v3, v20, v0
	v_mov_b32_e32 v18, v3
	s_nop 1
	v_permlane16_swap_b32_e32 v3, v18
	v_lshl_add_u64 v[0:1], s[12:13], 0, v[210:211]
	v_lshl_add_u64 v[16:17], v[206:207], 1, v[0:1]
	v_cvt_pk_bf16_f32 v2, v4, v5
	v_cvt_pk_bf16_f32 v4, v14, v15
	s_waitcnt lgkmcnt(0)
	v_add_f32_e32 v0, v3, v18
	v_mov_b32_e32 v1, v0
	s_nop 1
	v_permlane32_swap_b32_e32 v0, v1
	v_cvt_pk_bf16_f32 v3, v6, v7
	v_cvt_pk_bf16_f32 v5, v12, v13
	global_store_dwordx4 v[16:17], v[8:11], off sc1
	global_store_dwordx4 v[16:17], v[2:5], off offset:256 sc1
	s_and_saveexec_b64 s[36:37], s[6:7]
	s_cbranch_execz .LBB0_2692
	s_waitcnt lgkmcnt(0)
	v_add_f32_e32 v2, v0, v1
	v_lshlrev_b64 v[0:1], 6, v[208:209]
	v_lshl_add_u64 v[0:1], s[14:15], 0, v[0:1]
	v_lshl_add_u64 v[0:1], s[34:35], 2, v[0:1]
	s_lshl_b32 s10, s51, 2
	v_lshl_add_u64 v[0:1], v[0:1], 0, s[10:11]
	global_store_dword v[0:1], v2, off
	s_branch .LBB0_2692

.LBB0_2866:
	ds_read_b128 v[120:123], v244
	ds_read_b128 v[124:127], v244 offset:1024
	ds_read_b128 v[132:135], v244 offset:2048
	ds_read_b128 v[140:143], v244 offset:3072
	s_add_u32 s34, s30, 0xfff50080
	s_addc_u32 s35, s31, -1
	s_cmp_eq_u32 s59, 40
	s_cselect_b32 s37, s11, s35
	s_cselect_b32 s36, s10, s34
	s_cselect_b32 s35, s13, s58
	s_cselect_b32 s34, s12, s57
	v_lshl_add_u64 v[176:177], s[30:31], 0, v[202:203]
	s_add_i32 m0, s41, 0xc000
	ds_read_b128 v[144:147], v245
	ds_read_b128 v[148:151], v245 offset:1024
	ds_read_b128 v[152:155], v245 offset:2048
	ds_read_b128 v[156:159], v245 offset:3072
	ds_read_b128 v[160:163], v245 offset:4096
	ds_read_b128 v[164:167], v245 offset:5120
	ds_read_b128 v[168:171], v245 offset:6144
	ds_read_b128 v[172:175], v245 offset:7168
	global_load_lds_dwordx4 v[176:177], off
	v_lshl_add_u64 v[176:177], s[30:31], 0, v[204:205]
	s_add_i32 m0, s41, 0xe000
	s_nop 0
	global_load_lds_dwordx4 v[176:177], off
	s_waitcnt lgkmcnt(8)
	s_barrier
	s_waitcnt lgkmcnt(0)
	s_setprio 1
	s_waitcnt lgkmcnt(0)
	v_mfma_f32_16x16x32_bf16 v[136:139], v[120:123], v[144:147], v[136:139]
	v_mfma_f32_16x16x32_bf16 v[128:131], v[132:135], v[144:147], v[128:131]
	v_mfma_f32_16x16x32_bf16 v[108:111], v[120:123], v[152:155], v[108:111]
	v_mfma_f32_16x16x32_bf16 v[104:107], v[132:135], v[152:155], v[104:107]
	v_mfma_f32_16x16x32_bf16 v[92:95], v[120:123], v[160:163], v[92:95]
	v_mfma_f32_16x16x32_bf16 v[88:91], v[132:135], v[160:163], v[88:91]
	v_mfma_f32_16x16x32_bf16 v[76:79], v[120:123], v[168:171], v[76:79]
	v_mfma_f32_16x16x32_bf16 v[72:75], v[132:135], v[168:171], v[72:75]
	v_mfma_f32_16x16x32_bf16 v[136:139], v[124:127], v[148:151], v[136:139]
	v_mfma_f32_16x16x32_bf16 v[128:131], v[140:143], v[148:151], v[128:131]
	v_mfma_f32_16x16x32_bf16 v[108:111], v[124:127], v[156:159], v[108:111]
	v_mfma_f32_16x16x32_bf16 v[104:107], v[140:143], v[156:159], v[104:107]
	v_mfma_f32_16x16x32_bf16 v[92:95], v[124:127], v[164:167], v[92:95]
	v_mfma_f32_16x16x32_bf16 v[88:91], v[140:143], v[164:167], v[88:91]
	v_mfma_f32_16x16x32_bf16 v[76:79], v[124:127], v[172:175], v[76:79]
	v_mfma_f32_16x16x32_bf16 v[72:75], v[140:143], v[172:175], v[72:75]
	s_setprio 0
	s_barrier
	s_add_i32 s63, s51, s40
	v_lshl_add_u64 v[206:207], s[34:35], 0, v[196:197]
	s_mov_b32 m0, s63
	ds_read_b128 v[176:179], v246
	ds_read_b128 v[180:183], v246 offset:1024
	ds_read_b128 v[184:187], v246 offset:2048
	ds_read_b128 v[188:191], v246 offset:3072
	global_load_lds_dwordx4 v[206:207], off
	v_lshl_add_u64 v[208:209], s[34:35], 0, v[200:201]
	s_add_i32 m0, s63, 0x2000
	s_nop 0
	global_load_lds_dwordx4 v[208:209], off
	s_barrier
	s_waitcnt lgkmcnt(0)
	s_setprio 1
	s_waitcnt lgkmcnt(0)
	v_mfma_f32_16x16x32_bf16 v[116:119], v[176:179], v[144:147], v[116:119]
	v_mfma_f32_16x16x32_bf16 v[112:115], v[184:187], v[144:147], v[112:115]
	v_mfma_f32_16x16x32_bf16 v[100:103], v[176:179], v[152:155], v[100:103]
	v_mfma_f32_16x16x32_bf16 v[96:99], v[184:187], v[152:155], v[96:99]
	v_mfma_f32_16x16x32_bf16 v[84:87], v[176:179], v[160:163], v[84:87]
	v_mfma_f32_16x16x32_bf16 v[80:83], v[184:187], v[160:163], v[80:83]
	v_mfma_f32_16x16x32_bf16 v[68:71], v[176:179], v[168:171], v[68:71]
	v_mfma_f32_16x16x32_bf16 v[64:67], v[184:187], v[168:171], v[64:67]
	v_mfma_f32_16x16x32_bf16 v[116:119], v[180:183], v[148:151], v[116:119]
	v_mfma_f32_16x16x32_bf16 v[112:115], v[188:191], v[148:151], v[112:115]
	v_mfma_f32_16x16x32_bf16 v[100:103], v[180:183], v[156:159], v[100:103]
	v_mfma_f32_16x16x32_bf16 v[96:99], v[188:191], v[156:159], v[96:99]
	v_mfma_f32_16x16x32_bf16 v[84:87], v[180:183], v[164:167], v[84:87]
	v_mfma_f32_16x16x32_bf16 v[80:83], v[188:191], v[164:167], v[80:83]
	v_mfma_f32_16x16x32_bf16 v[68:71], v[180:183], v[172:175], v[68:71]
	v_mfma_f32_16x16x32_bf16 v[64:67], v[188:191], v[172:175], v[64:67]
	s_setprio 0
	s_mov_b32 m0, s41
	v_lshl_add_u64 v[210:211], s[36:37], 0, v[194:195]
	s_barrier
	ds_read_b128 v[144:147], v245 offset:16384
	ds_read_b128 v[148:151], v245 offset:17408
	ds_read_b128 v[152:155], v245 offset:18432
	ds_read_b128 v[156:159], v245 offset:19456
	ds_read_b128 v[160:163], v245 offset:20480
	ds_read_b128 v[164:167], v245 offset:21504
	ds_read_b128 v[168:171], v245 offset:22528
	ds_read_b128 v[172:175], v245 offset:23552
	global_load_lds_dwordx4 v[210:211], off
	v_lshl_add_u64 v[212:213], s[36:37], 0, v[198:199]
	s_mov_b32 m0, s42
	s_nop 0
	global_load_lds_dwordx4 v[212:213], off
	s_barrier
	s_waitcnt lgkmcnt(0)
	s_setprio 1
	s_waitcnt lgkmcnt(0)
	v_mfma_f32_16x16x32_bf16 v[60:63], v[120:123], v[144:147], v[60:63]
	v_mfma_f32_16x16x32_bf16 v[56:59], v[132:135], v[144:147], v[56:59]
	v_mfma_f32_16x16x32_bf16 v[44:47], v[120:123], v[152:155], v[44:47]
	v_mfma_f32_16x16x32_bf16 v[40:43], v[132:135], v[152:155], v[40:43]
	v_mfma_f32_16x16x32_bf16 v[28:31], v[120:123], v[160:163], v[28:31]
	v_mfma_f32_16x16x32_bf16 v[24:27], v[132:135], v[160:163], v[24:27]
	v_mfma_f32_16x16x32_bf16 v[12:15], v[120:123], v[168:171], v[12:15]
	v_mfma_f32_16x16x32_bf16 v[8:11], v[132:135], v[168:171], v[8:11]
	v_mfma_f32_16x16x32_bf16 v[60:63], v[124:127], v[148:151], v[60:63]
	v_mfma_f32_16x16x32_bf16 v[56:59], v[140:143], v[148:151], v[56:59]
	v_mfma_f32_16x16x32_bf16 v[44:47], v[124:127], v[156:159], v[44:47]
	v_mfma_f32_16x16x32_bf16 v[40:43], v[140:143], v[156:159], v[40:43]
	v_mfma_f32_16x16x32_bf16 v[28:31], v[124:127], v[164:167], v[28:31]
	v_mfma_f32_16x16x32_bf16 v[24:27], v[140:143], v[164:167], v[24:27]
	v_mfma_f32_16x16x32_bf16 v[12:15], v[124:127], v[172:175], v[12:15]
	v_mfma_f32_16x16x32_bf16 v[8:11], v[140:143], v[172:175], v[8:11]
	s_setprio 0
	s_barrier
	s_add_u32 s64, s34, 0xb0000
	s_addc_u32 s65, s35, 0
	s_add_i32 s63, s52, s40
	v_lshl_add_u64 v[120:121], s[64:65], 0, v[196:197]
	s_mov_b32 m0, s63
	s_nop 0
	global_load_lds_dwordx4 v[120:121], off
	v_lshl_add_u64 v[120:121], s[64:65], 0, v[200:201]
	s_add_i32 m0, s63, 0x2000
	s_nop 0
	global_load_lds_dwordx4 v[120:121], off
	s_waitcnt vmcnt(6)
	s_barrier
	s_setprio 1
	v_mfma_f32_16x16x32_bf16 v[52:55], v[176:179], v[144:147], v[52:55]
	v_mfma_f32_16x16x32_bf16 v[48:51], v[184:187], v[144:147], v[48:51]
	v_mfma_f32_16x16x32_bf16 v[36:39], v[176:179], v[152:155], v[36:39]
	v_mfma_f32_16x16x32_bf16 v[32:35], v[184:187], v[152:155], v[32:35]
	v_mfma_f32_16x16x32_bf16 v[20:23], v[176:179], v[160:163], v[20:23]
	v_mfma_f32_16x16x32_bf16 v[16:19], v[184:187], v[160:163], v[16:19]
	v_mfma_f32_16x16x32_bf16 v[4:7], v[176:179], v[168:171], v[4:7]
	v_mfma_f32_16x16x32_bf16 v[0:3], v[184:187], v[168:171], v[0:3]
	v_mfma_f32_16x16x32_bf16 v[52:55], v[180:183], v[148:151], v[52:55]
	v_mfma_f32_16x16x32_bf16 v[48:51], v[188:191], v[148:151], v[48:51]
	v_mfma_f32_16x16x32_bf16 v[36:39], v[180:183], v[156:159], v[36:39]
	v_mfma_f32_16x16x32_bf16 v[32:35], v[188:191], v[156:159], v[32:35]
	v_mfma_f32_16x16x32_bf16 v[20:23], v[180:183], v[164:167], v[20:23]
	v_mfma_f32_16x16x32_bf16 v[16:19], v[188:191], v[164:167], v[16:19]
	v_mfma_f32_16x16x32_bf16 v[4:7], v[180:183], v[172:175], v[4:7]
	v_mfma_f32_16x16x32_bf16 v[0:3], v[188:191], v[172:175], v[0:3]
	s_setprio 0
	s_add_i32 s63, 0, 0x18000
	v_add_u32_e32 v140, s63, v242
	s_barrier
	ds_read_b128 v[120:123], v140
	ds_read_b128 v[124:127], v140 offset:1024
	ds_read_b128 v[132:135], v140 offset:2048
	ds_read_b128 v[140:143], v140 offset:3072
	s_add_u32 s36, s36, 0xb0000
	s_addc_u32 s37, s37, 0
	s_mov_b32 m0, s43
	v_lshl_add_u64 v[176:177], s[36:37], 0, v[194:195]
	ds_read_b128 v[144:147], v245 offset:32768
	ds_read_b128 v[148:151], v245 offset:33792
	ds_read_b128 v[152:155], v245 offset:34816
	ds_read_b128 v[156:159], v245 offset:35840
	ds_read_b128 v[160:163], v245 offset:36864
	ds_read_b128 v[164:167], v245 offset:37888
	ds_read_b128 v[168:171], v245 offset:38912
	ds_read_b128 v[172:175], v245 offset:39936
	global_load_lds_dwordx4 v[176:177], off
	v_lshl_add_u64 v[176:177], s[36:37], 0, v[198:199]
	s_mov_b32 m0, s44
	s_nop 0
	global_load_lds_dwordx4 v[176:177], off
	s_waitcnt lgkmcnt(8)
	s_barrier
	s_waitcnt lgkmcnt(0)
	s_setprio 1
	s_waitcnt lgkmcnt(0)
	v_mfma_f32_16x16x32_bf16 v[136:139], v[120:123], v[144:147], v[136:139]
	v_mfma_f32_16x16x32_bf16 v[128:131], v[132:135], v[144:147], v[128:131]
	v_mfma_f32_16x16x32_bf16 v[108:111], v[120:123], v[152:155], v[108:111]
	v_mfma_f32_16x16x32_bf16 v[104:107], v[132:135], v[152:155], v[104:107]
	v_mfma_f32_16x16x32_bf16 v[92:95], v[120:123], v[160:163], v[92:95]
	v_mfma_f32_16x16x32_bf16 v[88:91], v[132:135], v[160:163], v[88:91]
	v_mfma_f32_16x16x32_bf16 v[76:79], v[120:123], v[168:171], v[76:79]
	v_mfma_f32_16x16x32_bf16 v[72:75], v[132:135], v[168:171], v[72:75]
	v_mfma_f32_16x16x32_bf16 v[136:139], v[124:127], v[148:151], v[136:139]
	v_mfma_f32_16x16x32_bf16 v[128:131], v[140:143], v[148:151], v[128:131]
	v_mfma_f32_16x16x32_bf16 v[108:111], v[124:127], v[156:159], v[108:111]
	v_mfma_f32_16x16x32_bf16 v[104:107], v[140:143], v[156:159], v[104:107]
	v_mfma_f32_16x16x32_bf16 v[92:95], v[124:127], v[164:167], v[92:95]
	v_mfma_f32_16x16x32_bf16 v[88:91], v[140:143], v[164:167], v[88:91]
	v_mfma_f32_16x16x32_bf16 v[76:79], v[124:127], v[172:175], v[76:79]
	v_mfma_f32_16x16x32_bf16 v[72:75], v[140:143], v[172:175], v[72:75]
	s_setprio 0
	s_barrier
	s_add_i32 s36, 0, 0x1c000
	s_add_i32 s37, s63, s40
	v_add_u32_e32 v188, s36, v242
	v_lshl_add_u64 v[206:207], v[206:207], 0, s[28:29]
	s_mov_b32 m0, s37
	ds_read_b128 v[176:179], v188
	ds_read_b128 v[180:183], v188 offset:1024
	ds_read_b128 v[184:187], v188 offset:2048
	ds_read_b128 v[188:191], v188 offset:3072
	global_load_lds_dwordx4 v[206:207], off
	v_lshl_add_u64 v[206:207], v[208:209], 0, s[28:29]
	s_add_i32 m0, s37, 0x2000
	s_nop 0
	global_load_lds_dwordx4 v[206:207], off
	s_barrier
	s_waitcnt lgkmcnt(0)
	s_setprio 1
	s_waitcnt lgkmcnt(0)
	v_mfma_f32_16x16x32_bf16 v[116:119], v[176:179], v[144:147], v[116:119]
	v_mfma_f32_16x16x32_bf16 v[112:115], v[184:187], v[144:147], v[112:115]
	v_mfma_f32_16x16x32_bf16 v[100:103], v[176:179], v[152:155], v[100:103]
	v_mfma_f32_16x16x32_bf16 v[96:99], v[184:187], v[152:155], v[96:99]
	v_mfma_f32_16x16x32_bf16 v[84:87], v[176:179], v[160:163], v[84:87]
	v_mfma_f32_16x16x32_bf16 v[80:83], v[184:187], v[160:163], v[80:83]
	v_mfma_f32_16x16x32_bf16 v[68:71], v[176:179], v[168:171], v[68:71]
	v_mfma_f32_16x16x32_bf16 v[64:67], v[184:187], v[168:171], v[64:67]
	v_mfma_f32_16x16x32_bf16 v[116:119], v[180:183], v[148:151], v[116:119]
	v_mfma_f32_16x16x32_bf16 v[112:115], v[188:191], v[148:151], v[112:115]
	v_mfma_f32_16x16x32_bf16 v[100:103], v[180:183], v[156:159], v[100:103]
	v_mfma_f32_16x16x32_bf16 v[96:99], v[188:191], v[156:159], v[96:99]
	v_mfma_f32_16x16x32_bf16 v[84:87], v[180:183], v[164:167], v[84:87]
	v_mfma_f32_16x16x32_bf16 v[80:83], v[188:191], v[164:167], v[80:83]
	v_mfma_f32_16x16x32_bf16 v[68:71], v[180:183], v[172:175], v[68:71]
	v_mfma_f32_16x16x32_bf16 v[64:67], v[188:191], v[172:175], v[64:67]
	s_setprio 0
	s_mov_b32 m0, s46
	v_lshl_add_u64 v[206:207], v[210:211], 0, s[28:29]
	s_barrier
	ds_read_b128 v[144:147], v245 offset:49152
	ds_read_b128 v[148:151], v245 offset:50176
	ds_read_b128 v[152:155], v245 offset:51200
	ds_read_b128 v[156:159], v245 offset:52224
	ds_read_b128 v[160:163], v245 offset:53248
	ds_read_b128 v[164:167], v245 offset:54272
	ds_read_b128 v[168:171], v245 offset:55296
	ds_read_b128 v[172:175], v245 offset:56320
	global_load_lds_dwordx4 v[206:207], off
	v_lshl_add_u64 v[206:207], v[212:213], 0, s[28:29]
	s_mov_b32 m0, s47
	s_nop 0
	global_load_lds_dwordx4 v[206:207], off
	s_barrier
	s_waitcnt lgkmcnt(0)
	s_setprio 1
	s_waitcnt lgkmcnt(0)
	v_mfma_f32_16x16x32_bf16 v[60:63], v[120:123], v[144:147], v[60:63]
	v_mfma_f32_16x16x32_bf16 v[56:59], v[132:135], v[144:147], v[56:59]
	v_mfma_f32_16x16x32_bf16 v[44:47], v[120:123], v[152:155], v[44:47]
	v_mfma_f32_16x16x32_bf16 v[40:43], v[132:135], v[152:155], v[40:43]
	v_mfma_f32_16x16x32_bf16 v[28:31], v[120:123], v[160:163], v[28:31]
	v_mfma_f32_16x16x32_bf16 v[24:27], v[132:135], v[160:163], v[24:27]
	v_mfma_f32_16x16x32_bf16 v[12:15], v[120:123], v[168:171], v[12:15]
	v_mfma_f32_16x16x32_bf16 v[8:11], v[132:135], v[168:171], v[8:11]
	v_mfma_f32_16x16x32_bf16 v[60:63], v[124:127], v[148:151], v[60:63]
	v_mfma_f32_16x16x32_bf16 v[56:59], v[140:143], v[148:151], v[56:59]
	v_mfma_f32_16x16x32_bf16 v[44:47], v[124:127], v[156:159], v[44:47]
	v_mfma_f32_16x16x32_bf16 v[40:43], v[140:143], v[156:159], v[40:43]
	v_mfma_f32_16x16x32_bf16 v[28:31], v[124:127], v[164:167], v[28:31]
	v_mfma_f32_16x16x32_bf16 v[24:27], v[140:143], v[164:167], v[24:27]
	v_mfma_f32_16x16x32_bf16 v[12:15], v[124:127], v[172:175], v[12:15]
	v_mfma_f32_16x16x32_bf16 v[8:11], v[140:143], v[172:175], v[8:11]
	s_setprio 0
	s_barrier
	s_add_u32 s34, s34, 0xb0080
	s_addc_u32 s35, s35, 0
	s_add_i32 s36, s36, s40
	v_lshl_add_u64 v[120:121], s[34:35], 0, v[196:197]
	s_mov_b32 m0, s36
	s_nop 0
	global_load_lds_dwordx4 v[120:121], off
	v_lshl_add_u64 v[120:121], s[34:35], 0, v[200:201]
	s_add_i32 m0, s36, 0x2000
	s_nop 0
	global_load_lds_dwordx4 v[120:121], off
	s_waitcnt vmcnt(6)
	s_barrier
	s_setprio 1
	v_mfma_f32_16x16x32_bf16 v[52:55], v[176:179], v[144:147], v[52:55]
	v_mfma_f32_16x16x32_bf16 v[48:51], v[184:187], v[144:147], v[48:51]
	v_mfma_f32_16x16x32_bf16 v[36:39], v[176:179], v[152:155], v[36:39]
	v_mfma_f32_16x16x32_bf16 v[32:35], v[184:187], v[152:155], v[32:35]
	v_mfma_f32_16x16x32_bf16 v[20:23], v[176:179], v[160:163], v[20:23]
	v_mfma_f32_16x16x32_bf16 v[16:19], v[184:187], v[160:163], v[16:19]
	v_mfma_f32_16x16x32_bf16 v[4:7], v[176:179], v[168:171], v[4:7]
	v_mfma_f32_16x16x32_bf16 v[0:3], v[184:187], v[168:171], v[0:3]
	v_mfma_f32_16x16x32_bf16 v[52:55], v[180:183], v[148:151], v[52:55]
	v_mfma_f32_16x16x32_bf16 v[48:51], v[188:191], v[148:151], v[48:51]
	v_mfma_f32_16x16x32_bf16 v[36:39], v[180:183], v[156:159], v[36:39]
	v_mfma_f32_16x16x32_bf16 v[32:35], v[188:191], v[156:159], v[32:35]
	v_mfma_f32_16x16x32_bf16 v[20:23], v[180:183], v[164:167], v[20:23]
	v_mfma_f32_16x16x32_bf16 v[16:19], v[188:191], v[164:167], v[16:19]
	v_mfma_f32_16x16x32_bf16 v[4:7], v[180:183], v[172:175], v[4:7]
	v_mfma_f32_16x16x32_bf16 v[0:3], v[188:191], v[172:175], v[0:3]
	s_setprio 0
	s_add_i32 s59, s59, 2
	s_add_u32 s30, s30, 0x100
	s_addc_u32 s31, s31, 0
	s_add_u32 s57, s57, 0x100
	s_addc_u32 s58, s58, 0
	s_cmp_gt_u32 s59, 41
	s_barrier
	s_cbranch_scc0 .LBB0_2866
	v_lshl_or_b32 v206, s16, 8, v243
	v_lshl_add_u32 v236, s56, 8, v193
	v_ashrrev_i32_e32 v207, 31, v206
	v_lshlrev_b64 v[238:239], 1, v[206:207]
	v_ashrrev_i32_e32 v237, 31, v236
	v_lshl_add_u64 v[124:125], s[24:25], 0, v[238:239]
	v_lshlrev_b64 v[240:241], 11, v[236:237]
	v_lshl_add_u64 v[120:121], v[124:125], 0, v[240:241]
	global_load_dwordx4 v[188:191], v[120:121], off
	global_load_dwordx4 v[184:187], v[120:121], off offset:256
	v_or_b32_e32 v232, 16, v236
	v_ashrrev_i32_e32 v233, 31, v232
	v_or_b32_e32 v228, 32, v236
	v_lshlrev_b64 v[234:235], 11, v[232:233]
	v_ashrrev_i32_e32 v229, 31, v228
	v_or_b32_e32 v224, 48, v236
	v_lshl_add_u64 v[120:121], v[124:125], 0, v[234:235]
	v_lshlrev_b64 v[230:231], 11, v[228:229]
	v_ashrrev_i32_e32 v225, 31, v224
	v_add_u32_e32 v220, 0x80, v236
	global_load_dwordx4 v[180:183], v[120:121], off
	global_load_dwordx4 v[176:179], v[120:121], off offset:256
	v_lshl_add_u64 v[120:121], v[124:125], 0, v[230:231]
	v_lshlrev_b64 v[226:227], 11, v[224:225]
	v_ashrrev_i32_e32 v221, 31, v220
	v_add_u32_e32 v216, 0x90, v236
	global_load_dwordx4 v[172:175], v[120:121], off
	global_load_dwordx4 v[168:171], v[120:121], off offset:256
	v_lshl_add_u64 v[120:121], v[124:125], 0, v[226:227]
	v_lshlrev_b64 v[222:223], 11, v[220:221]
	v_ashrrev_i32_e32 v217, 31, v216
	v_add_u32_e32 v212, 0xa0, v236
	v_add_u32_e32 v208, 0xb0, v236
	global_load_dwordx4 v[164:167], v[120:121], off
	global_load_dwordx4 v[160:163], v[120:121], off offset:256
	v_lshl_add_u64 v[120:121], v[124:125], 0, v[222:223]
	v_lshlrev_b64 v[218:219], 11, v[216:217]
	v_ashrrev_i32_e32 v213, 31, v212
	v_ashrrev_i32_e32 v209, 31, v208
	global_load_dwordx4 v[156:159], v[120:121], off
	global_load_dwordx4 v[152:155], v[120:121], off offset:256
	v_lshl_add_u64 v[120:121], v[124:125], 0, v[218:219]
	v_lshlrev_b64 v[214:215], 11, v[212:213]
	v_lshlrev_b64 v[210:211], 11, v[208:209]
	global_load_dwordx4 v[148:151], v[120:121], off
	global_load_dwordx4 v[144:147], v[120:121], off offset:256
	v_lshl_add_u64 v[120:121], v[124:125], 0, v[214:215]
	v_lshl_add_u64 v[124:125], v[124:125], 0, v[210:211]
	global_load_dwordx4 v[132:135], v[120:121], off
	s_nop 0
	global_load_dwordx4 v[120:123], v[120:121], off offset:256
	s_nop 0
	global_load_dwordx4 v[140:143], v[124:125], off
	s_nop 0
	global_load_dwordx4 v[124:127], v[124:125], off offset:256
	v_and_b32_e32 v249, 64, v247
	v_xor_b32_e32 v248, 16, v247
	v_add_u32_e32 v249, 64, v249
	v_cmp_lt_i32_e32 vcc, v248, v249
	v_xor_b32_e32 v250, 32, v247
	s_lshl_b32 s30, s16, 2
	v_cndmask_b32_e32 v248, v247, v248, vcc
	v_cmp_lt_i32_e32 vcc, v250, v249
	v_lshlrev_b32_e32 v248, 2, v248
	s_ashr_i32 s31, s30, 31
	v_cndmask_b32_e32 v249, v247, v250, vcc
	v_lshlrev_b32_e32 v249, 2, v249
	s_waitcnt vmcnt(0)
	v_lshlrev_b32_e32 v250, 16, v188
	v_and_b32_e32 v251, 0xffff0000, v188
	v_lshlrev_b32_e32 v188, 16, v189
	v_and_b32_e32 v189, 0xffff0000, v189
	v_lshlrev_b32_e32 v252, 16, v190
	v_and_b32_e32 v253, 0xffff0000, v190
	v_lshlrev_b32_e32 v190, 16, v191
	v_and_b32_e32 v191, 0xffff0000, v191
	v_pk_add_f32 v[138:139], v[138:139], v[188:189]
	v_pk_add_f32 v[136:137], v[136:137], v[250:251]
	v_pk_add_f32 v[188:189], v[130:131], v[190:191]
	v_pk_add_f32 v[130:131], v[128:129], v[252:253]
	v_mul_f32_e32 v128, v137, v137
	v_mul_f32_e32 v129, v139, v139
	v_fmac_f32_e32 v128, v136, v136
	v_fmac_f32_e32 v129, v138, v138
	v_add_f32_e32 v128, v128, v129
	v_mul_f32_e32 v129, v131, v131
	v_mul_f32_e32 v190, v189, v189
	v_fmac_f32_e32 v129, v130, v130
	v_fmac_f32_e32 v190, v188, v188
	v_add_f32_e32 v129, v129, v190
	v_add_f32_e32 v190, v128, v129
	v_cvt_pk_bf16_f32 v128, v136, v137
	v_lshl_add_u64 v[136:137], s[24:25], 0, v[240:241]
	v_cvt_pk_bf16_f32 v129, v138, v139
	v_cvt_pk_bf16_f32 v130, v130, v131
	v_cvt_pk_bf16_f32 v131, v188, v189
	v_lshl_add_u64 v[136:137], v[136:137], 0, v[238:239]
	global_store_dwordx4 v[136:137], v[128:131], off sc1
	v_lshlrev_b32_e32 v138, 16, v186
	v_and_b32_e32 v139, 0xffff0000, v186
	v_lshlrev_b32_e32 v128, 16, v184
	v_and_b32_e32 v129, 0xffff0000, v184
	v_lshlrev_b32_e32 v130, 16, v185
	v_and_b32_e32 v131, 0xffff0000, v185
	v_lshlrev_b32_e32 v184, 16, v187
	v_and_b32_e32 v185, 0xffff0000, v187
	v_pk_add_f32 v[118:119], v[118:119], v[130:131]
	v_pk_add_f32 v[116:117], v[116:117], v[128:129]
	v_pk_add_f32 v[128:129], v[114:115], v[184:185]
	v_pk_add_f32 v[114:115], v[112:113], v[138:139]
	v_mul_f32_e32 v112, v117, v117
	v_mul_f32_e32 v113, v119, v119
	v_fmac_f32_e32 v112, v116, v116
	v_fmac_f32_e32 v113, v118, v118
	v_add_f32_e32 v112, v112, v113
	v_mul_f32_e32 v113, v115, v115
	v_mul_f32_e32 v130, v129, v129
	v_fmac_f32_e32 v113, v114, v114
	v_fmac_f32_e32 v130, v128, v128
	v_add_f32_e32 v113, v113, v130
	v_add_f32_e32 v112, v112, v113
	v_add_f32_e32 v130, v190, v112
	v_cvt_pk_bf16_f32 v112, v116, v117
	v_cvt_pk_bf16_f32 v113, v118, v119
	v_cvt_pk_bf16_f32 v114, v114, v115
	v_cvt_pk_bf16_f32 v115, v128, v129
	global_store_dwordx4 v[136:137], v[112:115], off offset:256 sc1
	s_nop 1
	v_mov_b32_e32 v112, v130
	s_nop 1
	v_permlane16_swap_b32_e32 v130, v112
	s_waitcnt lgkmcnt(0)
	v_add_f32_e32 v112, v130, v112
	v_mov_b32_e32 v113, v112
	s_nop 1
	v_permlane32_swap_b32_e32 v112, v113
	s_and_saveexec_b64 s[34:35], s[6:7]
	s_cbranch_execz .LBB0_2869
	v_lshlrev_b64 v[114:115], 6, v[236:237]
	v_lshl_add_u64 v[114:115], s[26:27], 0, v[114:115]
	v_lshl_add_u64 v[114:115], s[30:31], 2, v[114:115]
	s_lshl_b32 s16, s45, 2
	v_lshl_add_u64 v[114:115], v[114:115], 0, s[16:17]
	s_waitcnt lgkmcnt(0)
	v_add_f32_e32 v112, v112, v113
	global_store_dword v[114:115], v112, off
